# un-serialized loads: weight transposes (16 loads in flight per tile), norm_rows, RWKV-gate/GLA/S5 epilogue load hoisting with counted waits
# speedup vs baseline: 1.1879x; 1.0437x over previous
; __device__ __forceinline__ void rw_shift8(const u16* proj, const float* mu, int m, int col, float* f) {
;   const u16* pr = proj + (size_t)m * PROJ1_LD + col;
;   float a[8], b[8];
;   unpack8(*(const uint4*)pr, a);
;   const bool hasprev = (m & (SEQL - 1)) != 0;
;   unpack8(*(const uint4*)(pr - (hasprev ? PROJ1_LD : 0)), b);
;   const float pz = hasprev ? 1.f : 0.f;
; #pragma unroll
;   for (int i = 0; i < 8; i++) b[i] *= pz;
;   float4 m0 = *(const float4*)(mu + col), m1 = *(const float4*)(mu + col + 4);
;   float mm[8] = {m0.x, m0.y, m0.z, m0.w, m1.x, m1.y, m1.z, m1.w};
; #pragma unroll
;   for (int i = 0; i < 8; i++) f[i] = a[i] + (b[i] - a[i]) * mm[i];
; }
.LBB0_110:
	s_ashr_i32 s7, s6, 31
	v_mov_b32_e32 v0, v132
	s_lshr_b32 s7, s7, 25
	s_mov_b64 s[60:61], s[88:89]
	v_ashrrev_i32_e32 v47, 2, v0
	s_add_i32 s7, s6, s7
	v_lshrrev_b32_e32 v2, 2, v47
	s_mov_b64 s[62:63], s[90:91]
	s_mov_b64 s[64:65], s[92:93]
	s_mov_b64 s[66:67], s[94:95]
	s_load_dwordx8 s[88:95], s[0:1], 0x1e0
	s_and_b32 s8, s7, 0xffffff80
	v_sub_u32_e32 v2, 0, v2
	v_ashrrev_i32_e32 v65, 7, v0
	v_lshlrev_b32_e32 v1, 3, v0
	v_xor_b32_e32 v49, v0, v2
	v_lshrrev_b32_e32 v2, 4, v0
	v_lshrrev_b32_e32 v66, 2, v0
	v_bfe_u32 v64, v0, 6, 1
	v_and_b32_e32 v67, 15, v0
	v_add_u32_e32 v0, s8, v47
	v_and_b32_e32 v4, 24, v1
	v_ashrrev_i32_e32 v1, 31, v0
	v_lshlrev_b64 v[0:1], 8, v[0:1]
	s_lshl_b32 s7, s7, 7
	s_waitcnt lgkmcnt(0)
	v_lshl_add_u64 v[0:1], s[88:89], 0, v[0:1]
	v_lshlrev_b32_e32 v134, 1, v4
	s_and_b32 s7, s7, 0xffffc000
	v_lshl_add_u64 v[32:33], v[0:1], 0, v[134:135]
	v_subrev_u32_e32 v0, s7, v47
	v_add_u32_e32 v12, s4, v0
	v_mov_b64_e32 v[70:71], s[22:23]
	v_mad_i64_i32 v[0:1], s[10:11], v12, s16, v[70:71]
	v_sub_u32_e32 v3, 0, v66
	v_lshl_add_u64 v[36:37], v[0:1], 0, v[134:135]
	v_xor_b32_e32 v48, v2, v3
	global_load_dwordx4 v[0:3], v[36:37], off offset:3328
	v_lshlrev_b32_e32 v46, 2, v4
	v_or_b32_e32 v4, 0x1a00, v46
	v_lshlrev_b32_e32 v49, 4, v49
	v_and_b32_e32 v49, 48, v49
	v_lshl_or_b32 v47, v47, 6, v49
	v_lshl_add_u64 v[34:35], v[32:33], 0, s[14:15]
	v_lshlrev_b32_e32 v48, 4, v48
	v_and_b32_e32 v48, 48, v48
	v_lshlrev_b32_e32 v62, 6, v67
	s_mov_b64 s[94:95], s[66:67]
	s_add_i32 s6, s6, s82
	s_mov_b64 s[92:93], s[64:65]
	s_mov_b64 s[90:91], s[62:63]
	s_mov_b64 s[88:89], s[60:61]
	s_waitcnt vmcnt(0)
	v_lshlrev_b32_e32 v8, 16, v0
	v_and_b32_e32 v9, 0xffff0000, v0
	v_and_b32_e32 v0, 0xfff, v12
	v_cmp_eq_u32_e32 vcc, 0, v0
	v_lshlrev_b32_e32 v10, 16, v1
	v_and_b32_e32 v11, 0xffff0000, v1
	v_cndmask_b32_e64 v1, -1, 0, vcc
	v_cndmask_b32_e64 v0, v205, 0, vcc
	v_lshl_add_u64 v[38:39], v[36:37], 0, v[0:1]
	v_lshlrev_b32_e32 v13, 16, v2
	v_and_b32_e32 v14, 0xffff0000, v2
	v_lshlrev_b32_e32 v15, 16, v3
	v_and_b32_e32 v16, 0xffff0000, v3
	global_load_dwordx4 v[0:3], v[38:39], off offset:3328
	v_cndmask_b32_e64 v44, 1.0, 0, vcc
	s_waitcnt vmcnt(0)
	v_lshlrev_b32_e32 v17, 16, v0
	v_and_b32_e32 v18, 0xffff0000, v0
	v_lshlrev_b32_e32 v19, 16, v1
	v_and_b32_e32 v20, 0xffff0000, v1
	v_lshlrev_b32_e32 v21, 16, v2
	v_and_b32_e32 v22, 0xffff0000, v2
	v_lshlrev_b32_e32 v23, 16, v3
	v_and_b32_e32 v24, 0xffff0000, v3
	global_load_dwordx4 v[0:3], v4, s[12:13] offset:16
	s_nop 0
	global_load_dwordx4 v[4:7], v4, s[12:13]
	v_fma_f32 v17, v44, v17, -v8
	s_waitcnt vmcnt(0)
	v_fmac_f32_e32 v8, v4, v17
	v_fma_f32 v17, v44, v18, -v9
	v_fmac_f32_e32 v9, v17, v5
	v_fma_f32 v17, v44, v19, -v10
	v_fmac_f32_e32 v10, v17, v6
	v_fma_f32 v17, v44, v20, -v11
	v_fmac_f32_e32 v11, v17, v7
	v_fma_f32 v17, v44, v21, -v13
	v_fmac_f32_e32 v13, v17, v0
	v_fma_f32 v17, v44, v22, -v14
	v_fmac_f32_e32 v14, v17, v1
	v_fma_f32 v17, v44, v23, -v15
	v_fmac_f32_e32 v15, v17, v2
	v_fma_f32 v17, v44, v24, -v16
	v_fmac_f32_e32 v16, v17, v3
	v_mul_f32_e32 v8, 0xbfb8aa3b, v8
	v_mul_f32_e32 v9, 0xbfb8aa3b, v9
	v_mul_f32_e32 v10, 0xbfb8aa3b, v10
	v_mul_f32_e32 v11, 0xbfb8aa3b, v11
	v_mul_f32_e32 v15, 0xbfb8aa3b, v15
	v_mul_f32_e32 v16, 0xbfb8aa3b, v16
	v_exp_f32_e32 v8, v8
	v_exp_f32_e32 v9, v9
	v_exp_f32_e32 v10, v10
	v_exp_f32_e32 v11, v11
	v_mul_f32_e32 v13, 0xbfb8aa3b, v13
	v_mul_f32_e32 v14, 0xbfb8aa3b, v14
	v_exp_f32_e32 v15, v15
	v_exp_f32_e32 v16, v16
	v_exp_f32_e32 v13, v13
	v_exp_f32_e32 v14, v14
	v_add_f32_e32 v8, 1.0, v8
	v_add_f32_e32 v9, 1.0, v9
	v_add_f32_e32 v10, 1.0, v10
	v_add_f32_e32 v11, 1.0, v11
	v_add_f32_e32 v15, 1.0, v15
	v_add_f32_e32 v16, 1.0, v16
	v_rcp_f32_e32 v8, v8
	v_rcp_f32_e32 v9, v9
	v_rcp_f32_e32 v10, v10
	v_rcp_f32_e32 v11, v11
	v_add_f32_e32 v13, 1.0, v13
	v_add_f32_e32 v14, 1.0, v14
	v_rcp_f32_e32 v15, v15
	v_rcp_f32_e32 v16, v16
	v_rcp_f32_e32 v13, v13
	v_rcp_f32_e32 v14, v14
	v_cvt_pk_bf16_f32 v8, v8, v9
	v_cvt_pk_bf16_f32 v9, v10, v11
	v_cvt_pk_bf16_f32 v11, v15, v16
	v_add_u32_e32 v16, 64, v12
	v_cvt_pk_bf16_f32 v10, v13, v14
	v_mad_i64_i32 v[12:13], s[10:11], v16, s16, v[70:71]
	v_lshl_add_u64 v[40:41], v[12:13], 0, v[134:135]
	global_load_dwordx4 v[12:15], v[40:41], off offset:3328
	s_waitcnt vmcnt(0)
	v_lshlrev_b32_e32 v17, 16, v12
	v_and_b32_e32 v18, 0xffff0000, v12
	v_and_b32_e32 v12, 0xfff, v16
	v_cmp_eq_u32_e32 vcc, 0, v12
	v_lshlrev_b32_e32 v19, 16, v13
	v_and_b32_e32 v20, 0xffff0000, v13
	v_cndmask_b32_e64 v13, -1, 0, vcc
	v_cndmask_b32_e64 v12, v205, 0, vcc
	v_lshl_add_u64 v[42:43], v[40:41], 0, v[12:13]
	v_lshlrev_b32_e32 v21, 16, v14
	v_and_b32_e32 v22, 0xffff0000, v14
	v_lshlrev_b32_e32 v23, 16, v15
	v_and_b32_e32 v24, 0xffff0000, v15
	global_load_dwordx4 v[12:15], v[42:43], off offset:3328
	v_cndmask_b32_e64 v45, 1.0, 0, vcc
	s_waitcnt vmcnt(0)
; __device__ __forceinline__ void rw_shift8(const u16* proj, const float* mu, int m, int col, float* f) {
;   const u16* pr = proj + (size_t)m * PROJ1_LD + col;
;   float a[8], b[8];
;   unpack8(*(const uint4*)pr, a);
;   const bool hasprev = (m & (SEQL - 1)) != 0;
;   unpack8(*(const uint4*)(pr - (hasprev ? PROJ1_LD : 0)), b);
;   const float pz = hasprev ? 1.f : 0.f;
; #pragma unroll
;   for (int i = 0; i < 8; i++) b[i] *= pz;
;   float4 m0 = *(const float4*)(mu + col), m1 = *(const float4*)(mu + col + 4);
;   float mm[8] = {m0.x, m0.y, m0.z, m0.w, m1.x, m1.y, m1.z, m1.w};
; #pragma unroll
;   for (int i = 0; i < 8; i++) f[i] = a[i] + (b[i] - a[i]) * mm[i];
; }
	v_lshlrev_b32_e32 v16, 16, v12
	v_and_b32_e32 v12, 0xffff0000, v12
	v_fma_f32 v16, v45, v16, -v17
	v_lshlrev_b32_e32 v25, 16, v13
	v_fmac_f32_e32 v17, v4, v16
	v_fma_f32 v4, v45, v12, -v18
	v_and_b32_e32 v13, 0xffff0000, v13
	v_fmac_f32_e32 v18, v5, v4
	v_fma_f32 v4, v45, v25, -v19
	v_lshlrev_b32_e32 v26, 16, v14
	v_fmac_f32_e32 v19, v6, v4
	v_fma_f32 v4, v45, v13, -v20
	v_and_b32_e32 v14, 0xffff0000, v14
	v_fmac_f32_e32 v20, v7, v4
	v_fma_f32 v4, v45, v26, -v21
	v_lshlrev_b32_e32 v27, 16, v15
	v_fmac_f32_e32 v21, v0, v4
	v_fma_f32 v0, v45, v14, -v22
	v_and_b32_e32 v15, 0xffff0000, v15
	v_fmac_f32_e32 v22, v1, v0
	v_fma_f32 v0, v45, v27, -v23
	v_fmac_f32_e32 v23, v2, v0
	v_fma_f32 v0, v45, v15, -v24
	v_fmac_f32_e32 v24, v3, v0
	v_mul_f32_e32 v0, 0xbfb8aa3b, v17
	v_mul_f32_e32 v1, 0xbfb8aa3b, v18
	v_mul_f32_e32 v2, 0xbfb8aa3b, v19
	v_mul_f32_e32 v3, 0xbfb8aa3b, v20
	v_mul_f32_e32 v4, 0xbfb8aa3b, v21
	v_mul_f32_e32 v5, 0xbfb8aa3b, v22
	v_exp_f32_e32 v0, v0
	v_exp_f32_e32 v1, v1
	v_exp_f32_e32 v2, v2
	v_exp_f32_e32 v3, v3
	v_exp_f32_e32 v4, v4
	v_exp_f32_e32 v5, v5
	v_mul_f32_e32 v6, 0xbfb8aa3b, v23
	v_mul_f32_e32 v7, 0xbfb8aa3b, v24
	v_exp_f32_e32 v6, v6
	v_exp_f32_e32 v7, v7
	v_add_f32_e32 v0, 1.0, v0
	v_add_f32_e32 v1, 1.0, v1
	v_add_f32_e32 v2, 1.0, v2
	v_add_f32_e32 v3, 1.0, v3
	v_add_f32_e32 v4, 1.0, v4
	v_add_f32_e32 v5, 1.0, v5
	v_rcp_f32_e32 v0, v0
	v_rcp_f32_e32 v1, v1
	v_rcp_f32_e32 v2, v2
	v_rcp_f32_e32 v3, v3
	v_rcp_f32_e32 v4, v4
	v_rcp_f32_e32 v5, v5
	v_add_f32_e32 v6, 1.0, v6
	v_add_f32_e32 v7, 1.0, v7
	v_rcp_f32_e32 v6, v6
	v_rcp_f32_e32 v7, v7
	v_cvt_pk_bf16_f32 v0, v0, v1
	v_cvt_pk_bf16_f32 v1, v2, v3
	v_cvt_pk_bf16_f32 v2, v4, v5
	v_add_co_u32_e32 v4, vcc, s17, v32
	v_cvt_pk_bf16_f32 v3, v6, v7
	s_nop 0
	v_addc_co_u32_e32 v5, vcc, 0, v33, vcc
	global_load_dwordx4 v[12:15], v[32:33], off
	global_load_dwordx4 v[16:19], v[4:5], off
	s_nop 0
	global_load_dwordx4 v[4:7], v[36:37], off offset:3392
	v_or_b32_e32 v24, 0x1a80, v46
	s_waitcnt vmcnt(0)
	v_lshlrev_b32_e32 v28, 16, v4
	v_and_b32_e32 v29, 0xffff0000, v4
	v_lshlrev_b32_e32 v30, 16, v5
	v_and_b32_e32 v31, 0xffff0000, v5
	v_lshlrev_b32_e32 v50, 16, v6
	v_and_b32_e32 v51, 0xffff0000, v6
	v_lshlrev_b32_e32 v52, 16, v7
	v_and_b32_e32 v53, 0xffff0000, v7
	global_load_dwordx4 v[4:7], v[38:39], off offset:3392
	global_load_dwordx4 v[20:23], v24, s[12:13] offset:16
	s_nop 0
	global_load_dwordx4 v[24:27], v24, s[12:13]
	s_waitcnt vmcnt(2)
	v_lshlrev_b32_e32 v54, 16, v4
	v_and_b32_e32 v4, 0xffff0000, v4
	v_lshlrev_b32_e32 v55, 16, v5
	v_fma_f32 v4, v44, v4, -v29
	v_and_b32_e32 v5, 0xffff0000, v5
	s_waitcnt vmcnt(0)
	v_fmac_f32_e32 v29, v4, v25
	v_fma_f32 v4, v44, v55, -v30
	v_lshlrev_b32_e32 v56, 16, v6
	v_fmac_f32_e32 v30, v4, v26
	v_fma_f32 v4, v44, v5, -v31
	v_and_b32_e32 v6, 0xffff0000, v6
	v_fmac_f32_e32 v31, v4, v27
	v_fma_f32 v4, v44, v56, -v50
	v_lshlrev_b32_e32 v57, 16, v7
	v_fmac_f32_e32 v50, v4, v20
	v_fma_f32 v4, v44, v6, -v51
	v_and_b32_e32 v7, 0xffff0000, v7
	v_fmac_f32_e32 v51, v4, v21
	v_fma_f32 v4, v44, v57, -v52
	v_fma_f32 v54, v44, v54, -v28
	v_fmac_f32_e32 v52, v4, v22
	v_fma_f32 v4, v44, v7, -v53
	v_fmac_f32_e32 v28, v24, v54
	v_fmac_f32_e32 v53, v4, v23
	v_mul_f32_e32 v4, 0xbfb8aa3b, v28
	v_mul_f32_e32 v5, 0xbfb8aa3b, v29
	v_mul_f32_e32 v6, 0xbfb8aa3b, v30
	v_mul_f32_e32 v7, 0xbfb8aa3b, v31
	v_mul_f32_e32 v28, 0xbfb8aa3b, v50
	v_mul_f32_e32 v29, 0xbfb8aa3b, v51
	v_mul_f32_e32 v30, 0xbfb8aa3b, v52
	v_mul_f32_e32 v31, 0xbfb8aa3b, v53
	v_exp_f32_e32 v4, v4
	v_exp_f32_e32 v5, v5
	v_exp_f32_e32 v6, v6
	v_exp_f32_e32 v7, v7
	v_exp_f32_e32 v28, v28
	v_exp_f32_e32 v29, v29
	v_exp_f32_e32 v30, v30
	v_exp_f32_e32 v31, v31
	v_add_f32_e32 v4, 1.0, v4
	v_add_f32_e32 v5, 1.0, v5
	v_add_f32_e32 v6, 1.0, v6
	v_add_f32_e32 v7, 1.0, v7
	v_add_f32_e32 v28, 1.0, v28
	v_add_f32_e32 v29, 1.0, v29
	v_add_f32_e32 v30, 1.0, v30
	v_add_f32_e32 v31, 1.0, v31
	v_rcp_f32_e32 v4, v4
	v_rcp_f32_e32 v5, v5
	v_rcp_f32_e32 v6, v6
	v_rcp_f32_e32 v7, v7
	v_rcp_f32_e32 v28, v28
	v_rcp_f32_e32 v29, v29
	v_rcp_f32_e32 v30, v30
	v_rcp_f32_e32 v31, v31
	v_cvt_pk_bf16_f32 v4, v4, v5
	v_cvt_pk_bf16_f32 v5, v6, v7
	v_cvt_pk_bf16_f32 v6, v28, v29
	v_cvt_pk_bf16_f32 v7, v30, v31
	global_load_dwordx4 v[28:31], v[40:41], off offset:3392
	s_waitcnt vmcnt(0)
	v_lshlrev_b32_e32 v50, 16, v28
	v_and_b32_e32 v51, 0xffff0000, v28
	v_lshlrev_b32_e32 v52, 16, v29
	v_and_b32_e32 v53, 0xffff0000, v29
	v_lshlrev_b32_e32 v54, 16, v30
	v_and_b32_e32 v55, 0xffff0000, v30
	v_lshlrev_b32_e32 v56, 16, v31
	v_and_b32_e32 v57, 0xffff0000, v31
	global_load_dwordx4 v[28:31], v[42:43], off offset:3392
	s_waitcnt vmcnt(0)
; #define G_LOAD(r0, r1, r2, r3, kt_)                                                    \
;   { const int k0_ = (kt_) * 32; r0 = al(m0 + lr0, k0_ + lkc, nt); r1 = al(m0 + lr0 + 64, k0_ + lkc, nt); \
;     r2 = *(const bf16x8*)(wp0 + k0_); r3 = *(const bf16x8*)(wp1 + k0_); }
; template <class AL, class EP>
; __device__ __forceinline__ void gemm_tile(const AL& al, const u16* __restrict__ Wt, int K, int m0, int n0, int nt,
;                                           const EP& ep, u16* sm) {
;     ...
;   G_LOAD(e0, e1, e2, e3, 0);
;   G_LOAD(o0, o1, o2, o3, 1);
;   G_STORE(e0, e1, e2, e3, 0);
;   if (nk > 2) G_LOAD(e0, e1, e2, e3, 2);
;   __syncthreads();
; __device__ __forceinline__ void rw_shift8(const u16* proj, const float* mu, int m, int col, float* f) {
;   const u16* pr = proj + (size_t)m * PROJ1_LD + col;
;   float a[8], b[8];
;   unpack8(*(const uint4*)pr, a);
;   const bool hasprev = (m & (SEQL - 1)) != 0;
;   unpack8(*(const uint4*)(pr - (hasprev ? PROJ1_LD : 0)), b);
;   const float pz = hasprev ? 1.f : 0.f;
; #pragma unroll
;   for (int i = 0; i < 8; i++) b[i] *= pz;
;   float4 m0 = *(const float4*)(mu + col), m1 = *(const float4*)(mu + col + 4);
;   float mm[8] = {m0.x, m0.y, m0.z, m0.w, m1.x, m1.y, m1.z, m1.w};
; #pragma unroll
;   for (int i = 0; i < 8; i++) f[i] = a[i] + (b[i] - a[i]) * mm[i];
; }
	v_lshlrev_b32_e32 v58, 16, v28
	v_and_b32_e32 v28, 0xffff0000, v28
	v_fma_f32 v58, v45, v58, -v50
	v_lshlrev_b32_e32 v59, 16, v29
	v_fmac_f32_e32 v50, v24, v58
	v_fma_f32 v24, v45, v28, -v51
	v_and_b32_e32 v29, 0xffff0000, v29
	v_fmac_f32_e32 v51, v25, v24
	v_fma_f32 v24, v45, v59, -v52
	v_lshlrev_b32_e32 v60, 16, v30
	v_fmac_f32_e32 v52, v26, v24
	v_fma_f32 v24, v45, v29, -v53
	v_and_b32_e32 v30, 0xffff0000, v30
	v_fmac_f32_e32 v53, v27, v24
	v_fma_f32 v24, v45, v60, -v54
	v_lshlrev_b32_e32 v61, 16, v31
	v_fmac_f32_e32 v54, v20, v24
	v_fma_f32 v20, v45, v30, -v55
	v_and_b32_e32 v31, 0xffff0000, v31
	v_fmac_f32_e32 v55, v21, v20
	v_fma_f32 v20, v45, v61, -v56
	v_fmac_f32_e32 v56, v22, v20
	v_fma_f32 v20, v45, v31, -v57
	v_fmac_f32_e32 v57, v23, v20
	v_mul_f32_e32 v20, 0xbfb8aa3b, v50
	v_mul_f32_e32 v21, 0xbfb8aa3b, v51
	v_mul_f32_e32 v22, 0xbfb8aa3b, v52
	v_mul_f32_e32 v23, 0xbfb8aa3b, v53
	v_mul_f32_e32 v24, 0xbfb8aa3b, v54
	v_mul_f32_e32 v25, 0xbfb8aa3b, v55
	v_mul_f32_e32 v26, 0xbfb8aa3b, v56
	v_mul_f32_e32 v27, 0xbfb8aa3b, v57
	v_exp_f32_e32 v20, v20
	v_exp_f32_e32 v21, v21
	v_exp_f32_e32 v22, v22
	v_exp_f32_e32 v23, v23
	v_exp_f32_e32 v24, v24
	v_exp_f32_e32 v25, v25
	v_exp_f32_e32 v26, v26
	v_exp_f32_e32 v27, v27
	v_add_f32_e32 v20, 1.0, v20
	v_add_f32_e32 v21, 1.0, v21
	v_add_f32_e32 v22, 1.0, v22
	v_add_f32_e32 v23, 1.0, v23
	v_add_f32_e32 v24, 1.0, v24
	v_add_f32_e32 v25, 1.0, v25
	v_add_f32_e32 v26, 1.0, v26
	v_add_f32_e32 v27, 1.0, v27
	v_rcp_f32_e32 v20, v20
	v_rcp_f32_e32 v21, v21
	v_rcp_f32_e32 v22, v22
	v_rcp_f32_e32 v23, v23
	v_rcp_f32_e32 v24, v24
	v_rcp_f32_e32 v25, v25
	v_rcp_f32_e32 v26, v26
	v_rcp_f32_e32 v27, v27
	v_cvt_pk_bf16_f32 v20, v20, v21
	v_cvt_pk_bf16_f32 v21, v22, v23
	v_cvt_pk_bf16_f32 v22, v24, v25
	v_cvt_pk_bf16_f32 v23, v26, v27
	global_load_dwordx4 v[24:27], v[32:33], off offset:64
	global_load_dwordx4 v[28:31], v[34:35], off offset:64
	ds_write_b128 v47, v[8:11]
	ds_write_b128 v47, v[0:3] offset:4096
	ds_write_b128 v47, v[12:15] offset:16384
	ds_write_b128 v47, v[16:19] offset:20480
	global_load_dwordx4 v[0:3], v[36:37], off offset:3456
	v_or_b32_e32 v12, 0x1b00, v46
	s_waitcnt vmcnt(0)
	v_lshlrev_b32_e32 v16, 16, v0
	v_and_b32_e32 v17, 0xffff0000, v0
	v_lshlrev_b32_e32 v18, 16, v1
	v_and_b32_e32 v19, 0xffff0000, v1
	v_lshlrev_b32_e32 v49, 16, v2
	v_and_b32_e32 v50, 0xffff0000, v2
	v_lshlrev_b32_e32 v51, 16, v3
	v_and_b32_e32 v52, 0xffff0000, v3
	global_load_dwordx4 v[0:3], v[38:39], off offset:3456
	global_load_dwordx4 v[8:11], v12, s[12:13] offset:16
	s_nop 0
	global_load_dwordx4 v[12:15], v12, s[12:13]
	s_waitcnt vmcnt(2)
	v_lshlrev_b32_e32 v53, 16, v0
	v_and_b32_e32 v0, 0xffff0000, v0
	v_lshlrev_b32_e32 v54, 16, v1
	v_fma_f32 v0, v44, v0, -v17
	v_and_b32_e32 v1, 0xffff0000, v1
	s_waitcnt vmcnt(0)
	v_fmac_f32_e32 v17, v0, v13
	v_fma_f32 v0, v44, v54, -v18
	v_lshlrev_b32_e32 v55, 16, v2
	v_fmac_f32_e32 v18, v0, v14
	v_fma_f32 v0, v44, v1, -v19
	v_and_b32_e32 v2, 0xffff0000, v2
	v_fmac_f32_e32 v19, v0, v15
	v_fma_f32 v0, v44, v55, -v49
	v_lshlrev_b32_e32 v56, 16, v3
	v_fmac_f32_e32 v49, v0, v8
	v_fma_f32 v0, v44, v2, -v50
	v_and_b32_e32 v3, 0xffff0000, v3
	v_fmac_f32_e32 v50, v0, v9
	v_fma_f32 v0, v44, v56, -v51
	v_fma_f32 v53, v44, v53, -v16
	v_fmac_f32_e32 v51, v0, v10
	v_fma_f32 v0, v44, v3, -v52
	v_fmac_f32_e32 v16, v12, v53
	v_fmac_f32_e32 v52, v0, v11
	v_mul_f32_e32 v0, 0xbfb8aa3b, v16
	v_mul_f32_e32 v1, 0xbfb8aa3b, v17
	v_mul_f32_e32 v2, 0xbfb8aa3b, v18
	v_mul_f32_e32 v3, 0xbfb8aa3b, v19
	v_mul_f32_e32 v16, 0xbfb8aa3b, v49
	v_mul_f32_e32 v17, 0xbfb8aa3b, v50
	v_mul_f32_e32 v18, 0xbfb8aa3b, v51
	v_mul_f32_e32 v19, 0xbfb8aa3b, v52
	v_exp_f32_e32 v0, v0
	v_exp_f32_e32 v1, v1
	v_exp_f32_e32 v2, v2
	v_exp_f32_e32 v3, v3
	v_exp_f32_e32 v16, v16
	v_exp_f32_e32 v17, v17
	v_exp_f32_e32 v18, v18
	v_exp_f32_e32 v19, v19
	v_add_f32_e32 v0, 1.0, v0
	v_add_f32_e32 v1, 1.0, v1
	v_add_f32_e32 v2, 1.0, v2
	v_add_f32_e32 v3, 1.0, v3
	v_add_f32_e32 v16, 1.0, v16
	v_add_f32_e32 v17, 1.0, v17
	v_add_f32_e32 v18, 1.0, v18
	v_add_f32_e32 v19, 1.0, v19
	v_rcp_f32_e32 v0, v0
	v_rcp_f32_e32 v1, v1
	v_rcp_f32_e32 v2, v2
	v_rcp_f32_e32 v3, v3
	v_rcp_f32_e32 v16, v16
	v_rcp_f32_e32 v17, v17
	v_rcp_f32_e32 v18, v18
	v_rcp_f32_e32 v19, v19
	v_cvt_pk_bf16_f32 v0, v0, v1
	v_cvt_pk_bf16_f32 v1, v2, v3
	v_cvt_pk_bf16_f32 v2, v16, v17
	v_cvt_pk_bf16_f32 v3, v18, v19
	global_load_dwordx4 v[16:19], v[40:41], off offset:3456
	s_waitcnt vmcnt(0)
	v_lshlrev_b32_e32 v49, 16, v16
	v_and_b32_e32 v50, 0xffff0000, v16
	v_lshlrev_b32_e32 v51, 16, v17
	v_and_b32_e32 v52, 0xffff0000, v17
	v_lshlrev_b32_e32 v53, 16, v18
	v_and_b32_e32 v54, 0xffff0000, v18
	v_lshlrev_b32_e32 v55, 16, v19
	v_and_b32_e32 v56, 0xffff0000, v19
	global_load_dwordx4 v[16:19], v[42:43], off offset:3456
	s_waitcnt vmcnt(0)
	v_lshlrev_b32_e32 v57, 16, v16
	v_and_b32_e32 v16, 0xffff0000, v16
	v_fma_f32 v57, v45, v57, -v49
	v_lshlrev_b32_e32 v58, 16, v17
	v_fmac_f32_e32 v49, v12, v57
	v_fma_f32 v12, v45, v16, -v50
	v_and_b32_e32 v17, 0xffff0000, v17
	v_fmac_f32_e32 v50, v13, v12
	v_fma_f32 v12, v45, v58, -v51
	v_lshlrev_b32_e32 v59, 16, v18
	v_fmac_f32_e32 v51, v14, v12
	v_fma_f32 v12, v45, v17, -v52
	v_and_b32_e32 v18, 0xffff0000, v18
	v_fmac_f32_e32 v52, v15, v12
	v_fma_f32 v12, v45, v59, -v53
	v_lshlrev_b32_e32 v60, 16, v19
	v_fmac_f32_e32 v53, v8, v12
	v_fma_f32 v8, v45, v18, -v54
	v_and_b32_e32 v19, 0xffff0000, v19
	v_fmac_f32_e32 v54, v9, v8
	v_fma_f32 v8, v45, v60, -v55
	v_fmac_f32_e32 v55, v10, v8
	v_fma_f32 v8, v45, v19, -v56
	v_fmac_f32_e32 v56, v11, v8
	v_mul_f32_e32 v8, 0xbfb8aa3b, v49
	v_mul_f32_e32 v9, 0xbfb8aa3b, v50
	v_mul_f32_e32 v10, 0xbfb8aa3b, v51
	v_mul_f32_e32 v11, 0xbfb8aa3b, v52
	v_mul_f32_e32 v12, 0xbfb8aa3b, v53
	v_mul_f32_e32 v13, 0xbfb8aa3b, v54
	v_mul_f32_e32 v14, 0xbfb8aa3b, v55
	v_mul_f32_e32 v15, 0xbfb8aa3b, v56
	v_exp_f32_e32 v8, v8
	v_exp_f32_e32 v9, v9
	v_exp_f32_e32 v10, v10
	v_exp_f32_e32 v11, v11
	v_exp_f32_e32 v12, v12
	v_exp_f32_e32 v13, v13
	v_exp_f32_e32 v14, v14
	v_exp_f32_e32 v15, v15
	v_add_f32_e32 v8, 1.0, v8
	v_add_f32_e32 v9, 1.0, v9
	v_add_f32_e32 v10, 1.0, v10
	v_add_f32_e32 v11, 1.0, v11
	v_add_f32_e32 v12, 1.0, v12
	v_add_f32_e32 v13, 1.0, v13
	v_add_f32_e32 v14, 1.0, v14
	v_add_f32_e32 v15, 1.0, v15
	v_rcp_f32_e32 v8, v8
	v_rcp_f32_e32 v9, v9
	v_rcp_f32_e32 v10, v10
	v_rcp_f32_e32 v11, v11
	v_rcp_f32_e32 v12, v12
	v_rcp_f32_e32 v13, v13
	v_rcp_f32_e32 v14, v14
	v_rcp_f32_e32 v15, v15
	v_lshlrev_b32_e32 v49, 12, v64
	v_or3_b32 v68, v48, v49, v62
	v_lshlrev_b32_e32 v49, 12, v65
	v_or3_b32 v69, v48, v49, v62
	v_cvt_pk_bf16_f32 v8, v8, v9
	v_cvt_pk_bf16_f32 v9, v10, v11
	v_cvt_pk_bf16_f32 v10, v12, v13
	v_cvt_pk_bf16_f32 v11, v14, v15
	global_load_dwordx4 v[12:15], v[34:35], off offset:128
	global_load_dwordx4 v[16:19], v[32:33], off offset:128
	s_waitcnt lgkmcnt(0)
	s_barrier
; #define G_LOAD(r0, r1, r2, r3, kt_)                                                    \
;   { const int k0_ = (kt_) * 32; r0 = al(m0 + lr0, k0_ + lkc, nt); r1 = al(m0 + lr0 + 64, k0_ + lkc, nt); \
;     r2 = *(const bf16x8*)(wp0 + k0_); r3 = *(const bf16x8*)(wp1 + k0_); }
; template <class AL, class EP>
; __device__ __forceinline__ void gemm_tile(const AL& al, const u16* __restrict__ Wt, int K, int m0, int n0, int nt,
;                                           const EP& ep, u16* sm) {
;     ...
;   G_LOAD(e0, e1, e2, e3, 0);
;   G_LOAD(o0, o1, o2, o3, 1);
;   G_STORE(e0, e1, e2, e3, 0);
;   if (nk > 2) G_LOAD(e0, e1, e2, e3, 2);
;   __syncthreads();
;   for (int kt = 0; kt < nk; kt += 2) {
;     G_COMPUTE(0);
;     G_STORE(o0, o1, o2, o3, 1);
;     if (kt + 3 < nk) G_LOAD(o0, o1, o2, o3, kt + 3);
;     __syncthreads();
;     G_COMPUTE(1);
;     if (kt + 2 < nk) {
;       G_STORE(e0, e1, e2, e3, 0);
;       if (kt + 4 < nk) G_LOAD(e0, e1, e2, e3, kt + 4);
;     }
;     __syncthreads();
;   }
	ds_read_b128 v[50:53], v68 offset:16384
	ds_read_b128 v[54:57], v68 offset:17408
	ds_read_b128 v[58:61], v68 offset:18432
	ds_read_b128 v[72:75], v68 offset:19456
	ds_read_b128 v[76:79], v69
	ds_read_b128 v[80:83], v69 offset:1024
	ds_read_b128 v[84:87], v69 offset:2048
	ds_read_b128 v[88:91], v69 offset:3072
	ds_write_b128 v47, v[4:7] offset:8192
	ds_write_b128 v47, v[20:23] offset:12288
	ds_write_b128 v47, v[24:27] offset:24576
	ds_write_b128 v47, v[28:31] offset:28672
	global_load_dwordx4 v[4:7], v[36:37], off offset:3520
	v_or_b32_e32 v20, 0x1b80, v46
	s_waitcnt lgkmcnt(7)
	v_mfma_f32_16x16x32_bf16 v[92:95], v[50:53], v[76:79], 0
	v_lshl_or_b32 v65, v65, 6, v67
	v_subrev_u32_e32 v65, s7, v65
	s_waitcnt vmcnt(0)
	v_lshlrev_b32_e32 v24, 16, v4
	v_and_b32_e32 v25, 0xffff0000, v4
	v_lshlrev_b32_e32 v26, 16, v5
	v_and_b32_e32 v27, 0xffff0000, v5
	v_lshlrev_b32_e32 v28, 16, v6
	v_and_b32_e32 v29, 0xffff0000, v6
	v_lshlrev_b32_e32 v30, 16, v7
	v_and_b32_e32 v31, 0xffff0000, v7
	global_load_dwordx4 v[4:7], v[38:39], off offset:3520
	s_waitcnt lgkmcnt(6)
	v_mfma_f32_16x16x32_bf16 v[96:99], v[50:53], v[80:83], 0
	s_waitcnt vmcnt(0)
	v_lshlrev_b32_e32 v36, 16, v4
	s_waitcnt lgkmcnt(5)
	v_mfma_f32_16x16x32_bf16 v[100:103], v[50:53], v[84:87], 0
	v_and_b32_e32 v37, 0xffff0000, v4
	v_lshlrev_b32_e32 v38, 16, v5
	v_and_b32_e32 v39, 0xffff0000, v5
	s_waitcnt lgkmcnt(4)
	v_mfma_f32_16x16x32_bf16 v[48:51], v[50:53], v[88:91], 0
	v_fma_f32 v36, v44, v36, -v24
	v_mfma_f32_16x16x32_bf16 v[104:107], v[54:57], v[76:79], 0
	v_mfma_f32_16x16x32_bf16 v[108:111], v[54:57], v[80:83], 0
	v_mfma_f32_16x16x32_bf16 v[112:115], v[54:57], v[84:87], 0
	v_mfma_f32_16x16x32_bf16 v[52:55], v[54:57], v[88:91], 0
	v_mfma_f32_16x16x32_bf16 v[116:119], v[58:61], v[76:79], 0
	v_mfma_f32_16x16x32_bf16 v[120:123], v[58:61], v[80:83], 0
	v_mfma_f32_16x16x32_bf16 v[124:127], v[58:61], v[84:87], 0
	v_mfma_f32_16x16x32_bf16 v[56:59], v[58:61], v[88:91], 0
	v_mfma_f32_16x16x32_bf16 v[60:63], v[72:75], v[76:79], 0
	v_mfma_f32_16x16x32_bf16 v[76:79], v[72:75], v[80:83], 0
	v_mfma_f32_16x16x32_bf16 v[80:83], v[72:75], v[84:87], 0
	v_lshlrev_b32_e32 v84, 16, v6
	v_and_b32_e32 v85, 0xffff0000, v6
	v_lshlrev_b32_e32 v86, 16, v7
	v_and_b32_e32 v87, 0xffff0000, v7
	global_load_dwordx4 v[4:7], v20, s[12:13] offset:16
	s_nop 0
	global_load_dwordx4 v[20:23], v20, s[12:13]
	v_mfma_f32_16x16x32_bf16 v[72:75], v[72:75], v[88:91], 0
	s_waitcnt vmcnt(0)
	v_fmac_f32_e32 v24, v20, v36
	v_fma_f32 v36, v44, v37, -v25
	v_fmac_f32_e32 v25, v36, v21
	v_fma_f32 v36, v44, v38, -v26
	v_fmac_f32_e32 v26, v36, v22
	v_fma_f32 v36, v44, v39, -v27
	v_fmac_f32_e32 v27, v36, v23
	v_fma_f32 v36, v44, v84, -v28
	v_fmac_f32_e32 v28, v36, v4
	v_fma_f32 v36, v44, v85, -v29
	v_fmac_f32_e32 v29, v36, v5
	v_fma_f32 v36, v44, v86, -v30
	v_fmac_f32_e32 v30, v36, v6
	v_fma_f32 v36, v44, v87, -v31
	v_fmac_f32_e32 v31, v36, v7
	v_mul_f32_e32 v24, 0xbfb8aa3b, v24
	v_mul_f32_e32 v25, 0xbfb8aa3b, v25
	v_mul_f32_e32 v26, 0xbfb8aa3b, v26
	v_mul_f32_e32 v27, 0xbfb8aa3b, v27
	v_mul_f32_e32 v28, 0xbfb8aa3b, v28
	v_mul_f32_e32 v29, 0xbfb8aa3b, v29
	v_mul_f32_e32 v30, 0xbfb8aa3b, v30
	v_mul_f32_e32 v31, 0xbfb8aa3b, v31
	v_exp_f32_e32 v24, v24
	v_exp_f32_e32 v25, v25
	v_exp_f32_e32 v26, v26
	v_exp_f32_e32 v27, v27
	v_exp_f32_e32 v28, v28
	v_exp_f32_e32 v29, v29
	v_exp_f32_e32 v30, v30
	v_exp_f32_e32 v31, v31
	v_add_f32_e32 v24, 1.0, v24
	v_add_f32_e32 v25, 1.0, v25
	v_add_f32_e32 v26, 1.0, v26
	v_add_f32_e32 v27, 1.0, v27
	v_add_f32_e32 v28, 1.0, v28
	v_add_f32_e32 v29, 1.0, v29
	v_add_f32_e32 v30, 1.0, v30
	v_add_f32_e32 v31, 1.0, v31
	v_rcp_f32_e32 v24, v24
	v_rcp_f32_e32 v25, v25
	v_rcp_f32_e32 v26, v26
	v_rcp_f32_e32 v27, v27
	v_rcp_f32_e32 v28, v28
	v_rcp_f32_e32 v29, v29
	v_rcp_f32_e32 v30, v30
	v_rcp_f32_e32 v31, v31
	v_cvt_pk_bf16_f32 v24, v24, v25
	v_cvt_pk_bf16_f32 v25, v26, v27
	v_cvt_pk_bf16_f32 v26, v28, v29
	v_cvt_pk_bf16_f32 v27, v30, v31
	global_load_dwordx4 v[28:31], v[40:41], off offset:3520
	s_waitcnt vmcnt(0)
	v_lshlrev_b32_e32 v36, 16, v28
	v_and_b32_e32 v37, 0xffff0000, v28
	v_lshlrev_b32_e32 v38, 16, v29
	v_and_b32_e32 v39, 0xffff0000, v29
	v_lshlrev_b32_e32 v40, 16, v30
	v_and_b32_e32 v41, 0xffff0000, v30
	v_lshlrev_b32_e32 v44, 16, v31
	v_and_b32_e32 v46, 0xffff0000, v31
	global_load_dwordx4 v[28:31], v[42:43], off offset:3520
	s_waitcnt vmcnt(0)
	v_lshlrev_b32_e32 v42, 16, v28
	v_and_b32_e32 v28, 0xffff0000, v28
	v_fma_f32 v42, v45, v42, -v36
	v_lshlrev_b32_e32 v43, 16, v29
	v_fmac_f32_e32 v36, v20, v42
	v_fma_f32 v20, v45, v28, -v37
	v_and_b32_e32 v29, 0xffff0000, v29
	v_fmac_f32_e32 v37, v21, v20
	v_fma_f32 v20, v45, v43, -v38
	v_lshlrev_b32_e32 v84, 16, v30
	v_fmac_f32_e32 v38, v22, v20
	v_fma_f32 v20, v45, v29, -v39
	v_and_b32_e32 v30, 0xffff0000, v30
	v_fmac_f32_e32 v39, v23, v20
	v_fma_f32 v20, v45, v84, -v40
	v_lshlrev_b32_e32 v85, 16, v31
	v_fmac_f32_e32 v40, v4, v20
	v_fma_f32 v4, v45, v30, -v41
	v_and_b32_e32 v31, 0xffff0000, v31
	v_fmac_f32_e32 v41, v5, v4
	v_fma_f32 v4, v45, v85, -v44
	v_fmac_f32_e32 v44, v6, v4
	v_fma_f32 v4, v45, v31, -v46
	v_fmac_f32_e32 v46, v7, v4
	v_mul_f32_e32 v4, 0xbfb8aa3b, v36
	v_mul_f32_e32 v5, 0xbfb8aa3b, v37
	v_mul_f32_e32 v6, 0xbfb8aa3b, v38
	v_mul_f32_e32 v7, 0xbfb8aa3b, v39
	v_mul_f32_e32 v20, 0xbfb8aa3b, v40
	v_mul_f32_e32 v21, 0xbfb8aa3b, v41
	v_mul_f32_e32 v22, 0xbfb8aa3b, v44
	v_mul_f32_e32 v23, 0xbfb8aa3b, v46
	v_exp_f32_e32 v4, v4
	v_exp_f32_e32 v5, v5
	v_exp_f32_e32 v6, v6
	v_exp_f32_e32 v7, v7
	v_exp_f32_e32 v20, v20
	v_exp_f32_e32 v21, v21
	v_exp_f32_e32 v22, v22
	v_exp_f32_e32 v23, v23
	v_add_f32_e32 v4, 1.0, v4
	v_add_f32_e32 v5, 1.0, v5
	v_add_f32_e32 v6, 1.0, v6
	v_add_f32_e32 v7, 1.0, v7
	v_add_f32_e32 v20, 1.0, v20
	v_add_f32_e32 v21, 1.0, v21
	v_add_f32_e32 v22, 1.0, v22
	v_add_f32_e32 v23, 1.0, v23
	v_rcp_f32_e32 v4, v4
	v_rcp_f32_e32 v5, v5
	v_rcp_f32_e32 v6, v6
	v_rcp_f32_e32 v7, v7
	v_rcp_f32_e32 v20, v20
	v_rcp_f32_e32 v21, v21
	v_rcp_f32_e32 v22, v22
	v_rcp_f32_e32 v23, v23
	v_cvt_pk_bf16_f32 v4, v4, v5
	v_cvt_pk_bf16_f32 v5, v6, v7
	v_cvt_pk_bf16_f32 v6, v20, v21
	v_cvt_pk_bf16_f32 v7, v22, v23
	global_load_dwordx4 v[20:23], v[32:33], off offset:192
	global_load_dwordx4 v[28:31], v[34:35], off offset:192
	s_waitcnt lgkmcnt(0)
	s_barrier
; __device__ __forceinline__ void unpack4(uint2 u, float* f) { f[0] = bflo(u.x); f[1] = bfhi(u.x); f[2] = bflo(u.y); f[3] = bfhi(u.y); }
; #define G_LOAD(r0, r1, r2, r3, kt_)                                                    \
;   { const int k0_ = (kt_) * 32; r0 = al(m0 + lr0, k0_ + lkc, nt); r1 = al(m0 + lr0 + 64, k0_ + lkc, nt); \
;     r2 = *(const bf16x8*)(wp0 + k0_); r3 = *(const bf16x8*)(wp1 + k0_); }
; template <class AL, class EP>
; __device__ __forceinline__ void gemm_tile(const AL& al, const u16* __restrict__ Wt, int K, int m0, int n0, int nt,
;                                           const EP& ep, u16* sm) {
;     ...
;   for (int kt = 0; kt < nk; kt += 2) {
;     G_COMPUTE(0);
;     G_STORE(o0, o1, o2, o3, 1);
;     if (kt + 3 < nk) G_LOAD(o0, o1, o2, o3, kt + 3);
;     __syncthreads();
;     G_COMPUTE(1);
;     if (kt + 2 < nk) {
;       G_STORE(e0, e1, e2, e3, 0);
;       if (kt + 4 < nk) G_LOAD(e0, e1, e2, e3, kt + 4);
;     }
;     __syncthreads();
;   }
;   __device__ __forceinline__ void operator()(f32x4 (&acc)[4][4], int mw, int nw, int lane, int) const {
;     ...
; #pragma unroll
;     for (int j = 0; j < 4; j++) {
;       const int m = mw + j * 16 + (lane & 15);
;       float y[16], sum = 0.f;
;       const float c3 = c3buf[(size_t)m * 8 + hh];
; #pragma unroll
;       for (int i = 0; i < 4; i++) {
;         const int ch = nw + i * 16 + (lane >> 4) * 4;
;         unpack4(*(const uint2*)(A + (size_t)m * 1024 + ch), y + i * 4);
;         sum += y[i * 4] + y[i * 4 + 1] + y[i * 4 + 2] + y[i * 4 + 3];
;       }
	ds_read_b128 v[32:35], v68 offset:24576
	ds_read_b128 v[36:39], v68 offset:25600
	ds_read_b128 v[40:43], v68 offset:26624
	ds_read_b128 v[84:87], v68 offset:27648
	ds_read_b128 v[88:91], v69 offset:8192
	ds_read_b128 v[128:131], v69 offset:9216
	ds_read_b128 v[144:147], v69 offset:10240
	ds_read_b128 v[148:151], v69 offset:11264
	s_waitcnt lgkmcnt(3)
	v_mfma_f32_16x16x32_bf16 v[92:95], v[32:35], v[88:91], v[92:95]
	ds_write_b128 v47, v[0:3]
	ds_write_b128 v47, v[8:11] offset:4096
	ds_write_b128 v47, v[16:19] offset:16384
	ds_write_b128 v47, v[12:15] offset:20480
	s_waitcnt lgkmcnt(0)
	s_barrier
	v_mfma_f32_16x16x32_bf16 v[96:99], v[32:35], v[128:131], v[96:99]
	v_mfma_f32_16x16x32_bf16 v[100:103], v[32:35], v[144:147], v[100:103]
	v_mfma_f32_16x16x32_bf16 v[32:35], v[32:35], v[148:151], v[48:51]
	v_mfma_f32_16x16x32_bf16 v[48:51], v[36:39], v[88:91], v[104:107]
	v_mfma_f32_16x16x32_bf16 v[104:107], v[36:39], v[128:131], v[108:111]
	v_mfma_f32_16x16x32_bf16 v[108:111], v[36:39], v[144:147], v[112:115]
	v_mfma_f32_16x16x32_bf16 v[36:39], v[36:39], v[148:151], v[52:55]
	v_mfma_f32_16x16x32_bf16 v[52:55], v[40:43], v[88:91], v[116:119]
	v_mfma_f32_16x16x32_bf16 v[112:115], v[40:43], v[128:131], v[120:123]
	v_mfma_f32_16x16x32_bf16 v[116:119], v[40:43], v[144:147], v[124:127]
	v_mfma_f32_16x16x32_bf16 v[40:43], v[40:43], v[148:151], v[56:59]
	v_mfma_f32_16x16x32_bf16 v[56:59], v[84:87], v[88:91], v[60:63]
	v_mfma_f32_16x16x32_bf16 v[60:63], v[84:87], v[128:131], v[76:79]
	v_mfma_f32_16x16x32_bf16 v[76:79], v[84:87], v[144:147], v[80:83]
	v_mfma_f32_16x16x32_bf16 v[72:75], v[84:87], v[148:151], v[72:75]
	ds_read_b128 v[0:3], v68 offset:16384
	ds_read_b128 v[8:11], v68 offset:17408
	ds_read_b128 v[12:15], v68 offset:18432
	ds_read_b128 v[16:19], v68 offset:19456
	ds_read_b128 v[80:83], v69
	ds_read_b128 v[84:87], v69 offset:1024
	ds_read_b128 v[88:91], v69 offset:2048
	ds_read_b128 v[120:123], v69 offset:3072
	ds_write_b128 v47, v[24:27] offset:8192
	ds_write_b128 v47, v[4:7] offset:12288
	s_waitcnt vmcnt(1)
	ds_write_b128 v47, v[20:23] offset:24576
	s_waitcnt vmcnt(0)
	ds_write_b128 v47, v[28:31] offset:28672
	s_waitcnt lgkmcnt(7)
	v_mfma_f32_16x16x32_bf16 v[92:95], v[0:3], v[80:83], v[92:95]
	s_waitcnt lgkmcnt(0)
	s_barrier
	v_mfma_f32_16x16x32_bf16 v[96:99], v[0:3], v[84:87], v[96:99]
	v_mfma_f32_16x16x32_bf16 v[100:103], v[0:3], v[88:91], v[100:103]
	v_mfma_f32_16x16x32_bf16 v[0:3], v[0:3], v[120:123], v[32:35]
	v_mfma_f32_16x16x32_bf16 v[32:35], v[8:11], v[80:83], v[48:51]
	v_mfma_f32_16x16x32_bf16 v[48:51], v[8:11], v[84:87], v[104:107]
	v_mfma_f32_16x16x32_bf16 v[104:107], v[8:11], v[88:91], v[108:111]
	v_mfma_f32_16x16x32_bf16 v[8:11], v[8:11], v[120:123], v[36:39]
	v_mfma_f32_16x16x32_bf16 v[36:39], v[12:15], v[80:83], v[52:55]
	v_mfma_f32_16x16x32_bf16 v[108:111], v[12:15], v[84:87], v[112:115]
	v_mfma_f32_16x16x32_bf16 v[112:115], v[12:15], v[88:91], v[116:119]
	v_mfma_f32_16x16x32_bf16 v[116:119], v[12:15], v[120:123], v[40:43]
	v_mfma_f32_16x16x32_bf16 v[80:83], v[16:19], v[80:83], v[56:59]
	v_mfma_f32_16x16x32_bf16 v[84:87], v[16:19], v[84:87], v[60:63]
	v_mfma_f32_16x16x32_bf16 v[76:79], v[16:19], v[88:91], v[76:79]
	v_mfma_f32_16x16x32_bf16 v[72:75], v[16:19], v[120:123], v[72:75]
	ds_read_b128 v[4:7], v68 offset:24576
	ds_read_b128 v[16:19], v68 offset:25600
	ds_read_b128 v[88:91], v68 offset:26624
	ds_read_b128 v[120:123], v68 offset:27648
	ds_read_b128 v[124:127], v69 offset:8192
	ds_read_b128 v[128:131], v69 offset:9216
	ds_read_b128 v[144:147], v69 offset:10240
	ds_read_b128 v[148:151], v69 offset:11264
	v_lshl_or_b32 v68, v64, 6, s8
	v_ashrrev_i32_e32 v64, 6, v68
	s_waitcnt lgkmcnt(3)
	v_mfma_f32_16x16x32_bf16 v[56:59], v[16:19], v[124:127], v[32:35]
	v_and_or_b32 v66, v66, 12, v68
	s_waitcnt lgkmcnt(0)
	s_barrier
	v_mfma_f32_16x16x32_bf16 v[40:43], v[16:19], v[128:131], v[48:51]
	v_ashrrev_i32_e32 v67, 31, v66
	v_mfma_f32_16x16x32_bf16 v[24:27], v[16:19], v[144:147], v[104:107]
	v_mfma_f32_16x16x32_bf16 v[8:11], v[16:19], v[148:151], v[8:11]
	v_mfma_f32_16x16x32_bf16 v[16:19], v[120:123], v[144:147], v[76:79]
	s_nop 2
	v_add_u32_e32 v76, s4, v65
	v_ashrrev_i32_e32 v77, 31, v76
	v_ashrrev_i32_e32 v65, 31, v64
	v_lshlrev_b64 v[68:69], 5, v[76:77]
	v_mfma_f32_16x16x32_bf16 v[12:15], v[4:7], v[148:151], v[0:3]
	v_lshl_add_u64 v[68:69], s[26:27], 0, v[68:69]
	s_add_i32 s4, s4, s58
	s_cmpk_gt_i32 s6, 0x1ff
	v_mfma_f32_16x16x32_bf16 v[0:3], v[120:123], v[148:151], v[72:75]
	s_nop 2
	v_lshlrev_b64 v[74:75], 2, v[64:65]
	v_lshl_add_u64 v[64:65], v[68:69], 0, v[74:75]
	global_load_dword v78, v[64:65], off
	v_lshlrev_b64 v[64:65], 11, v[76:77]
	v_lshl_add_u64 v[64:65], s[30:31], 0, v[64:65]
	v_lshlrev_b64 v[72:73], 1, v[66:67]
	v_mfma_f32_16x16x32_bf16 v[48:51], v[120:123], v[124:127], v[80:83]
	v_mad_i64_i32 v[68:69], s[8:9], v76, s16, v[70:71]
	s_nop 1
	v_lshl_add_u64 v[80:81], v[64:65], 0, v[72:73]
	global_load_dwordx2 v[152:153], v[80:81], off
	global_load_dwordx2 v[154:155], v[80:81], off offset:32
	global_load_dwordx2 v[156:157], v[80:81], off offset:64
	global_load_dwordx2 v[158:159], v[80:81], off offset:96
	s_nop 0
	v_mfma_f32_16x16x32_bf16 v[60:63], v[4:7], v[124:127], v[92:95]
	v_mfma_f32_16x16x32_bf16 v[44:47], v[4:7], v[128:131], v[96:99]
	s_nop 0
	s_nop 0
	s_waitcnt vmcnt(3)
	v_lshlrev_b32_e32 v92, 16, v152
	v_and_b32_e32 v93, 0xffff0000, v152
	v_lshlrev_b32_e32 v94, 16, v153
	v_and_b32_e32 v95, 0xffff0000, v153
	s_nop 0
	v_mfma_f32_16x16x32_bf16 v[28:31], v[4:7], v[144:147], v[100:103]
	s_nop 0
	s_waitcnt vmcnt(2)
; __device__ __forceinline__ void unpack4(uint2 u, float* f) { f[0] = bflo(u.x); f[1] = bfhi(u.x); f[2] = bflo(u.y); f[3] = bfhi(u.y); }
; __device__ __forceinline__ float xadd16(float x) { unsigned a = __float_as_uint(x); auto r = __builtin_amdgcn_permlane16_swap(a, a, false, false); return __uint_as_float(r[0]) + __uint_as_float(r[1]); }
; __device__ __forceinline__ float xadd32(float x) { unsigned a = __float_as_uint(x); auto r = __builtin_amdgcn_permlane32_swap(a, a, false, false); return __uint_as_float(r[0]) + __uint_as_float(r[1]); }
;   __device__ __forceinline__ void operator()(f32x4 (&acc)[4][4], int mw, int nw, int lane, int) const {
;     ...
; #pragma unroll
;     for (int j = 0; j < 4; j++) {
;       const int m = mw + j * 16 + (lane & 15);
;       float y[16], sum = 0.f;
;       const float c3 = c3buf[(size_t)m * 8 + hh];
; #pragma unroll
;       for (int i = 0; i < 4; i++) {
;         const int ch = nw + i * 16 + (lane >> 4) * 4;
;         unpack4(*(const uint2*)(A + (size_t)m * 1024 + ch), y + i * 4);
;         sum += y[i * 4] + y[i * 4 + 1] + y[i * 4 + 2] + y[i * 4 + 3];
;       }
;       sum = xadd32(xadd16(sum));
;       const float mean = sum * (1.f / 64.f);
;       float var = 0.f;
; #pragma unroll
;       for (int i = 0; i < 16; i++) var += (y[i] - mean) * (y[i] - mean);
;       var = xadd32(xadd16(var));
;       const float rstd = rsqrtf(var * (1.f / 64.f) + 64e-5f);
; #pragma unroll
;       for (int i = 0; i < 4; i++) {
;         const int ch = nw + i * 16 + (lane >> 4) * 4;
;         float vs[4];
;         rw_shift4(pj, mu, m, 1088 + ch, vs);
;         float4 lg = *(const float4*)(ln_g + ch), lb = *(const float4*)(ln_b + ch);
;         float o0 = ((y[i * 4 + 0] - mean) * rstd * lg.x + lb.x + c3 * vs[0]) * acc[i][j][0];
	v_lshlrev_b32_e32 v96, 16, v154
	v_and_b32_e32 v97, 0xffff0000, v154
	v_lshlrev_b32_e32 v98, 16, v155
	v_and_b32_e32 v99, 0xffff0000, v155
	s_nop 0
	v_mfma_f32_16x16x32_bf16 v[52:55], v[88:91], v[124:127], v[36:39]
	s_nop 0
	s_waitcnt vmcnt(1)
	v_lshlrev_b32_e32 v100, 16, v156
	v_and_b32_e32 v101, 0xffff0000, v156
	v_lshlrev_b32_e32 v102, 16, v157
	v_add_f32_e32 v64, v101, v100
	v_and_b32_e32 v103, 0xffff0000, v157
	v_add_f32_e32 v64, v64, v102
	v_add_f32_e32 v77, v64, v103
	s_nop 0
	v_mfma_f32_16x16x32_bf16 v[36:39], v[88:91], v[128:131], v[108:111]
	s_nop 0
	s_waitcnt vmcnt(0)
	v_lshlrev_b32_e32 v104, 16, v158
	v_and_b32_e32 v105, 0xffff0000, v158
	v_lshlrev_b32_e32 v106, 16, v159
	v_add_f32_e32 v64, v105, v104
	v_and_b32_e32 v107, 0xffff0000, v159
	v_add_f32_e32 v64, v64, v106
	v_add_f32_e32 v79, v64, v107
	v_and_b32_e32 v64, 0xfcf, v76
	v_cmp_eq_u32_e32 vcc, 0, v64
	v_lshl_add_u64 v[110:111], v[68:69], 0, v[72:73]
	global_load_dwordx2 v[152:153], v[110:111], off offset:2176
	global_load_dwordx2 v[164:165], v[110:111], off offset:2208
	global_load_dwordx2 v[180:181], v[110:111], off offset:2240
	global_load_dwordx2 v[196:197], v[110:111], off offset:2272
	v_mfma_f32_16x16x32_bf16 v[20:23], v[88:91], v[144:147], v[112:115]
	v_cndmask_b32_e64 v65, -1, 0, vcc
	v_cndmask_b32_e64 v64, v205, 0, vcc
	s_nop 0
	v_lshl_add_u64 v[114:115], v[110:111], 0, v[64:65]
	global_load_dwordx2 v[154:155], v[114:115], off offset:2176
	global_load_dwordx2 v[166:167], v[114:115], off offset:2208
	global_load_dwordx2 v[182:183], v[114:115], off offset:2240
	global_load_dwordx2 v[220:221], v[114:115], off offset:2272
	s_nop 0
	v_mfma_f32_16x16x32_bf16 v[32:35], v[120:123], v[128:131], v[84:87]
	v_cndmask_b32_e64 v108, 1.0, 0, vcc
	s_nop 0
	s_waitcnt vmcnt(7)
	v_lshlrev_b32_e32 v112, 16, v152
	v_and_b32_e32 v113, 0xffff0000, v152
	v_lshlrev_b32_e32 v86, 16, v153
	v_and_b32_e32 v87, 0xffff0000, v153
	v_lshlrev_b64 v[68:69], 2, v[66:67]
	v_mfma_f32_16x16x32_bf16 v[4:7], v[88:91], v[148:151], v[116:119]
	s_nop 0
	s_waitcnt vmcnt(3)
	v_lshlrev_b32_e32 v88, 16, v155
	v_and_b32_e32 v89, 0xffff0000, v155
	v_lshl_add_u64 v[66:67], s[94:95], 0, v[68:69]
	global_load_dwordx4 v[156:159], v[66:67], off
	global_load_dwordx4 v[172:175], v[66:67], off offset:64
	global_load_dwordx4 v[188:191], v[66:67], off offset:128
	global_load_dwordx4 v[232:235], v[66:67], off offset:192
	global_load_dwordx4 v[244:247], v[66:67], off
	v_lshlrev_b32_e32 v116, 16, v154
	v_and_b32_e32 v117, 0xffff0000, v154
	v_lshl_add_u64 v[64:65], s[72:73], 0, v[68:69]
	global_load_dwordx4 v[160:163], v[64:65], off
	global_load_dwordx4 v[176:179], v[64:65], off offset:64
	global_load_dwordx4 v[192:195], v[64:65], off offset:128
	global_load_dwordx4 v[236:239], v[64:65], off offset:192
	global_load_dwordx4 v[248:251], v[64:65], off
	v_lshl_add_u64 v[68:69], s[12:13], 0, v[68:69]
	v_add_co_u32_e32 v68, vcc, s35, v68
	v_pk_fma_f32 v[88:89], v[108:109], v[88:89], v[86:87] op_sel_hi:[0,1,1] neg_lo:[0,0,1] neg_hi:[0,0,1]
	s_nop 0
	v_addc_co_u32_e32 v69, vcc, 0, v69, vcc
	global_load_dwordx4 v[152:155], v[68:69], off offset:256
	global_load_dwordx4 v[168:171], v[68:69], off offset:320
	global_load_dwordx4 v[184:187], v[68:69], off offset:384
	global_load_dwordx4 v[222:225], v[68:69], off offset:448
	global_load_dwordx4 v[240:243], v[68:69], off offset:256
	global_load_dwordx4 v[252:255], v[68:69], off offset:320
	s_nop 0
	v_pk_fma_f32 v[116:117], v[108:109], v[116:117], v[112:113] op_sel_hi:[0,1,1] neg_lo:[0,0,1] neg_hi:[0,0,1]
	v_add_f32_e32 v109, v93, v92
	v_add_f32_e32 v109, v109, v94
	v_add_f32_e32 v109, v109, v95
	v_add_f32_e32 v109, 0, v109
	s_nop 0
	s_waitcnt vmcnt(5)
	v_pk_fma_f32 v[118:119], v[154:155], v[88:89], v[86:87]
	s_nop 0
	s_nop 0
	v_pk_fma_f32 v[152:153], v[152:153], v[116:117], v[112:113]
	v_add_f32_e32 v112, v97, v96
	v_add_f32_e32 v112, v112, v98
	v_add_f32_e32 v112, v112, v99
	v_add_f32_e32 v109, v109, v112
	v_add_f32_e32 v77, v109, v77
	v_add_f32_e32 v77, v77, v79
	v_mov_b32_e32 v79, v77
	s_nop 1
	v_permlane16_swap_b32_e32 v77, v79
	v_add_f32_e32 v77, v77, v79
	v_mov_b32_e32 v79, v77
	s_nop 1
	v_permlane32_swap_b32_e32 v77, v79
	v_add_f32_e32 v77, v77, v79
	v_mul_f32_e32 v112, 0x3c800000, v77
	v_pk_add_f32 v[92:93], v[92:93], v[112:113] op_sel_hi:[1,0] neg_lo:[0,1] neg_hi:[0,1]
	v_pk_add_f32 v[94:95], v[94:95], v[112:113] op_sel_hi:[1,0] neg_lo:[0,1] neg_hi:[0,1]
	v_mul_f32_e32 v116, v93, v93
	v_pk_fma_f32 v[116:117], v[92:93], v[92:93], v[116:117] op_sel_hi:[1,1,0]
	v_mul_f32_e32 v120, v95, v95
	v_pk_fma_f32 v[116:117], v[94:95], v[94:95], v[116:117]
	v_pk_add_f32 v[96:97], v[96:97], v[112:113] op_sel_hi:[1,0] neg_lo:[0,1] neg_hi:[0,1]
	v_pk_add_f32 v[116:117], v[120:121], v[116:117] op_sel_hi:[0,1]
	v_pk_fma_f32 v[116:117], v[96:97], v[96:97], v[116:117]
	v_mul_f32_e32 v120, v97, v97
	v_pk_add_f32 v[116:117], v[120:121], v[116:117] op_sel_hi:[0,1]
	v_pk_add_f32 v[98:99], v[98:99], v[112:113] op_sel_hi:[1,0] neg_lo:[0,1] neg_hi:[0,1]
	v_pk_add_f32 v[100:101], v[100:101], v[112:113] op_sel_hi:[1,0] neg_lo:[0,1] neg_hi:[0,1]
	v_pk_fma_f32 v[116:117], v[98:99], v[98:99], v[116:117]
	v_mul_f32_e32 v120, v99, v99
	v_pk_add_f32 v[116:117], v[120:121], v[116:117] op_sel_hi:[0,1]
	v_pk_fma_f32 v[116:117], v[100:101], v[100:101], v[116:117]
	v_mul_f32_e32 v120, v101, v101
	v_pk_add_f32 v[116:117], v[120:121], v[116:117] op_sel_hi:[0,1]
	v_pk_add_f32 v[102:103], v[102:103], v[112:113] op_sel_hi:[1,0] neg_lo:[0,1] neg_hi:[0,1]
	v_pk_add_f32 v[104:105], v[104:105], v[112:113] op_sel_hi:[1,0] neg_lo:[0,1] neg_hi:[0,1]
	v_pk_fma_f32 v[116:117], v[102:103], v[102:103], v[116:117]
	v_mul_f32_e32 v120, v103, v103
; __device__ __forceinline__ uint2 pack4(float a, float b, float c, float d) { return make_uint2(pack2(a, b), pack2(c, d)); }
;   __device__ __forceinline__ void operator()(f32x4 (&acc)[4][4], int mw, int nw, int lane, int) const {
;     ...
; #pragma unroll
;       for (int i = 0; i < 4; i++) {
;         const int ch = nw + i * 16 + (lane >> 4) * 4;
;         float vs[4];
;         rw_shift4(pj, mu, m, 1088 + ch, vs);
;         float4 lg = *(const float4*)(ln_g + ch), lb = *(const float4*)(ln_b + ch);
;         float o0 = ((y[i * 4 + 0] - mean) * rstd * lg.x + lb.x + c3 * vs[0]) * acc[i][j][0];
;         float o1 = ((y[i * 4 + 1] - mean) * rstd * lg.y + lb.y + c3 * vs[1]) * acc[i][j][1];
;         float o2 = ((y[i * 4 + 2] - mean) * rstd * lg.z + lb.z + c3 * vs[2]) * acc[i][j][2];
;         float o3 = ((y[i * 4 + 3] - mean) * rstd * lg.w + lb.w + c3 * vs[3]) * acc[i][j][3];
;         *(uint2*)(A + (size_t)m * 1024 + ch) = pack4(o0, o1, o2, o3);
;       }
	v_pk_add_f32 v[116:117], v[120:121], v[116:117] op_sel_hi:[0,1]
	v_pk_fma_f32 v[116:117], v[104:105], v[104:105], v[116:117]
	v_mul_f32_e32 v120, v105, v105
	v_pk_add_f32 v[116:117], v[120:121], v[116:117] op_sel_hi:[0,1]
	v_pk_add_f32 v[106:107], v[106:107], v[112:113] op_sel_hi:[1,0] neg_lo:[0,1] neg_hi:[0,1]
	s_nop 0
	v_pk_fma_f32 v[112:113], v[106:107], v[106:107], v[116:117]
	v_mul_f32_e32 v116, v107, v107
	v_pk_add_f32 v[112:113], v[116:117], v[112:113] op_sel_hi:[0,1]
	v_mov_b32_e32 v77, v112
	s_nop 1
	v_permlane16_swap_b32_e32 v112, v77
	v_add_f32_e32 v77, v112, v77
	v_mov_b32_e32 v79, v77
	s_nop 1
	v_permlane32_swap_b32_e32 v77, v79
	v_add_f32_e32 v77, v77, v79
	v_fmamk_f32 v77, v77, 0x3c800000, v201
	v_cmp_gt_f32_e32 vcc, s85, v77
	v_mul_f32_e32 v79, 0x4b800000, v77
	s_nop 0
	v_cndmask_b32_e32 v77, v77, v79, vcc
	v_rsq_f32_e32 v77, v77
	s_nop 0
	v_mul_f32_e32 v79, 0x45800000, v77
	v_cndmask_b32_e32 v112, v77, v79, vcc
	v_pk_mul_f32 v[92:93], v[92:93], v[112:113] op_sel_hi:[1,0]
	s_nop 0
	v_pk_fma_f32 v[156:157], v[156:157], v[92:93], v[160:161]
	s_nop 0
	v_pk_fma_f32 v[152:153], v[78:79], v[152:153], v[156:157] op_sel_hi:[0,1,1]
	v_pk_mul_f32 v[60:61], v[60:61], v[152:153]
	v_pk_mul_f32 v[82:83], v[94:95], v[112:113] op_sel_hi:[1,0]
	v_cvt_pk_bf16_f32 v60, v60, v61
	v_pk_fma_f32 v[82:83], v[82:83], v[158:159], v[162:163]
	v_pk_mul_f32 v[90:91], v[96:97], v[112:113] op_sel_hi:[1,0]
	v_pk_fma_f32 v[82:83], v[78:79], v[118:119], v[82:83] op_sel_hi:[0,1,1]
	v_pk_mul_f32 v[62:63], v[62:63], v[82:83]
	s_nop 0
	v_cvt_pk_bf16_f32 v61, v62, v63
	global_store_dwordx2 v[80:81], v[60:61], off
	s_nop 0
	s_nop 0
	v_lshlrev_b32_e32 v82, 16, v164
	v_and_b32_e32 v83, 0xffff0000, v164
	v_lshlrev_b32_e32 v84, 16, v165
	v_and_b32_e32 v85, 0xffff0000, v165
	s_nop 0
	s_nop 0
	v_lshlrev_b32_e32 v86, 16, v166
	v_and_b32_e32 v87, 0xffff0000, v166
	v_lshlrev_b32_e32 v88, 16, v167
	v_and_b32_e32 v89, 0xffff0000, v167
	s_nop 0
	v_pk_fma_f32 v[86:87], v[108:109], v[86:87], v[82:83] op_sel_hi:[0,1,1] neg_lo:[0,0,1] neg_hi:[0,0,1]
	s_nop 0
	s_waitcnt vmcnt(5)
	v_pk_fma_f32 v[86:87], v[168:169], v[86:87], v[82:83]
	v_pk_fma_f32 v[60:61], v[108:109], v[88:89], v[84:85] op_sel_hi:[0,1,1] neg_lo:[0,0,1] neg_hi:[0,0,1]
	v_pk_fma_f32 v[88:89], v[170:171], v[60:61], v[84:85]
	s_nop 0
	s_nop 0
	s_nop 0
	v_pk_fma_f32 v[172:173], v[90:91], v[172:173], v[176:177]
	s_nop 0
	v_pk_fma_f32 v[172:173], v[78:79], v[86:87], v[172:173] op_sel_hi:[0,1,1]
	v_pk_mul_f32 v[56:57], v[56:57], v[172:173]
	v_pk_mul_f32 v[60:61], v[98:99], v[112:113] op_sel_hi:[1,0]
	v_cvt_pk_bf16_f32 v56, v56, v57
	v_pk_fma_f32 v[60:61], v[60:61], v[174:175], v[178:179]
	v_pk_mul_f32 v[86:87], v[100:101], v[112:113] op_sel_hi:[1,0]
	v_pk_fma_f32 v[60:61], v[78:79], v[88:89], v[60:61] op_sel_hi:[0,1,1]
	v_pk_mul_f32 v[58:59], v[58:59], v[60:61]
	s_nop 0
	v_cvt_pk_bf16_f32 v57, v58, v59
	global_store_dwordx2 v[80:81], v[56:57], off offset:32
	s_nop 0
	s_nop 0
	v_lshlrev_b32_e32 v60, 16, v180
	v_and_b32_e32 v61, 0xffff0000, v180
	v_lshlrev_b32_e32 v62, 16, v181
	v_and_b32_e32 v63, 0xffff0000, v181
	s_nop 0
	s_nop 0
	v_lshlrev_b32_e32 v82, 16, v182
	v_and_b32_e32 v83, 0xffff0000, v182
	v_lshlrev_b32_e32 v84, 16, v183
	v_and_b32_e32 v85, 0xffff0000, v183
	s_nop 0
	v_pk_fma_f32 v[82:83], v[108:109], v[82:83], v[60:61] op_sel_hi:[0,1,1] neg_lo:[0,0,1] neg_hi:[0,0,1]
	s_nop 0
	s_waitcnt vmcnt(5)
	v_pk_fma_f32 v[82:83], v[184:185], v[82:83], v[60:61]
	v_pk_fma_f32 v[56:57], v[108:109], v[84:85], v[62:63] op_sel_hi:[0,1,1] neg_lo:[0,0,1] neg_hi:[0,0,1]
	v_pk_fma_f32 v[84:85], v[186:187], v[56:57], v[62:63]
	s_nop 0
	s_nop 0
	s_nop 0
	v_pk_fma_f32 v[188:189], v[86:87], v[188:189], v[192:193]
	s_nop 0
	v_pk_fma_f32 v[188:189], v[78:79], v[82:83], v[188:189] op_sel_hi:[0,1,1]
	v_pk_mul_f32 v[52:53], v[52:53], v[188:189]
	v_pk_mul_f32 v[56:57], v[102:103], v[112:113] op_sel_hi:[1,0]
	v_cvt_pk_bf16_f32 v52, v52, v53
	v_pk_fma_f32 v[56:57], v[56:57], v[190:191], v[194:195]
	v_pk_mul_f32 v[82:83], v[104:105], v[112:113] op_sel_hi:[1,0]
	v_pk_fma_f32 v[56:57], v[78:79], v[84:85], v[56:57] op_sel_hi:[0,1,1]
	v_pk_mul_f32 v[54:55], v[54:55], v[56:57]
	s_nop 0
	v_cvt_pk_bf16_f32 v53, v54, v55
	global_store_dwordx2 v[80:81], v[52:53], off offset:64
	s_nop 0
	s_nop 0
	v_lshlrev_b32_e32 v56, 16, v196
	v_and_b32_e32 v57, 0xffff0000, v196
	v_lshlrev_b32_e32 v58, 16, v197
	v_and_b32_e32 v59, 0xffff0000, v197
	s_nop 0
	s_nop 0
	v_lshlrev_b32_e32 v60, 16, v220
	v_and_b32_e32 v61, 0xffff0000, v220
	v_lshlrev_b32_e32 v62, 16, v221
	v_and_b32_e32 v63, 0xffff0000, v221
	s_nop 0
	v_pk_fma_f32 v[60:61], v[108:109], v[60:61], v[56:57] op_sel_hi:[0,1,1] neg_lo:[0,0,1] neg_hi:[0,0,1]
	s_nop 0
	s_waitcnt vmcnt(5)
	v_pk_fma_f32 v[60:61], v[222:223], v[60:61], v[56:57]
	v_pk_fma_f32 v[52:53], v[108:109], v[62:63], v[58:59] op_sel_hi:[0,1,1] neg_lo:[0,0,1] neg_hi:[0,0,1]
	v_pk_fma_f32 v[62:63], v[224:225], v[52:53], v[58:59]
	s_nop 0
	s_nop 0
	s_nop 0
	v_pk_fma_f32 v[232:233], v[82:83], v[232:233], v[236:237]
	s_nop 0
	v_pk_fma_f32 v[232:233], v[78:79], v[60:61], v[232:233] op_sel_hi:[0,1,1]
	v_pk_mul_f32 v[48:49], v[48:49], v[232:233]
	v_pk_mul_f32 v[52:53], v[106:107], v[112:113] op_sel_hi:[1,0]
	v_cvt_pk_bf16_f32 v48, v48, v49
	v_pk_fma_f32 v[52:53], v[52:53], v[234:235], v[238:239]
	s_nop 0
	v_pk_fma_f32 v[52:53], v[78:79], v[62:63], v[52:53] op_sel_hi:[0,1,1]
	v_pk_mul_f32 v[50:51], v[50:51], v[52:53]
	s_nop 0
	v_cvt_pk_bf16_f32 v49, v50, v51
	global_store_dwordx2 v[80:81], v[48:49], off offset:96
	v_add_u32_e32 v48, 16, v76
	v_ashrrev_i32_e32 v49, 31, v48
	v_lshlrev_b64 v[50:51], 5, v[48:49]
	v_lshl_add_u64 v[50:51], s[26:27], 0, v[50:51]
	v_lshl_add_u64 v[50:51], v[50:51], 0, v[74:75]
	global_load_dword v56, v[50:51], off
	v_lshlrev_b64 v[50:51], 11, v[48:49]
	v_lshl_add_u64 v[50:51], s[30:31], 0, v[50:51]
	v_lshl_add_u64 v[58:59], v[50:51], 0, v[72:73]
	global_load_dwordx2 v[50:51], v[58:59], off
	global_load_dwordx2 v[54:55], v[58:59], off offset:32
	global_load_dwordx2 v[62:63], v[58:59], off offset:64
	global_load_dwordx2 v[80:81], v[58:59], off offset:96
	s_nop 0
	s_waitcnt vmcnt(3)
; __device__ __forceinline__ void unpack4(uint2 u, float* f) { f[0] = bflo(u.x); f[1] = bfhi(u.x); f[2] = bflo(u.y); f[3] = bfhi(u.y); }
; __device__ __forceinline__ uint2 pack4(float a, float b, float c, float d) { return make_uint2(pack2(a, b), pack2(c, d)); }
; __device__ __forceinline__ float xadd16(float x) { unsigned a = __float_as_uint(x); auto r = __builtin_amdgcn_permlane16_swap(a, a, false, false); return __uint_as_float(r[0]) + __uint_as_float(r[1]); }
; __device__ __forceinline__ float xadd32(float x) { unsigned a = __float_as_uint(x); auto r = __builtin_amdgcn_permlane32_swap(a, a, false, false); return __uint_as_float(r[0]) + __uint_as_float(r[1]); }
;   __device__ __forceinline__ void operator()(f32x4 (&acc)[4][4], int mw, int nw, int lane, int) const {
;     ...
;       const int m = mw + j * 16 + (lane & 15);
;       float y[16], sum = 0.f;
;       const float c3 = c3buf[(size_t)m * 8 + hh];
; #pragma unroll
;       for (int i = 0; i < 4; i++) {
;         const int ch = nw + i * 16 + (lane >> 4) * 4;
;         unpack4(*(const uint2*)(A + (size_t)m * 1024 + ch), y + i * 4);
;         sum += y[i * 4] + y[i * 4 + 1] + y[i * 4 + 2] + y[i * 4 + 3];
;       }
;       sum = xadd32(xadd16(sum));
;       const float mean = sum * (1.f / 64.f);
;       float var = 0.f;
; #pragma unroll
;       for (int i = 0; i < 16; i++) var += (y[i] - mean) * (y[i] - mean);
;       var = xadd32(xadd16(var));
;       const float rstd = rsqrtf(var * (1.f / 64.f) + 64e-5f);
; #pragma unroll
;       for (int i = 0; i < 4; i++) {
;         const int ch = nw + i * 16 + (lane >> 4) * 4;
;         float vs[4];
;         rw_shift4(pj, mu, m, 1088 + ch, vs);
;         float4 lg = *(const float4*)(ln_g + ch), lb = *(const float4*)(ln_b + ch);
;         float o0 = ((y[i * 4 + 0] - mean) * rstd * lg.x + lb.x + c3 * vs[0]) * acc[i][j][0];
;         float o1 = ((y[i * 4 + 1] - mean) * rstd * lg.y + lb.y + c3 * vs[1]) * acc[i][j][1];
;         float o2 = ((y[i * 4 + 2] - mean) * rstd * lg.z + lb.z + c3 * vs[2]) * acc[i][j][2];
;         float o3 = ((y[i * 4 + 3] - mean) * rstd * lg.w + lb.w + c3 * vs[3]) * acc[i][j][3];
;         *(uint2*)(A + (size_t)m * 1024 + ch) = pack4(o0, o1, o2, o3);
	v_lshlrev_b32_e32 v52, 16, v50
	v_and_b32_e32 v53, 0xffff0000, v50
	v_lshlrev_b32_e32 v50, 16, v51
	v_add_f32_e32 v49, v53, v52
	s_nop 0
	s_waitcnt vmcnt(2)
	v_lshlrev_b32_e32 v60, 16, v54
	v_and_b32_e32 v61, 0xffff0000, v54
	v_and_b32_e32 v51, 0xffff0000, v51
	v_add_f32_e32 v49, v49, v50
	v_lshlrev_b32_e32 v54, 16, v55
	v_add_f32_e32 v57, v61, v60
	v_add_f32_e32 v49, v49, v51
	v_and_b32_e32 v55, 0xffff0000, v55
	v_add_f32_e32 v57, v57, v54
	v_add_f32_e32 v49, 0, v49
	v_add_f32_e32 v57, v57, v55
	s_nop 0
	s_waitcnt vmcnt(1)
	v_lshlrev_b32_e32 v78, 16, v62
	v_and_b32_e32 v79, 0xffff0000, v62
	v_add_f32_e32 v49, v49, v57
	v_lshlrev_b32_e32 v62, 16, v63
	v_add_f32_e32 v57, v79, v78
	v_and_b32_e32 v63, 0xffff0000, v63
	v_add_f32_e32 v57, v57, v62
	v_add_f32_e32 v57, v57, v63
	s_nop 0
	s_waitcnt vmcnt(0)
	v_lshlrev_b32_e32 v82, 16, v80
	v_and_b32_e32 v83, 0xffff0000, v80
	v_add_f32_e32 v49, v49, v57
	v_lshlrev_b32_e32 v80, 16, v81
	v_add_f32_e32 v57, v83, v82
	v_and_b32_e32 v81, 0xffff0000, v81
	v_add_f32_e32 v57, v57, v80
	v_add_f32_e32 v57, v57, v81
	v_add_f32_e32 v49, v49, v57
	v_mov_b32_e32 v57, v49
	s_nop 1
	v_permlane16_swap_b32_e32 v49, v57
	v_add_f32_e32 v49, v49, v57
	v_mov_b32_e32 v57, v49
	s_nop 1
	v_permlane32_swap_b32_e32 v49, v57
	v_add_f32_e32 v49, v49, v57
	v_mul_f32_e32 v84, 0x3c800000, v49
	v_pk_add_f32 v[86:87], v[52:53], v[84:85] op_sel_hi:[1,0] neg_lo:[0,1] neg_hi:[0,1]
	v_pk_add_f32 v[88:89], v[50:51], v[84:85] op_sel_hi:[1,0] neg_lo:[0,1] neg_hi:[0,1]
	v_mul_f32_e32 v52, v87, v87
	v_pk_fma_f32 v[52:53], v[86:87], v[86:87], v[52:53] op_sel_hi:[1,1,0]
	v_pk_add_f32 v[60:61], v[60:61], v[84:85] op_sel_hi:[1,0] neg_lo:[0,1] neg_hi:[0,1]
	v_pk_fma_f32 v[50:51], v[88:89], v[88:89], v[52:53]
	v_mul_f32_e32 v52, v89, v89
	v_pk_add_f32 v[50:51], v[52:53], v[50:51] op_sel_hi:[0,1]
	v_pk_fma_f32 v[50:51], v[60:61], v[60:61], v[50:51]
	v_mul_f32_e32 v52, v61, v61
	v_pk_add_f32 v[50:51], v[52:53], v[50:51] op_sel_hi:[0,1]
	v_pk_add_f32 v[90:91], v[54:55], v[84:85] op_sel_hi:[1,0] neg_lo:[0,1] neg_hi:[0,1]
	v_pk_add_f32 v[78:79], v[78:79], v[84:85] op_sel_hi:[1,0] neg_lo:[0,1] neg_hi:[0,1]
	v_pk_fma_f32 v[50:51], v[90:91], v[90:91], v[50:51]
	v_mul_f32_e32 v52, v91, v91
	v_pk_add_f32 v[50:51], v[52:53], v[50:51] op_sel_hi:[0,1]
	v_pk_fma_f32 v[50:51], v[78:79], v[78:79], v[50:51]
	v_mul_f32_e32 v52, v79, v79
	v_pk_add_f32 v[50:51], v[52:53], v[50:51] op_sel_hi:[0,1]
	v_pk_add_f32 v[62:63], v[62:63], v[84:85] op_sel_hi:[1,0] neg_lo:[0,1] neg_hi:[0,1]
	v_pk_add_f32 v[82:83], v[82:83], v[84:85] op_sel_hi:[1,0] neg_lo:[0,1] neg_hi:[0,1]
	v_pk_fma_f32 v[50:51], v[62:63], v[62:63], v[50:51]
	v_mul_f32_e32 v52, v63, v63
	v_pk_add_f32 v[50:51], v[52:53], v[50:51] op_sel_hi:[0,1]
	v_pk_fma_f32 v[50:51], v[82:83], v[82:83], v[50:51]
	v_mul_f32_e32 v52, v83, v83
	v_pk_add_f32 v[50:51], v[52:53], v[50:51] op_sel_hi:[0,1]
	v_pk_add_f32 v[80:81], v[80:81], v[84:85] op_sel_hi:[1,0] neg_lo:[0,1] neg_hi:[0,1]
	s_nop 0
	v_pk_fma_f32 v[50:51], v[80:81], v[80:81], v[50:51]
	v_mul_f32_e32 v52, v81, v81
	v_pk_add_f32 v[50:51], v[52:53], v[50:51] op_sel_hi:[0,1]
	v_mov_b32_e32 v49, v50
	s_nop 1
	v_permlane16_swap_b32_e32 v50, v49
	v_add_f32_e32 v49, v50, v49
	v_mov_b32_e32 v50, v49
	s_nop 1
	v_permlane32_swap_b32_e32 v49, v50
	v_add_f32_e32 v49, v49, v50
	v_fmamk_f32 v49, v49, 0x3c800000, v201
	v_cmp_gt_f32_e32 vcc, s85, v49
	v_mul_f32_e32 v50, 0x4b800000, v49
	s_nop 0
	v_cndmask_b32_e32 v49, v49, v50, vcc
	v_rsq_f32_e32 v49, v49
	s_nop 0
	v_mul_f32_e32 v50, 0x45800000, v49
	v_cndmask_b32_e32 v84, v49, v50, vcc
	v_mad_i64_i32 v[48:49], s[8:9], v48, s16, v[70:71]
	v_lshl_add_u64 v[92:93], v[48:49], 0, v[72:73]
	global_load_dwordx2 v[152:153], v[92:93], off offset:2176
	global_load_dwordx2 v[154:155], v[92:93], off offset:-3456
	global_load_dwordx2 v[156:157], v[92:93], off offset:2208
	global_load_dwordx2 v[158:159], v[92:93], off offset:-3424
	global_load_dwordx2 v[160:161], v[92:93], off offset:2240
	global_load_dwordx2 v[162:163], v[92:93], off offset:-3392
	global_load_dwordx2 v[164:165], v[92:93], off offset:2272
	global_load_dwordx2 v[166:167], v[92:93], off offset:-3360
	s_nop 0
	s_nop 0
	v_pk_mul_f32 v[86:87], v[86:87], v[84:85] op_sel_hi:[1,0]
	v_pk_mul_f32 v[60:61], v[60:61], v[84:85] op_sel_hi:[1,0]
	s_nop 0
	s_waitcnt vmcnt(7)
	v_lshlrev_b32_e32 v52, 16, v152
	v_lshlrev_b32_e32 v54, 16, v153
	s_nop 0
	s_waitcnt vmcnt(6)
	v_lshlrev_b32_e32 v94, 16, v154
	v_and_b32_e32 v53, 0xffff0000, v152
	v_and_b32_e32 v95, 0xffff0000, v154
	v_lshlrev_b32_e32 v96, 16, v155
	v_and_b32_e32 v55, 0xffff0000, v153
	v_and_b32_e32 v97, 0xffff0000, v155
	s_nop 0
	v_pk_add_f32 v[94:95], v[94:95], v[52:53] neg_lo:[0,1] neg_hi:[0,1]
	s_nop 0
	v_pk_fma_f32 v[94:95], v[240:241], v[94:95], v[52:53]
	v_pk_add_f32 v[48:49], v[96:97], v[54:55] neg_lo:[0,1] neg_hi:[0,1]
	s_nop 0
	v_pk_fma_f32 v[96:97], v[242:243], v[48:49], v[54:55]
	s_nop 0
	s_nop 0
	s_nop 0
	v_pk_fma_f32 v[244:245], v[244:245], v[86:87], v[248:249]
	s_nop 0
	v_pk_fma_f32 v[244:245], v[56:57], v[94:95], v[244:245] op_sel_hi:[0,1,1]
	v_pk_mul_f32 v[44:45], v[44:45], v[244:245]
	v_pk_mul_f32 v[48:49], v[88:89], v[84:85] op_sel_hi:[1,0]
	v_cvt_pk_bf16_f32 v44, v44, v45
	v_pk_fma_f32 v[48:49], v[48:49], v[246:247], v[250:251]
	s_nop 0
	v_pk_fma_f32 v[48:49], v[56:57], v[96:97], v[48:49] op_sel_hi:[0,1,1]
	v_pk_mul_f32 v[46:47], v[46:47], v[48:49]
	s_nop 0
	v_cvt_pk_bf16_f32 v45, v46, v47
	global_store_dwordx2 v[58:59], v[44:45], off
	s_nop 0
	s_nop 0
	s_nop 0
	s_nop 0
	s_waitcnt vmcnt(6)
	v_lshlrev_b32_e32 v48, 16, v156
	v_lshlrev_b32_e32 v50, 16, v157
	s_nop 0
	s_waitcnt vmcnt(5)
; __device__ __forceinline__ uint2 pack4(float a, float b, float c, float d) { return make_uint2(pack2(a, b), pack2(c, d)); }
;   __device__ __forceinline__ void operator()(f32x4 (&acc)[4][4], int mw, int nw, int lane, int) const {
;     ...
; #pragma unroll
;       for (int i = 0; i < 4; i++) {
;         const int ch = nw + i * 16 + (lane >> 4) * 4;
;         float vs[4];
;         rw_shift4(pj, mu, m, 1088 + ch, vs);
;         float4 lg = *(const float4*)(ln_g + ch), lb = *(const float4*)(ln_b + ch);
;         float o0 = ((y[i * 4 + 0] - mean) * rstd * lg.x + lb.x + c3 * vs[0]) * acc[i][j][0];
;         float o1 = ((y[i * 4 + 1] - mean) * rstd * lg.y + lb.y + c3 * vs[1]) * acc[i][j][1];
;         float o2 = ((y[i * 4 + 2] - mean) * rstd * lg.z + lb.z + c3 * vs[2]) * acc[i][j][2];
;         float o3 = ((y[i * 4 + 3] - mean) * rstd * lg.w + lb.w + c3 * vs[3]) * acc[i][j][3];
;         *(uint2*)(A + (size_t)m * 1024 + ch) = pack4(o0, o1, o2, o3);
;       }
	v_lshlrev_b32_e32 v52, 16, v158
	v_and_b32_e32 v49, 0xffff0000, v156
	v_and_b32_e32 v53, 0xffff0000, v158
	v_lshlrev_b32_e32 v54, 16, v159
	v_and_b32_e32 v51, 0xffff0000, v157
	v_and_b32_e32 v55, 0xffff0000, v159
	s_nop 0
	v_pk_add_f32 v[52:53], v[52:53], v[48:49] neg_lo:[0,1] neg_hi:[0,1]
	s_nop 0
	v_pk_fma_f32 v[52:53], v[252:253], v[52:53], v[48:49]
	v_pk_add_f32 v[44:45], v[54:55], v[50:51] neg_lo:[0,1] neg_hi:[0,1]
	s_nop 0
	v_pk_fma_f32 v[54:55], v[254:255], v[44:45], v[50:51]
	global_load_dwordx4 v[44:47], v[66:67], off offset:64
	global_load_dwordx4 v[48:51], v[64:65], off offset:64
	s_nop 0
	s_waitcnt vmcnt(0)
	v_pk_fma_f32 v[44:45], v[60:61], v[44:45], v[48:49]
	s_nop 0
	v_pk_fma_f32 v[44:45], v[56:57], v[52:53], v[44:45] op_sel_hi:[0,1,1]
	v_pk_mul_f32 v[40:41], v[40:41], v[44:45]
	v_pk_mul_f32 v[44:45], v[90:91], v[84:85] op_sel_hi:[1,0]
	v_cvt_pk_bf16_f32 v40, v40, v41
	v_pk_fma_f32 v[44:45], v[44:45], v[46:47], v[50:51]
	v_pk_mul_f32 v[52:53], v[78:79], v[84:85] op_sel_hi:[1,0]
	v_pk_fma_f32 v[44:45], v[56:57], v[54:55], v[44:45] op_sel_hi:[0,1,1]
	v_pk_mul_f32 v[42:43], v[42:43], v[44:45]
	s_nop 0
	v_cvt_pk_bf16_f32 v41, v42, v43
	global_store_dwordx2 v[58:59], v[40:41], off offset:32
	s_nop 0
	s_nop 0
	s_nop 0
	s_nop 0
	v_lshlrev_b32_e32 v44, 16, v160
	v_lshlrev_b32_e32 v46, 16, v161
	s_nop 0
	v_lshlrev_b32_e32 v48, 16, v162
	v_and_b32_e32 v45, 0xffff0000, v160
	v_and_b32_e32 v49, 0xffff0000, v162
	v_lshlrev_b32_e32 v50, 16, v163
	v_and_b32_e32 v47, 0xffff0000, v161
	v_and_b32_e32 v51, 0xffff0000, v163
	global_load_dwordx4 v[40:43], v[68:69], off offset:384
	v_pk_add_f32 v[48:49], v[48:49], v[44:45] neg_lo:[0,1] neg_hi:[0,1]
	s_nop 0
	s_waitcnt vmcnt(0)
	v_pk_fma_f32 v[48:49], v[40:41], v[48:49], v[44:45]
	v_pk_add_f32 v[40:41], v[50:51], v[46:47] neg_lo:[0,1] neg_hi:[0,1]
	s_nop 0
	v_pk_fma_f32 v[50:51], v[42:43], v[40:41], v[46:47]
	global_load_dwordx4 v[40:43], v[66:67], off offset:128
	global_load_dwordx4 v[44:47], v[64:65], off offset:128
	s_nop 0
	s_waitcnt vmcnt(0)
	v_pk_fma_f32 v[40:41], v[52:53], v[40:41], v[44:45]
	s_nop 0
	v_pk_fma_f32 v[40:41], v[56:57], v[48:49], v[40:41] op_sel_hi:[0,1,1]
	v_pk_mul_f32 v[36:37], v[36:37], v[40:41]
	v_pk_mul_f32 v[40:41], v[62:63], v[84:85] op_sel_hi:[1,0]
	v_cvt_pk_bf16_f32 v36, v36, v37
	v_pk_fma_f32 v[40:41], v[40:41], v[42:43], v[46:47]
	v_pk_mul_f32 v[48:49], v[82:83], v[84:85] op_sel_hi:[1,0]
	v_pk_fma_f32 v[40:41], v[56:57], v[50:51], v[40:41] op_sel_hi:[0,1,1]
	v_pk_mul_f32 v[38:39], v[38:39], v[40:41]
	s_nop 0
	v_cvt_pk_bf16_f32 v37, v38, v39
	global_store_dwordx2 v[58:59], v[36:37], off offset:64
	s_nop 0
	s_nop 0
	s_nop 0
	s_nop 0
	v_lshlrev_b32_e32 v40, 16, v164
	v_lshlrev_b32_e32 v42, 16, v165
	s_nop 0
	v_lshlrev_b32_e32 v44, 16, v166
	v_and_b32_e32 v41, 0xffff0000, v164
	v_and_b32_e32 v45, 0xffff0000, v166
	v_lshlrev_b32_e32 v46, 16, v167
	v_and_b32_e32 v43, 0xffff0000, v165
	v_and_b32_e32 v47, 0xffff0000, v167
	global_load_dwordx4 v[36:39], v[68:69], off offset:448
	v_pk_add_f32 v[44:45], v[44:45], v[40:41] neg_lo:[0,1] neg_hi:[0,1]
	s_nop 0
	s_waitcnt vmcnt(0)
	v_pk_fma_f32 v[44:45], v[36:37], v[44:45], v[40:41]
	v_pk_add_f32 v[36:37], v[46:47], v[42:43] neg_lo:[0,1] neg_hi:[0,1]
	s_nop 0
	v_pk_fma_f32 v[46:47], v[38:39], v[36:37], v[42:43]
	global_load_dwordx4 v[36:39], v[66:67], off offset:192
	global_load_dwordx4 v[40:43], v[64:65], off offset:192
	s_nop 0
	s_waitcnt vmcnt(0)
	v_pk_fma_f32 v[36:37], v[48:49], v[36:37], v[40:41]
	s_nop 0
	v_pk_fma_f32 v[36:37], v[56:57], v[44:45], v[36:37] op_sel_hi:[0,1,1]
	v_pk_mul_f32 v[32:33], v[32:33], v[36:37]
	v_pk_mul_f32 v[36:37], v[80:81], v[84:85] op_sel_hi:[1,0]
	v_cvt_pk_bf16_f32 v32, v32, v33
	v_pk_fma_f32 v[36:37], v[36:37], v[38:39], v[42:43]
	s_nop 0
	v_pk_fma_f32 v[36:37], v[56:57], v[46:47], v[36:37] op_sel_hi:[0,1,1]
	v_pk_mul_f32 v[34:35], v[34:35], v[36:37]
	s_nop 0
	v_cvt_pk_bf16_f32 v33, v34, v35
	global_store_dwordx2 v[58:59], v[32:33], off offset:96
	v_add_u32_e32 v32, 32, v76
	v_ashrrev_i32_e32 v33, 31, v32
	v_lshlrev_b64 v[34:35], 5, v[32:33]
	v_lshl_add_u64 v[34:35], s[26:27], 0, v[34:35]
	v_lshl_add_u64 v[34:35], v[34:35], 0, v[74:75]
	global_load_dword v40, v[34:35], off
	v_lshlrev_b64 v[34:35], 11, v[32:33]
	v_lshl_add_u64 v[34:35], s[30:31], 0, v[34:35]
	v_lshl_add_u64 v[42:43], v[34:35], 0, v[72:73]
	global_load_dwordx2 v[34:35], v[42:43], off
	global_load_dwordx2 v[38:39], v[42:43], off offset:32
	global_load_dwordx2 v[46:47], v[42:43], off offset:64
	global_load_dwordx2 v[50:51], v[42:43], off offset:96
	s_nop 0
	s_waitcnt vmcnt(3)
	v_lshlrev_b32_e32 v36, 16, v34
	v_and_b32_e32 v37, 0xffff0000, v34
	v_lshlrev_b32_e32 v34, 16, v35
	v_add_f32_e32 v33, v37, v36
	s_nop 0
	s_waitcnt vmcnt(2)
	v_lshlrev_b32_e32 v44, 16, v38
	v_and_b32_e32 v45, 0xffff0000, v38
	v_and_b32_e32 v35, 0xffff0000, v35
	v_add_f32_e32 v33, v33, v34
	v_lshlrev_b32_e32 v38, 16, v39
	v_add_f32_e32 v41, v45, v44
	v_add_f32_e32 v33, v33, v35
	v_and_b32_e32 v39, 0xffff0000, v39
	v_add_f32_e32 v41, v41, v38
	v_add_f32_e32 v33, 0, v33
	v_add_f32_e32 v41, v41, v39
	s_nop 0
	s_waitcnt vmcnt(1)
	v_lshlrev_b32_e32 v48, 16, v46
	v_and_b32_e32 v49, 0xffff0000, v46
	v_add_f32_e32 v33, v33, v41
	v_lshlrev_b32_e32 v46, 16, v47
	v_add_f32_e32 v41, v49, v48
	v_and_b32_e32 v47, 0xffff0000, v47
	v_add_f32_e32 v41, v41, v46
	v_add_f32_e32 v41, v41, v47
	s_nop 0
	s_waitcnt vmcnt(0)
; __device__ __forceinline__ void unpack4(uint2 u, float* f) { f[0] = bflo(u.x); f[1] = bfhi(u.x); f[2] = bflo(u.y); f[3] = bfhi(u.y); }
; __device__ __forceinline__ uint2 pack4(float a, float b, float c, float d) { return make_uint2(pack2(a, b), pack2(c, d)); }
; __device__ __forceinline__ float xadd16(float x) { unsigned a = __float_as_uint(x); auto r = __builtin_amdgcn_permlane16_swap(a, a, false, false); return __uint_as_float(r[0]) + __uint_as_float(r[1]); }
; __device__ __forceinline__ float xadd32(float x) { unsigned a = __float_as_uint(x); auto r = __builtin_amdgcn_permlane32_swap(a, a, false, false); return __uint_as_float(r[0]) + __uint_as_float(r[1]); }
;   __device__ __forceinline__ void operator()(f32x4 (&acc)[4][4], int mw, int nw, int lane, int) const {
;     ...
;       const int m = mw + j * 16 + (lane & 15);
;       float y[16], sum = 0.f;
;       const float c3 = c3buf[(size_t)m * 8 + hh];
; #pragma unroll
;       for (int i = 0; i < 4; i++) {
;         const int ch = nw + i * 16 + (lane >> 4) * 4;
;         unpack4(*(const uint2*)(A + (size_t)m * 1024 + ch), y + i * 4);
;         sum += y[i * 4] + y[i * 4 + 1] + y[i * 4 + 2] + y[i * 4 + 3];
;       }
;       sum = xadd32(xadd16(sum));
;       const float mean = sum * (1.f / 64.f);
;       float var = 0.f;
; #pragma unroll
;       for (int i = 0; i < 16; i++) var += (y[i] - mean) * (y[i] - mean);
;       var = xadd32(xadd16(var));
;       const float rstd = rsqrtf(var * (1.f / 64.f) + 64e-5f);
; #pragma unroll
;       for (int i = 0; i < 4; i++) {
;         const int ch = nw + i * 16 + (lane >> 4) * 4;
;         float vs[4];
;         rw_shift4(pj, mu, m, 1088 + ch, vs);
;         float4 lg = *(const float4*)(ln_g + ch), lb = *(const float4*)(ln_b + ch);
;         float o0 = ((y[i * 4 + 0] - mean) * rstd * lg.x + lb.x + c3 * vs[0]) * acc[i][j][0];
;         float o1 = ((y[i * 4 + 1] - mean) * rstd * lg.y + lb.y + c3 * vs[1]) * acc[i][j][1];
;         float o2 = ((y[i * 4 + 2] - mean) * rstd * lg.z + lb.z + c3 * vs[2]) * acc[i][j][2];
;         float o3 = ((y[i * 4 + 3] - mean) * rstd * lg.w + lb.w + c3 * vs[3]) * acc[i][j][3];
;         *(uint2*)(A + (size_t)m * 1024 + ch) = pack4(o0, o1, o2, o3);
	v_lshlrev_b32_e32 v52, 16, v50
	v_and_b32_e32 v53, 0xffff0000, v50
	v_add_f32_e32 v33, v33, v41
	v_lshlrev_b32_e32 v50, 16, v51
	v_add_f32_e32 v41, v53, v52
	v_and_b32_e32 v51, 0xffff0000, v51
	v_add_f32_e32 v41, v41, v50
	v_add_f32_e32 v41, v41, v51
	v_add_f32_e32 v33, v33, v41
	v_mov_b32_e32 v41, v33
	s_nop 1
	v_permlane16_swap_b32_e32 v33, v41
	v_add_f32_e32 v33, v33, v41
	v_mov_b32_e32 v41, v33
	s_nop 1
	v_permlane32_swap_b32_e32 v33, v41
	v_add_f32_e32 v33, v33, v41
	v_mul_f32_e32 v54, 0x3c800000, v33
	v_pk_add_f32 v[56:57], v[36:37], v[54:55] op_sel_hi:[1,0] neg_lo:[0,1] neg_hi:[0,1]
	v_pk_add_f32 v[58:59], v[34:35], v[54:55] op_sel_hi:[1,0] neg_lo:[0,1] neg_hi:[0,1]
	v_mul_f32_e32 v36, v57, v57
	v_pk_fma_f32 v[36:37], v[56:57], v[56:57], v[36:37] op_sel_hi:[1,1,0]
	v_pk_add_f32 v[44:45], v[44:45], v[54:55] op_sel_hi:[1,0] neg_lo:[0,1] neg_hi:[0,1]
	v_pk_fma_f32 v[34:35], v[58:59], v[58:59], v[36:37]
	v_mul_f32_e32 v36, v59, v59
	v_pk_add_f32 v[34:35], v[36:37], v[34:35] op_sel_hi:[0,1]
	v_pk_fma_f32 v[34:35], v[44:45], v[44:45], v[34:35]
	v_mul_f32_e32 v36, v45, v45
	v_pk_add_f32 v[34:35], v[36:37], v[34:35] op_sel_hi:[0,1]
	v_pk_add_f32 v[60:61], v[38:39], v[54:55] op_sel_hi:[1,0] neg_lo:[0,1] neg_hi:[0,1]
	v_pk_add_f32 v[48:49], v[48:49], v[54:55] op_sel_hi:[1,0] neg_lo:[0,1] neg_hi:[0,1]
	v_pk_fma_f32 v[34:35], v[60:61], v[60:61], v[34:35]
	v_mul_f32_e32 v36, v61, v61
	v_pk_add_f32 v[34:35], v[36:37], v[34:35] op_sel_hi:[0,1]
	v_pk_fma_f32 v[34:35], v[48:49], v[48:49], v[34:35]
	v_mul_f32_e32 v36, v49, v49
	v_pk_add_f32 v[34:35], v[36:37], v[34:35] op_sel_hi:[0,1]
	v_pk_add_f32 v[46:47], v[46:47], v[54:55] op_sel_hi:[1,0] neg_lo:[0,1] neg_hi:[0,1]
	v_pk_add_f32 v[52:53], v[52:53], v[54:55] op_sel_hi:[1,0] neg_lo:[0,1] neg_hi:[0,1]
	v_pk_fma_f32 v[34:35], v[46:47], v[46:47], v[34:35]
	v_mul_f32_e32 v36, v47, v47
	v_pk_add_f32 v[34:35], v[36:37], v[34:35] op_sel_hi:[0,1]
	v_pk_fma_f32 v[34:35], v[52:53], v[52:53], v[34:35]
	v_mul_f32_e32 v36, v53, v53
	v_pk_add_f32 v[34:35], v[36:37], v[34:35] op_sel_hi:[0,1]
	v_pk_add_f32 v[50:51], v[50:51], v[54:55] op_sel_hi:[1,0] neg_lo:[0,1] neg_hi:[0,1]
	s_nop 0
	v_pk_fma_f32 v[34:35], v[50:51], v[50:51], v[34:35]
	v_mul_f32_e32 v36, v51, v51
	v_pk_add_f32 v[34:35], v[36:37], v[34:35] op_sel_hi:[0,1]
	v_mov_b32_e32 v33, v34
	s_nop 1
	v_permlane16_swap_b32_e32 v34, v33
	v_add_f32_e32 v33, v34, v33
	v_mov_b32_e32 v34, v33
	s_nop 1
	v_permlane32_swap_b32_e32 v33, v34
	v_add_f32_e32 v33, v33, v34
	v_fmamk_f32 v33, v33, 0x3c800000, v201
	v_cmp_gt_f32_e32 vcc, s85, v33
	v_mul_f32_e32 v34, 0x4b800000, v33
	s_nop 0
	v_cndmask_b32_e32 v33, v33, v34, vcc
	v_rsq_f32_e32 v33, v33
	s_nop 0
	v_mul_f32_e32 v34, 0x45800000, v33
	v_cndmask_b32_e32 v54, v33, v34, vcc
	v_mad_i64_i32 v[32:33], s[8:9], v32, s16, v[70:71]
	v_lshl_add_u64 v[62:63], v[32:33], 0, v[72:73]
	global_load_dwordx2 v[152:153], v[62:63], off offset:2176
	global_load_dwordx2 v[154:155], v[62:63], off offset:-3456
	global_load_dwordx2 v[156:157], v[62:63], off offset:2208
	global_load_dwordx2 v[158:159], v[62:63], off offset:-3424
	global_load_dwordx2 v[160:161], v[62:63], off offset:2240
	global_load_dwordx2 v[162:163], v[62:63], off offset:-3392
	global_load_dwordx2 v[164:165], v[62:63], off offset:2272
	global_load_dwordx2 v[166:167], v[62:63], off offset:-3360
	s_nop 0
	s_nop 0
	v_pk_mul_f32 v[56:57], v[56:57], v[54:55] op_sel_hi:[1,0]
	v_pk_mul_f32 v[44:45], v[44:45], v[54:55] op_sel_hi:[1,0]
	s_nop 0
	s_waitcnt vmcnt(7)
	v_lshlrev_b32_e32 v36, 16, v152
	v_lshlrev_b32_e32 v38, 16, v153
	s_nop 0
	s_waitcnt vmcnt(6)
	v_lshlrev_b32_e32 v78, 16, v154
	v_and_b32_e32 v37, 0xffff0000, v152
	v_and_b32_e32 v79, 0xffff0000, v154
	v_lshlrev_b32_e32 v80, 16, v155
	v_and_b32_e32 v39, 0xffff0000, v153
	v_and_b32_e32 v81, 0xffff0000, v155
	global_load_dwordx4 v[32:35], v[68:69], off offset:256
	v_pk_add_f32 v[78:79], v[78:79], v[36:37] neg_lo:[0,1] neg_hi:[0,1]
	s_nop 0
	s_waitcnt vmcnt(0)
	v_pk_fma_f32 v[78:79], v[32:33], v[78:79], v[36:37]
	v_pk_add_f32 v[32:33], v[80:81], v[38:39] neg_lo:[0,1] neg_hi:[0,1]
	s_nop 0
	v_pk_fma_f32 v[80:81], v[34:35], v[32:33], v[38:39]
	global_load_dwordx4 v[32:35], v[66:67], off
	global_load_dwordx4 v[36:39], v[64:65], off
	s_nop 0
	s_waitcnt vmcnt(0)
	v_pk_fma_f32 v[32:33], v[32:33], v[56:57], v[36:37]
	s_nop 0
	v_pk_fma_f32 v[32:33], v[40:41], v[78:79], v[32:33] op_sel_hi:[0,1,1]
	v_pk_mul_f32 v[28:29], v[28:29], v[32:33]
	v_pk_mul_f32 v[32:33], v[58:59], v[54:55] op_sel_hi:[1,0]
	v_cvt_pk_bf16_f32 v28, v28, v29
	v_pk_fma_f32 v[32:33], v[32:33], v[34:35], v[38:39]
	s_nop 0
	v_pk_fma_f32 v[32:33], v[40:41], v[80:81], v[32:33] op_sel_hi:[0,1,1]
	v_pk_mul_f32 v[30:31], v[30:31], v[32:33]
	s_nop 0
	v_cvt_pk_bf16_f32 v29, v30, v31
	global_store_dwordx2 v[42:43], v[28:29], off
	s_nop 0
	s_nop 0
	s_nop 0
	s_nop 0
	v_lshlrev_b32_e32 v32, 16, v156
	v_lshlrev_b32_e32 v34, 16, v157
	s_nop 0
	v_lshlrev_b32_e32 v36, 16, v158
	v_and_b32_e32 v33, 0xffff0000, v156
	v_and_b32_e32 v37, 0xffff0000, v158
	v_lshlrev_b32_e32 v38, 16, v159
	v_and_b32_e32 v35, 0xffff0000, v157
	v_and_b32_e32 v39, 0xffff0000, v159
	global_load_dwordx4 v[28:31], v[68:69], off offset:320
	v_pk_add_f32 v[36:37], v[36:37], v[32:33] neg_lo:[0,1] neg_hi:[0,1]
	s_nop 0
	s_waitcnt vmcnt(0)
	v_pk_fma_f32 v[36:37], v[28:29], v[36:37], v[32:33]
	v_pk_add_f32 v[28:29], v[38:39], v[34:35] neg_lo:[0,1] neg_hi:[0,1]
	s_nop 0
	v_pk_fma_f32 v[38:39], v[30:31], v[28:29], v[34:35]
	global_load_dwordx4 v[28:31], v[66:67], off offset:64
	global_load_dwordx4 v[32:35], v[64:65], off offset:64
	s_nop 0
	s_waitcnt vmcnt(0)
; __device__ __forceinline__ void unpack4(uint2 u, float* f) { f[0] = bflo(u.x); f[1] = bfhi(u.x); f[2] = bflo(u.y); f[3] = bfhi(u.y); }
; __device__ __forceinline__ uint2 pack4(float a, float b, float c, float d) { return make_uint2(pack2(a, b), pack2(c, d)); }
; __device__ __forceinline__ float xadd16(float x) { unsigned a = __float_as_uint(x); auto r = __builtin_amdgcn_permlane16_swap(a, a, false, false); return __uint_as_float(r[0]) + __uint_as_float(r[1]); }
; __device__ __forceinline__ float xadd32(float x) { unsigned a = __float_as_uint(x); auto r = __builtin_amdgcn_permlane32_swap(a, a, false, false); return __uint_as_float(r[0]) + __uint_as_float(r[1]); }
;   __device__ __forceinline__ void operator()(f32x4 (&acc)[4][4], int mw, int nw, int lane, int) const {
;     ...
;     for (int j = 0; j < 4; j++) {
;       const int m = mw + j * 16 + (lane & 15);
;       float y[16], sum = 0.f;
;       const float c3 = c3buf[(size_t)m * 8 + hh];
; #pragma unroll
;       for (int i = 0; i < 4; i++) {
;         const int ch = nw + i * 16 + (lane >> 4) * 4;
;         unpack4(*(const uint2*)(A + (size_t)m * 1024 + ch), y + i * 4);
;         sum += y[i * 4] + y[i * 4 + 1] + y[i * 4 + 2] + y[i * 4 + 3];
;       }
;       sum = xadd32(xadd16(sum));
;       const float mean = sum * (1.f / 64.f);
;       float var = 0.f;
; #pragma unroll
;       for (int i = 0; i < 16; i++) var += (y[i] - mean) * (y[i] - mean);
;       var = xadd32(xadd16(var));
;       const float rstd = rsqrtf(var * (1.f / 64.f) + 64e-5f);
; #pragma unroll
;       for (int i = 0; i < 4; i++) {
;         const int ch = nw + i * 16 + (lane >> 4) * 4;
;         float vs[4];
;         rw_shift4(pj, mu, m, 1088 + ch, vs);
;         float4 lg = *(const float4*)(ln_g + ch), lb = *(const float4*)(ln_b + ch);
;         float o0 = ((y[i * 4 + 0] - mean) * rstd * lg.x + lb.x + c3 * vs[0]) * acc[i][j][0];
;         float o1 = ((y[i * 4 + 1] - mean) * rstd * lg.y + lb.y + c3 * vs[1]) * acc[i][j][1];
;         float o2 = ((y[i * 4 + 2] - mean) * rstd * lg.z + lb.z + c3 * vs[2]) * acc[i][j][2];
;         float o3 = ((y[i * 4 + 3] - mean) * rstd * lg.w + lb.w + c3 * vs[3]) * acc[i][j][3];
;         *(uint2*)(A + (size_t)m * 1024 + ch) = pack4(o0, o1, o2, o3);
	v_pk_fma_f32 v[28:29], v[44:45], v[28:29], v[32:33]
	s_nop 0
	v_pk_fma_f32 v[28:29], v[40:41], v[36:37], v[28:29] op_sel_hi:[0,1,1]
	v_pk_mul_f32 v[24:25], v[24:25], v[28:29]
	v_pk_mul_f32 v[28:29], v[60:61], v[54:55] op_sel_hi:[1,0]
	v_cvt_pk_bf16_f32 v24, v24, v25
	v_pk_fma_f32 v[28:29], v[28:29], v[30:31], v[34:35]
	v_pk_mul_f32 v[36:37], v[48:49], v[54:55] op_sel_hi:[1,0]
	v_pk_fma_f32 v[28:29], v[40:41], v[38:39], v[28:29] op_sel_hi:[0,1,1]
	v_pk_mul_f32 v[26:27], v[26:27], v[28:29]
	v_add_u32_e32 v38, 48, v76
	v_cvt_pk_bf16_f32 v25, v26, v27
	global_store_dwordx2 v[42:43], v[24:25], off offset:32
	s_nop 0
	v_ashrrev_i32_e32 v39, 31, v38
	s_nop 0
	s_nop 0
	v_lshlrev_b32_e32 v28, 16, v160
	v_lshlrev_b32_e32 v30, 16, v161
	s_nop 0
	v_lshlrev_b32_e32 v32, 16, v162
	v_and_b32_e32 v29, 0xffff0000, v160
	v_and_b32_e32 v33, 0xffff0000, v162
	v_lshlrev_b32_e32 v34, 16, v163
	v_and_b32_e32 v31, 0xffff0000, v161
	v_and_b32_e32 v35, 0xffff0000, v163
	global_load_dwordx4 v[24:27], v[68:69], off offset:384
	v_pk_add_f32 v[32:33], v[32:33], v[28:29] neg_lo:[0,1] neg_hi:[0,1]
	s_nop 0
	s_waitcnt vmcnt(0)
	v_pk_fma_f32 v[32:33], v[24:25], v[32:33], v[28:29]
	v_pk_add_f32 v[24:25], v[34:35], v[30:31] neg_lo:[0,1] neg_hi:[0,1]
	s_nop 0
	v_pk_fma_f32 v[34:35], v[26:27], v[24:25], v[30:31]
	global_load_dwordx4 v[24:27], v[66:67], off offset:128
	global_load_dwordx4 v[28:31], v[64:65], off offset:128
	s_nop 0
	s_waitcnt vmcnt(0)
	v_pk_fma_f32 v[24:25], v[36:37], v[24:25], v[28:29]
	s_nop 0
	v_pk_fma_f32 v[24:25], v[40:41], v[32:33], v[24:25] op_sel_hi:[0,1,1]
	v_pk_mul_f32 v[20:21], v[20:21], v[24:25]
	v_pk_mul_f32 v[24:25], v[46:47], v[54:55] op_sel_hi:[1,0]
	v_cvt_pk_bf16_f32 v20, v20, v21
	v_pk_fma_f32 v[24:25], v[24:25], v[26:27], v[30:31]
	v_pk_mul_f32 v[32:33], v[52:53], v[54:55] op_sel_hi:[1,0]
	v_pk_fma_f32 v[24:25], v[40:41], v[34:35], v[24:25] op_sel_hi:[0,1,1]
	v_pk_mul_f32 v[22:23], v[22:23], v[24:25]
	s_nop 0
	v_cvt_pk_bf16_f32 v21, v22, v23
	global_store_dwordx2 v[42:43], v[20:21], off offset:64
	s_nop 0
	s_nop 0
	s_nop 0
	s_nop 0
	v_lshlrev_b32_e32 v24, 16, v164
	v_lshlrev_b32_e32 v26, 16, v165
	s_nop 0
	v_lshlrev_b32_e32 v28, 16, v166
	v_and_b32_e32 v25, 0xffff0000, v164
	v_and_b32_e32 v29, 0xffff0000, v166
	v_lshlrev_b32_e32 v30, 16, v167
	v_and_b32_e32 v27, 0xffff0000, v165
	v_and_b32_e32 v31, 0xffff0000, v167
	global_load_dwordx4 v[20:23], v[68:69], off offset:448
	v_pk_add_f32 v[28:29], v[28:29], v[24:25] neg_lo:[0,1] neg_hi:[0,1]
	s_nop 0
	s_waitcnt vmcnt(0)
	v_pk_fma_f32 v[28:29], v[20:21], v[28:29], v[24:25]
	v_pk_add_f32 v[20:21], v[30:31], v[26:27] neg_lo:[0,1] neg_hi:[0,1]
	s_nop 0
	v_pk_fma_f32 v[30:31], v[22:23], v[20:21], v[26:27]
	global_load_dwordx4 v[20:23], v[66:67], off offset:192
	global_load_dwordx4 v[24:27], v[64:65], off offset:192
	s_nop 0
	s_waitcnt vmcnt(0)
	v_pk_fma_f32 v[20:21], v[32:33], v[20:21], v[24:25]
	s_nop 0
	v_pk_fma_f32 v[20:21], v[40:41], v[28:29], v[20:21] op_sel_hi:[0,1,1]
	v_pk_mul_f32 v[16:17], v[16:17], v[20:21]
	v_pk_mul_f32 v[20:21], v[50:51], v[54:55] op_sel_hi:[1,0]
	v_cvt_pk_bf16_f32 v16, v16, v17
	v_pk_fma_f32 v[20:21], v[20:21], v[22:23], v[26:27]
	s_nop 0
	v_pk_fma_f32 v[20:21], v[40:41], v[30:31], v[20:21] op_sel_hi:[0,1,1]
	v_pk_mul_f32 v[18:19], v[18:19], v[20:21]
	s_nop 0
	v_cvt_pk_bf16_f32 v17, v18, v19
	global_store_dwordx2 v[42:43], v[16:17], off offset:96
	v_lshlrev_b64 v[16:17], 5, v[38:39]
	v_lshl_add_u64 v[16:17], s[26:27], 0, v[16:17]
	v_lshl_add_u64 v[16:17], v[16:17], 0, v[74:75]
	global_load_dword v18, v[16:17], off
	v_lshlrev_b64 v[16:17], 11, v[38:39]
	v_lshl_add_u64 v[16:17], s[30:31], 0, v[16:17]
	v_lshl_add_u64 v[16:17], v[16:17], 0, v[72:73]
	global_load_dwordx2 v[152:153], v[16:17], off offset:64
	global_load_dwordx2 v[154:155], v[16:17], off offset:96
	global_load_dwordx2 v[20:21], v[16:17], off
	global_load_dwordx2 v[24:25], v[16:17], off offset:32
	v_mad_i64_i32 v[38:39], s[8:9], v38, s16, v[70:71]
	v_lshl_add_u64 v[38:39], v[38:39], 0, v[72:73]
	global_load_dwordx2 v[156:157], v[38:39], off offset:-3456
	global_load_dwordx2 v[158:159], v[38:39], off offset:2176
	global_load_dwordx2 v[160:161], v[38:39], off offset:2208
	global_load_dwordx2 v[162:163], v[38:39], off offset:-3424
	global_load_dwordx2 v[164:165], v[38:39], off offset:2240
	global_load_dwordx2 v[166:167], v[38:39], off offset:-3392
	global_load_dwordx2 v[168:169], v[38:39], off offset:2272
	global_load_dwordx2 v[170:171], v[38:39], off offset:-3360
	s_nop 0
	s_waitcnt vmcnt(9)
	v_lshlrev_b32_e32 v22, 16, v20
	v_and_b32_e32 v23, 0xffff0000, v20
	v_lshlrev_b32_e32 v20, 16, v21
	v_add_f32_e32 v19, v23, v22
	s_nop 0
	s_waitcnt vmcnt(8)
; __device__ __forceinline__ void unpack4(uint2 u, float* f) { f[0] = bflo(u.x); f[1] = bfhi(u.x); f[2] = bflo(u.y); f[3] = bfhi(u.y); }
; __device__ __forceinline__ uint2 pack4(float a, float b, float c, float d) { return make_uint2(pack2(a, b), pack2(c, d)); }
; __device__ __forceinline__ float xadd16(float x) { unsigned a = __float_as_uint(x); auto r = __builtin_amdgcn_permlane16_swap(a, a, false, false); return __uint_as_float(r[0]) + __uint_as_float(r[1]); }
; __device__ __forceinline__ float xadd32(float x) { unsigned a = __float_as_uint(x); auto r = __builtin_amdgcn_permlane32_swap(a, a, false, false); return __uint_as_float(r[0]) + __uint_as_float(r[1]); }
;   __device__ __forceinline__ void operator()(f32x4 (&acc)[4][4], int mw, int nw, int lane, int) const {
;     ...
;     for (int j = 0; j < 4; j++) {
;       const int m = mw + j * 16 + (lane & 15);
;       float y[16], sum = 0.f;
;       const float c3 = c3buf[(size_t)m * 8 + hh];
; #pragma unroll
;       for (int i = 0; i < 4; i++) {
;         const int ch = nw + i * 16 + (lane >> 4) * 4;
;         unpack4(*(const uint2*)(A + (size_t)m * 1024 + ch), y + i * 4);
;         sum += y[i * 4] + y[i * 4 + 1] + y[i * 4 + 2] + y[i * 4 + 3];
;       }
;       sum = xadd32(xadd16(sum));
;       const float mean = sum * (1.f / 64.f);
;       float var = 0.f;
; #pragma unroll
;       for (int i = 0; i < 16; i++) var += (y[i] - mean) * (y[i] - mean);
;       var = xadd32(xadd16(var));
;       const float rstd = rsqrtf(var * (1.f / 64.f) + 64e-5f);
; #pragma unroll
;       for (int i = 0; i < 4; i++) {
;         const int ch = nw + i * 16 + (lane >> 4) * 4;
;         float vs[4];
;         rw_shift4(pj, mu, m, 1088 + ch, vs);
;         float4 lg = *(const float4*)(ln_g + ch), lb = *(const float4*)(ln_b + ch);
;         float o0 = ((y[i * 4 + 0] - mean) * rstd * lg.x + lb.x + c3 * vs[0]) * acc[i][j][0];
;         float o1 = ((y[i * 4 + 1] - mean) * rstd * lg.y + lb.y + c3 * vs[1]) * acc[i][j][1];
;         float o2 = ((y[i * 4 + 2] - mean) * rstd * lg.z + lb.z + c3 * vs[2]) * acc[i][j][2];
;         float o3 = ((y[i * 4 + 3] - mean) * rstd * lg.w + lb.w + c3 * vs[3]) * acc[i][j][3];
;         *(uint2*)(A + (size_t)m * 1024 + ch) = pack4(o0, o1, o2, o3);
;       }
	v_lshlrev_b32_e32 v26, 16, v24
	v_and_b32_e32 v27, 0xffff0000, v24
	v_and_b32_e32 v21, 0xffff0000, v21
	v_add_f32_e32 v19, v19, v20
	v_lshlrev_b32_e32 v24, 16, v25
	v_add_f32_e32 v28, v27, v26
	v_add_f32_e32 v19, v19, v21
	v_and_b32_e32 v25, 0xffff0000, v25
	v_add_f32_e32 v28, v28, v24
	v_add_f32_e32 v19, 0, v19
	v_add_f32_e32 v28, v28, v25
	v_add_f32_e32 v19, v19, v28
	s_nop 0
	s_nop 0
	v_lshlrev_b32_e32 v40, 16, v152
	v_and_b32_e32 v41, 0xffff0000, v152
	v_lshlrev_b32_e32 v42, 16, v153
	v_add_f32_e32 v28, v41, v40
	v_and_b32_e32 v43, 0xffff0000, v153
	v_add_f32_e32 v28, v28, v42
	v_add_f32_e32 v28, v28, v43
	v_add_f32_e32 v19, v19, v28
	s_nop 0
	s_nop 0
	v_lshlrev_b32_e32 v44, 16, v154
	v_and_b32_e32 v45, 0xffff0000, v154
	v_lshlrev_b32_e32 v46, 16, v155
	v_add_f32_e32 v28, v45, v44
	v_and_b32_e32 v47, 0xffff0000, v155
	v_add_f32_e32 v28, v28, v46
	v_add_f32_e32 v28, v28, v47
	v_add_f32_e32 v19, v19, v28
	v_mov_b32_e32 v28, v19
	s_nop 1
	v_permlane16_swap_b32_e32 v19, v28
	v_add_f32_e32 v19, v19, v28
	v_mov_b32_e32 v28, v19
	s_nop 1
	v_permlane32_swap_b32_e32 v19, v28
	v_add_f32_e32 v19, v19, v28
	v_mul_f32_e32 v48, 0x3c800000, v19
	v_pk_add_f32 v[36:37], v[22:23], v[48:49] op_sel_hi:[1,0] neg_lo:[0,1] neg_hi:[0,1]
	v_pk_add_f32 v[34:35], v[20:21], v[48:49] op_sel_hi:[1,0] neg_lo:[0,1] neg_hi:[0,1]
	v_mul_f32_e32 v22, v37, v37
	v_pk_fma_f32 v[22:23], v[36:37], v[36:37], v[22:23] op_sel_hi:[1,1,0]
	v_pk_add_f32 v[32:33], v[26:27], v[48:49] op_sel_hi:[1,0] neg_lo:[0,1] neg_hi:[0,1]
	v_pk_fma_f32 v[20:21], v[34:35], v[34:35], v[22:23]
	v_mul_f32_e32 v22, v35, v35
	v_pk_add_f32 v[20:21], v[22:23], v[20:21] op_sel_hi:[0,1]
	v_pk_fma_f32 v[20:21], v[32:33], v[32:33], v[20:21]
	v_mul_f32_e32 v22, v33, v33
	v_pk_add_f32 v[20:21], v[22:23], v[20:21] op_sel_hi:[0,1]
	v_pk_add_f32 v[30:31], v[24:25], v[48:49] op_sel_hi:[1,0] neg_lo:[0,1] neg_hi:[0,1]
	v_pk_add_f32 v[28:29], v[40:41], v[48:49] op_sel_hi:[1,0] neg_lo:[0,1] neg_hi:[0,1]
	v_pk_fma_f32 v[20:21], v[30:31], v[30:31], v[20:21]
	v_mul_f32_e32 v22, v31, v31
	v_pk_add_f32 v[20:21], v[22:23], v[20:21] op_sel_hi:[0,1]
	v_pk_fma_f32 v[20:21], v[28:29], v[28:29], v[20:21]
	v_mul_f32_e32 v22, v29, v29
	v_pk_add_f32 v[20:21], v[22:23], v[20:21] op_sel_hi:[0,1]
	v_pk_add_f32 v[26:27], v[42:43], v[48:49] op_sel_hi:[1,0] neg_lo:[0,1] neg_hi:[0,1]
	s_nop 0
	v_pk_fma_f32 v[20:21], v[26:27], v[26:27], v[20:21]
	v_mul_f32_e32 v22, v27, v27
	v_pk_add_f32 v[22:23], v[22:23], v[20:21] op_sel_hi:[0,1]
	v_pk_add_f32 v[20:21], v[44:45], v[48:49] op_sel_hi:[1,0] neg_lo:[0,1] neg_hi:[0,1]
	s_nop 0
	s_waitcnt vmcnt(7)
	v_lshlrev_b32_e32 v50, 16, v157
	v_pk_fma_f32 v[22:23], v[20:21], v[20:21], v[22:23]
	v_mul_f32_e32 v24, v21, v21
	v_pk_add_f32 v[24:25], v[24:25], v[22:23] op_sel_hi:[0,1]
	v_pk_add_f32 v[22:23], v[46:47], v[48:49] op_sel_hi:[1,0] neg_lo:[0,1] neg_hi:[0,1]
	v_lshlrev_b32_e32 v48, 16, v156
	v_pk_fma_f32 v[24:25], v[22:23], v[22:23], v[24:25]
	v_mul_f32_e32 v40, v23, v23
	v_pk_add_f32 v[24:25], v[40:41], v[24:25] op_sel_hi:[0,1]
	s_nop 0
	v_and_b32_e32 v49, 0xffff0000, v156
	v_and_b32_e32 v51, 0xffff0000, v157
	v_mov_b32_e32 v19, v24
	s_nop 1
	v_permlane16_swap_b32_e32 v24, v19
	v_add_f32_e32 v19, v24, v19
	v_mov_b32_e32 v24, v19
	s_nop 1
	v_permlane32_swap_b32_e32 v19, v24
	v_add_f32_e32 v19, v19, v24
	v_fmamk_f32 v19, v19, 0x3c800000, v201
	v_cmp_gt_f32_e32 vcc, s85, v19
	v_mul_f32_e32 v24, 0x4b800000, v19
	s_nop 0
	s_waitcnt vmcnt(6)
	v_lshlrev_b32_e32 v44, 16, v158
	v_lshlrev_b32_e32 v46, 16, v159
	v_and_b32_e32 v45, 0xffff0000, v158
	v_and_b32_e32 v47, 0xffff0000, v159
	global_load_dwordx4 v[40:43], v[68:69], off offset:256
	v_pk_add_f32 v[48:49], v[48:49], v[44:45] neg_lo:[0,1] neg_hi:[0,1]
	v_cndmask_b32_e32 v19, v19, v24, vcc
	v_rsq_f32_e32 v19, v19
	s_nop 0
	s_waitcnt vmcnt(0)
	v_pk_fma_f32 v[48:49], v[40:41], v[48:49], v[44:45]
	v_pk_add_f32 v[40:41], v[50:51], v[46:47] neg_lo:[0,1] neg_hi:[0,1]
	v_mul_f32_e32 v24, 0x45800000, v19
	v_pk_fma_f32 v[50:51], v[42:43], v[40:41], v[46:47]
	global_load_dwordx4 v[40:43], v[66:67], off
	global_load_dwordx4 v[44:47], v[64:65], off
	v_cndmask_b32_e32 v24, v19, v24, vcc
	v_pk_mul_f32 v[36:37], v[36:37], v[24:25] op_sel_hi:[1,0]
	v_pk_mul_f32 v[34:35], v[34:35], v[24:25] op_sel_hi:[1,0]
	v_pk_mul_f32 v[32:33], v[32:33], v[24:25] op_sel_hi:[1,0]
	v_pk_mul_f32 v[28:29], v[28:29], v[24:25] op_sel_hi:[1,0]
	v_pk_mul_f32 v[20:21], v[20:21], v[24:25] op_sel_hi:[1,0]
	s_nop 0
	s_waitcnt vmcnt(0)
; __device__ __forceinline__ void unpack4(uint2 u, float* f) { f[0] = bflo(u.x); f[1] = bfhi(u.x); f[2] = bflo(u.y); f[3] = bfhi(u.y); }
; __device__ __forceinline__ uint2 pack4(float a, float b, float c, float d) { return make_uint2(pack2(a, b), pack2(c, d)); }
; __device__ __forceinline__ void rw_shift4(const u16* proj, const float* mu, int m, int col, float* f) {
;   const u16* pr = proj + (size_t)m * PROJ1_LD + col;
;   float a[4], b[4];
;   unpack4(*(const uint2*)pr, a);
;   const bool hasprev = (m & (SEQL - 1)) != 0;
;   unpack4(*(const uint2*)(pr - (hasprev ? PROJ1_LD : 0)), b);
;   const float pz = hasprev ? 1.f : 0.f;
;   b[0] *= pz; b[1] *= pz; b[2] *= pz; b[3] *= pz;
;   float4 m0 = *(const float4*)(mu + col);
;   f[0] = a[0] + (b[0] - a[0]) * m0.x; f[1] = a[1] + (b[1] - a[1]) * m0.y;
;   f[2] = a[2] + (b[2] - a[2]) * m0.z; f[3] = a[3] + (b[3] - a[3]) * m0.w;
; }
;   __device__ __forceinline__ void operator()(f32x4 (&acc)[4][4], int mw, int nw, int lane, int) const {
;     ...
; #pragma unroll
;       for (int i = 0; i < 4; i++) {
;         const int ch = nw + i * 16 + (lane >> 4) * 4;
;         float vs[4];
;         rw_shift4(pj, mu, m, 1088 + ch, vs);
;         float4 lg = *(const float4*)(ln_g + ch), lb = *(const float4*)(ln_b + ch);
;         float o0 = ((y[i * 4 + 0] - mean) * rstd * lg.x + lb.x + c3 * vs[0]) * acc[i][j][0];
;         float o1 = ((y[i * 4 + 1] - mean) * rstd * lg.y + lb.y + c3 * vs[1]) * acc[i][j][1];
;         float o2 = ((y[i * 4 + 2] - mean) * rstd * lg.z + lb.z + c3 * vs[2]) * acc[i][j][2];
;         float o3 = ((y[i * 4 + 3] - mean) * rstd * lg.w + lb.w + c3 * vs[3]) * acc[i][j][3];
;         *(uint2*)(A + (size_t)m * 1024 + ch) = pack4(o0, o1, o2, o3);
;       }
	v_pk_fma_f32 v[36:37], v[40:41], v[36:37], v[44:45]
	v_pk_fma_f32 v[34:35], v[34:35], v[42:43], v[46:47]
	v_pk_fma_f32 v[36:37], v[18:19], v[48:49], v[36:37] op_sel_hi:[0,1,1]
	v_pk_fma_f32 v[34:35], v[18:19], v[50:51], v[34:35] op_sel_hi:[0,1,1]
	v_pk_mul_f32 v[12:13], v[12:13], v[36:37]
	v_pk_mul_f32 v[14:15], v[14:15], v[34:35]
	v_cvt_pk_bf16_f32 v12, v12, v13
	v_cvt_pk_bf16_f32 v13, v14, v15
	global_store_dwordx2 v[16:17], v[12:13], off
	s_nop 0
	s_nop 0
	s_nop 0
	s_nop 0
	v_lshlrev_b32_e32 v34, 16, v160
	v_lshlrev_b32_e32 v36, 16, v161
	s_nop 0
	v_lshlrev_b32_e32 v40, 16, v162
	v_and_b32_e32 v35, 0xffff0000, v160
	v_and_b32_e32 v41, 0xffff0000, v162
	v_lshlrev_b32_e32 v42, 16, v163
	v_and_b32_e32 v37, 0xffff0000, v161
	v_and_b32_e32 v43, 0xffff0000, v163
	global_load_dwordx4 v[12:15], v[68:69], off offset:320
	v_pk_add_f32 v[40:41], v[40:41], v[34:35] neg_lo:[0,1] neg_hi:[0,1]
	s_nop 0
	s_waitcnt vmcnt(0)
	v_pk_fma_f32 v[40:41], v[12:13], v[40:41], v[34:35]
	v_pk_add_f32 v[12:13], v[42:43], v[36:37] neg_lo:[0,1] neg_hi:[0,1]
	s_nop 0
	v_pk_fma_f32 v[42:43], v[14:15], v[12:13], v[36:37]
	global_load_dwordx4 v[12:15], v[66:67], off offset:64
	global_load_dwordx4 v[34:37], v[64:65], off offset:64
	s_nop 0
	s_waitcnt vmcnt(0)
	v_pk_fma_f32 v[12:13], v[32:33], v[12:13], v[34:35]
	s_nop 0
	v_pk_fma_f32 v[12:13], v[18:19], v[40:41], v[12:13] op_sel_hi:[0,1,1]
	v_pk_mul_f32 v[8:9], v[8:9], v[12:13]
	v_pk_mul_f32 v[12:13], v[30:31], v[24:25] op_sel_hi:[1,0]
	v_cvt_pk_bf16_f32 v8, v8, v9
	v_pk_fma_f32 v[12:13], v[12:13], v[14:15], v[36:37]
	s_nop 0
	v_pk_fma_f32 v[12:13], v[18:19], v[42:43], v[12:13] op_sel_hi:[0,1,1]
	v_pk_mul_f32 v[10:11], v[10:11], v[12:13]
	s_nop 0
	v_cvt_pk_bf16_f32 v9, v10, v11
	global_store_dwordx2 v[16:17], v[8:9], off offset:32
	s_nop 0
	s_nop 0
	s_nop 0
	s_nop 0
	v_lshlrev_b32_e32 v12, 16, v164
	v_lshlrev_b32_e32 v14, 16, v165
	s_nop 0
	v_lshlrev_b32_e32 v30, 16, v166
	v_and_b32_e32 v13, 0xffff0000, v164
	v_and_b32_e32 v31, 0xffff0000, v166
	v_lshlrev_b32_e32 v32, 16, v167
	v_and_b32_e32 v15, 0xffff0000, v165
	v_and_b32_e32 v33, 0xffff0000, v167
	global_load_dwordx4 v[8:11], v[68:69], off offset:384
	v_pk_add_f32 v[30:31], v[30:31], v[12:13] neg_lo:[0,1] neg_hi:[0,1]
	s_nop 0
	s_waitcnt vmcnt(0)
	v_pk_fma_f32 v[30:31], v[8:9], v[30:31], v[12:13]
	v_pk_add_f32 v[8:9], v[32:33], v[14:15] neg_lo:[0,1] neg_hi:[0,1]
	s_nop 0
	v_pk_fma_f32 v[32:33], v[10:11], v[8:9], v[14:15]
	global_load_dwordx4 v[8:11], v[66:67], off offset:128
	global_load_dwordx4 v[12:15], v[64:65], off offset:128
	s_nop 0
	s_waitcnt vmcnt(0)
	v_pk_fma_f32 v[8:9], v[28:29], v[8:9], v[12:13]
	s_nop 0
	v_pk_fma_f32 v[8:9], v[18:19], v[30:31], v[8:9] op_sel_hi:[0,1,1]
	v_pk_mul_f32 v[4:5], v[4:5], v[8:9]
	v_pk_mul_f32 v[8:9], v[26:27], v[24:25] op_sel_hi:[1,0]
	v_cvt_pk_bf16_f32 v4, v4, v5
	v_pk_fma_f32 v[8:9], v[8:9], v[10:11], v[14:15]
	s_nop 0
	v_pk_fma_f32 v[8:9], v[18:19], v[32:33], v[8:9] op_sel_hi:[0,1,1]
	v_pk_mul_f32 v[6:7], v[6:7], v[8:9]
	s_nop 0
	v_cvt_pk_bf16_f32 v5, v6, v7
	global_store_dwordx2 v[16:17], v[4:5], off offset:64
	s_nop 0
	s_nop 0
	s_nop 0
	s_nop 0
	v_lshlrev_b32_e32 v8, 16, v168
	v_lshlrev_b32_e32 v10, 16, v169
	s_nop 0
	v_lshlrev_b32_e32 v12, 16, v170
	v_and_b32_e32 v9, 0xffff0000, v168
	v_and_b32_e32 v13, 0xffff0000, v170
	v_lshlrev_b32_e32 v14, 16, v171
	v_and_b32_e32 v11, 0xffff0000, v169
	v_and_b32_e32 v15, 0xffff0000, v171
	global_load_dwordx4 v[4:7], v[68:69], off offset:448
	v_pk_add_f32 v[12:13], v[12:13], v[8:9] neg_lo:[0,1] neg_hi:[0,1]
	s_nop 0
	s_waitcnt vmcnt(0)
	v_pk_fma_f32 v[12:13], v[4:5], v[12:13], v[8:9]
	v_pk_add_f32 v[4:5], v[14:15], v[10:11] neg_lo:[0,1] neg_hi:[0,1]
	s_nop 0
	v_pk_fma_f32 v[14:15], v[6:7], v[4:5], v[10:11]
	global_load_dwordx4 v[4:7], v[66:67], off offset:192
	global_load_dwordx4 v[8:11], v[64:65], off offset:192
	s_nop 0
	s_waitcnt vmcnt(0)
	v_pk_fma_f32 v[4:5], v[20:21], v[4:5], v[8:9]
	s_nop 0
	v_pk_fma_f32 v[4:5], v[18:19], v[12:13], v[4:5] op_sel_hi:[0,1,1]
	v_pk_mul_f32 v[0:1], v[0:1], v[4:5]
	v_pk_mul_f32 v[4:5], v[22:23], v[24:25] op_sel_hi:[1,0]
	v_cvt_pk_bf16_f32 v0, v0, v1
	v_pk_fma_f32 v[4:5], v[4:5], v[6:7], v[10:11]
	s_nop 0
	v_pk_fma_f32 v[4:5], v[18:19], v[14:15], v[4:5] op_sel_hi:[0,1,1]
	v_pk_mul_f32 v[2:3], v[2:3], v[4:5]
	s_nop 0
	v_cvt_pk_bf16_f32 v1, v2, v3
	global_store_dwordx2 v[16:17], v[0:1], off offset:96
	s_cbranch_scc0 .LBB0_110

; __device__ __forceinline__ int ltid() { int t = threadIdx.x; asm volatile("" : "+v"(t)); return t; }
; __device__ __forceinline__ void transpose_tile(const TDesc& d, int tile, float* sm) {
;   const int ktn = d.K >> 6;
;   const int kt = tile % ktn, ntl = tile / ktn;
;   const int k0 = kt * 64, n0 = ntl * 64;
;   const int tid = ltid();
;   __syncthreads();
; #pragma unroll
;   for (int i = 0; i < 16; i++) {
;     int e = tid + i * 256;
;     int kk = e >> 6, nn = e & 63;
;     const int nc = n0 + nn;
;     float v = __builtin_nontemporal_load(&d.src[(size_t)(k0 + kk) * d.N + (nc < d.N ? nc : d.N - 1)]);
;     sm[kk * 65 + nn] = (nc < d.N) ? v : 0.f;
;   }
;   __syncthreads();
; #pragma unroll
;   for (int i = 0; i < 2; i++) {
;     int e = tid + i * 256;
;     int nn = e >> 3, kc = (e & 7) * 8;
;     float f[8];
; #pragma unroll
;     for (int q = 0; q < 8; q++) f[q] = sm[(kc + q) * 65 + nn];
;     *(bf16x8*)(d.dst + (size_t)(n0 + nn) * d.K + k0 + kc) = pack8(f);
;   }
.LBB0_117:
	s_lshl_b64 s[6:7], s[6:7], 5
	s_add_u32 s12, s0, s6
	s_addc_u32 s13, s1, s7
	s_load_dwordx4 s[8:11], s[12:13], 0x738
	s_load_dwordx2 s[6:7], s[12:13], 0x748
	s_load_dword s4, s[12:13], 0x754
	v_mov_b32_e32 v1, v132
	s_load_dword s12, s[12:13], 0x748
	s_waitcnt lgkmcnt(0)
	v_mov_b32_e32 v2, s8
	s_sub_i32 s4, s14, s4
	s_abs_i32 s15, s4
	s_ashr_i32 s12, s12, 6
	s_abs_i32 s16, s12
	v_cvt_f32_u32_e32 v0, s16
	s_sub_i32 s17, 0, s16
	s_xor_b32 s13, s4, s12
	s_ashr_i32 s13, s13, 31
	v_rcp_iflag_f32_e32 v0, v0
	v_mov_b32_e32 v3, s9
	v_ashrrev_i32_e32 v6, 6, v1
	v_mul_f32_e32 v0, 0x4f7ffffe, v0
	v_cvt_u32_f32_e32 v0, v0
	s_barrier
	v_ashrrev_i32_e32 v11, 3, v1
	v_readfirstlane_b32 s61, v0
	s_mul_i32 s17, s17, s61
	s_mul_hi_u32 s17, s61, s17
	s_add_i32 s61, s61, s17
	s_mul_hi_u32 s17, s15, s61
	s_mul_i32 s61, s17, s16
	s_sub_i32 s15, s15, s61
	s_add_i32 s61, s17, 1
	s_sub_i32 s62, s15, s16
	s_cmp_ge_u32 s15, s16
	s_cselect_b32 s17, s61, s17
	s_cselect_b32 s15, s62, s15
	s_add_i32 s61, s17, 1
	s_cmp_ge_u32 s15, s16
	s_cselect_b32 s15, s61, s17
	s_xor_b32 s15, s15, s13
	s_sub_i32 s13, s15, s13
	s_mul_i32 s12, s13, s12
	s_sub_i32 s4, s4, s12
	s_lshl_b32 s12, s4, 6
	s_lshl_b32 s4, s13, 6
	v_and_b32_e32 v0, 63, v1
	v_or_b32_e32 v4, s4, v0
	s_add_i32 s8, s7, -1
	v_cmp_gt_i32_e32 vcc, s7, v4
	v_min_i32_e32 v4, s8, v4
	v_ashrrev_i32_e32 v5, 31, v4
	v_lshl_add_u64 v[2:3], v[4:5], 2, v[2:3]
	v_add_u32_e32 v4, s12, v6
	v_mad_i64_i32 v[4:5], s[8:9], s7, v4, 0
	v_lshl_add_u64 v[4:5], v[4:5], 2, v[2:3]
	v_lshlrev_b32_e32 v0, 2, v0
	s_movk_i32 s13, 0x104
	v_mov_b32_e32 v28, s7
	v_mov_b32_e32 v29, 0
	v_lshlrev_b32_e32 v28, 4, v28
	v_mad_u32_u24 v30, v6, s13, v0
	global_load_dword v12, v[4:5], off nt
	v_lshl_add_u64 v[4:5], v[4:5], 0, v[28:29]
	global_load_dword v13, v[4:5], off nt
	v_lshl_add_u64 v[4:5], v[4:5], 0, v[28:29]
	global_load_dword v14, v[4:5], off nt
	v_lshl_add_u64 v[4:5], v[4:5], 0, v[28:29]
	global_load_dword v15, v[4:5], off nt
	v_lshl_add_u64 v[4:5], v[4:5], 0, v[28:29]
	global_load_dword v16, v[4:5], off nt
	v_lshl_add_u64 v[4:5], v[4:5], 0, v[28:29]
	global_load_dword v17, v[4:5], off nt
	v_lshl_add_u64 v[4:5], v[4:5], 0, v[28:29]
	global_load_dword v18, v[4:5], off nt
	v_lshl_add_u64 v[4:5], v[4:5], 0, v[28:29]
	global_load_dword v19, v[4:5], off nt
	v_lshl_add_u64 v[4:5], v[4:5], 0, v[28:29]
	global_load_dword v20, v[4:5], off nt
	v_lshl_add_u64 v[4:5], v[4:5], 0, v[28:29]
	global_load_dword v21, v[4:5], off nt
	v_lshl_add_u64 v[4:5], v[4:5], 0, v[28:29]
	global_load_dword v22, v[4:5], off nt
	v_lshl_add_u64 v[4:5], v[4:5], 0, v[28:29]
	global_load_dword v23, v[4:5], off nt
	v_lshl_add_u64 v[4:5], v[4:5], 0, v[28:29]
	global_load_dword v24, v[4:5], off nt
	v_lshl_add_u64 v[4:5], v[4:5], 0, v[28:29]
	global_load_dword v25, v[4:5], off nt
	v_lshl_add_u64 v[4:5], v[4:5], 0, v[28:29]
	global_load_dword v26, v[4:5], off nt
	v_lshl_add_u64 v[4:5], v[4:5], 0, v[28:29]
	global_load_dword v27, v[4:5], off nt
	s_waitcnt vmcnt(15)
	v_cndmask_b32_e32 v31, 0, v12, vcc
	ds_write_b32 v30, v31
	s_waitcnt vmcnt(14)
	v_cndmask_b32_e32 v32, 0, v13, vcc
	ds_write_b32 v30, v32 offset:1040
	s_waitcnt vmcnt(13)
	v_cndmask_b32_e32 v31, 0, v14, vcc
	ds_write_b32 v30, v31 offset:2080
	s_waitcnt vmcnt(12)
	v_cndmask_b32_e32 v32, 0, v15, vcc
	ds_write_b32 v30, v32 offset:3120
	s_waitcnt vmcnt(11)
	v_cndmask_b32_e32 v31, 0, v16, vcc
	ds_write_b32 v30, v31 offset:4160
	s_waitcnt vmcnt(10)
	v_cndmask_b32_e32 v32, 0, v17, vcc
	ds_write_b32 v30, v32 offset:5200
	s_waitcnt vmcnt(9)
	v_cndmask_b32_e32 v31, 0, v18, vcc
	ds_write_b32 v30, v31 offset:6240
	s_waitcnt vmcnt(8)
	v_cndmask_b32_e32 v32, 0, v19, vcc
	ds_write_b32 v30, v32 offset:7280
	s_waitcnt vmcnt(7)
	v_cndmask_b32_e32 v31, 0, v20, vcc
	ds_write_b32 v30, v31 offset:8320
	s_waitcnt vmcnt(6)
	v_cndmask_b32_e32 v32, 0, v21, vcc
	ds_write_b32 v30, v32 offset:9360
	s_waitcnt vmcnt(5)
	v_cndmask_b32_e32 v31, 0, v22, vcc
	ds_write_b32 v30, v31 offset:10400
	s_waitcnt vmcnt(4)
	v_cndmask_b32_e32 v32, 0, v23, vcc
	ds_write_b32 v30, v32 offset:11440
	s_waitcnt vmcnt(3)
	v_cndmask_b32_e32 v31, 0, v24, vcc
	ds_write_b32 v30, v31 offset:12480
	s_waitcnt vmcnt(2)
	v_cndmask_b32_e32 v32, 0, v25, vcc
	ds_write_b32 v30, v32 offset:13520
	s_waitcnt vmcnt(1)
	v_cndmask_b32_e32 v31, 0, v26, vcc
	ds_write_b32 v30, v31 offset:14560
	s_waitcnt vmcnt(0)
	v_cndmask_b32_e32 v32, 0, v27, vcc
	ds_write_b32 v30, v32 offset:15600
	v_add_u32_e32 v4, 0x100, v1
	v_lshlrev_b32_e32 v0, 3, v1
	v_and_b32_e32 v5, 56, v0
	v_mul_u32_u24_e32 v10, 0x104, v5
	v_lshl_add_u32 v6, v11, 2, v10
	s_waitcnt lgkmcnt(0)
	s_barrier
	ds_read2_b32 v[0:1], v6 offset1:65
	ds_read2_b32 v[2:3], v6 offset0:130 offset1:195
	v_add_u32_e32 v8, 0x400, v6
	ds_read2_b32 v[6:7], v8 offset0:4 offset1:69
	ds_read2_b32 v[8:9], v8 offset0:134 offset1:199
	s_ashr_i32 s13, s12, 31
	s_waitcnt lgkmcnt(3)
	v_cvt_pk_bf16_f32 v0, v0, v1
	s_waitcnt lgkmcnt(2)
	v_cvt_pk_bf16_f32 v1, v2, v3
	s_waitcnt lgkmcnt(1)
	v_cvt_pk_bf16_f32 v2, v6, v7
	v_add_u32_e32 v6, s4, v11
	v_mad_i64_i32 v[6:7], s[8:9], s6, v6, 0
	v_lshl_add_u64 v[6:7], v[6:7], 1, s[10:11]
	s_lshl_b64 s[8:9], s[12:13], 1
	v_lshl_add_u64 v[6:7], v[6:7], 0, s[8:9]
	v_lshlrev_b32_e32 v134, 1, v5
	s_waitcnt lgkmcnt(0)
	v_cvt_pk_bf16_f32 v3, v8, v9
	v_lshl_add_u64 v[6:7], v[6:7], 0, v[134:135]
	v_ashrrev_i32_e32 v8, 3, v4
	global_store_dwordx4 v[6:7], v[0:3], off
	v_lshl_add_u32 v4, v8, 2, v10
	ds_read2_b32 v[0:1], v4 offset1:65
	ds_read2_b32 v[2:3], v4 offset0:130 offset1:195
	v_add_u32_e32 v6, 0x400, v4
	ds_read2_b32 v[4:5], v6 offset0:4 offset1:69
	ds_read2_b32 v[6:7], v6 offset0:134 offset1:199
	s_waitcnt lgkmcnt(3)
	v_cvt_pk_bf16_f32 v0, v0, v1
	s_waitcnt lgkmcnt(2)
	v_cvt_pk_bf16_f32 v1, v2, v3
	s_waitcnt lgkmcnt(1)
	v_cvt_pk_bf16_f32 v2, v4, v5
	v_add_u32_e32 v4, s4, v8
	v_mad_i64_i32 v[4:5], s[6:7], s6, v4, 0
	v_lshl_add_u64 v[4:5], v[4:5], 1, s[10:11]
	v_lshl_add_u64 v[4:5], v[4:5], 0, s[8:9]
	s_waitcnt lgkmcnt(0)
	v_cvt_pk_bf16_f32 v3, v6, v7
	v_lshl_add_u64 v[4:5], v[4:5], 0, v[134:135]
	v_readlane_b32 s4, v230, 9
	global_store_dwordx4 v[4:5], v[0:3], off
	s_add_i32 s14, s4, s14

; __device__ __forceinline__ uint2 pack4(float a, float b, float c, float d) { return make_uint2(pack2(a, b), pack2(c, d)); }
; __device__ __forceinline__ int ltid() { int t = threadIdx.x; asm volatile("" : "+v"(t)); return t; }
; __device__ __forceinline__ void norm_rows(const float* in, const float* gain, u16* outb, int nrows, int job0w, int jstridew) {
;   const int lane = ltid() & 63;
;   for (int r = job0w; r < nrows; r += jstridew) {
;     const float4* ip = (const float4*)(in + (size_t)r * 1024);
;     float4 v[4];
;     float ss = 0.f;
; #pragma unroll
;     for (int i = 0; i < 4; i++) {
;       { const f32x4 t_ = __builtin_nontemporal_load((const f32x4*)ip + lane + i * 64); v[i] = make_float4(t_[0], t_[1], t_[2], t_[3]); }
;       ss += v[i].x * v[i].x + v[i].y * v[i].y + v[i].z * v[i].z + v[i].w * v[i].w;
;     }
;     ss = wave_sum(ss);
;     float sc = rsqrtf(ss * (1.f / 1024.f) + 1e-6f);
; #pragma unroll
;     for (int i = 0; i < 4; i++) {
;       float4 g = ((const float4*)gain)[lane + i * 64];
;       *(uint2*)(outb + (size_t)r * 1024 + (lane + i * 64) * 4) =
;           pack4(v[i].x * sc * g.x, v[i].y * sc * g.y, v[i].z * sc * g.z, v[i].w * sc * g.w);
;     }
.LBB0_187:
	s_andn2_b64 vcc, exec, s[6:7]
	s_movk_i32 s56, 0x1600
	v_readlane_b32 s16, v229, 33
	v_readlane_b32 s17, v229, 34
	s_cbranch_vccnz .LBB0_202
	s_movk_i32 s4, 0x400
	v_mov_b32_e32 v0, v132
	v_cmp_gt_i32_e32 vcc, s4, v142
	s_and_saveexec_b64 s[6:7], vcc
	v_readlane_b32 s10, v229, 5
	v_readlane_b32 s12, v229, 1
	v_readlane_b32 s14, v229, 7
	s_mov_b32 s4, s10
	s_movk_i32 s10, 0x3ff
	v_readlane_b32 s13, v229, 2
	v_readlane_b32 s15, v229, 8
	v_readlane_b32 s11, v229, 6
	s_cbranch_execz .LBB0_191
	v_and_b32_e32 v2, 63, v0
	v_lshlrev_b32_e32 v134, 4, v2
	v_readlane_b32 s8, v230, 22
	v_readlane_b32 s9, v230, 23
	v_or_b32_e32 v0, 0x400, v134
	v_mov_b32_e32 v1, v135
	v_lshl_add_u64 v[18:19], s[8:9], 0, v[0:1]
	v_or_b32_e32 v0, 0x800, v134
	v_lshl_add_u64 v[20:21], s[8:9], 0, v[0:1]
	v_or_b32_e32 v0, 0xc00, v134
	v_ashrrev_i32_e32 v143, 31, v142
	v_lshl_add_u64 v[16:17], s[8:9], 0, v[134:135]
	v_lshl_add_u64 v[22:23], s[8:9], 0, v[0:1]
	v_lshlrev_b64 v[0:1], 11, v[142:143]
	v_readlane_b32 s8, v230, 63
	v_lshl_or_b32 v0, v2, 3, v0
	v_readlane_b32 s9, v229, 0
	v_mov_b32_e32 v28, v142
	s_nop 0
	v_lshl_add_u64 v[24:25], s[8:9], 0, v[0:1]
	v_lshlrev_b64 v[0:1], 12, v[142:143]
	v_readlane_b32 s8, v229, 3
	v_or_b32_e32 v0, v0, v134
	v_readlane_b32 s9, v229, 4
	s_nop 1
	v_lshl_add_u64 v[26:27], s[8:9], 0, v[0:1]
	s_mov_b64 s[8:9], 0
	global_load_dwordx4 v[152:155], v[16:17], off
	global_load_dwordx4 v[156:159], v[18:19], off
	global_load_dwordx4 v[160:163], v[20:21], off
	global_load_dwordx4 v[164:167], v[22:23], off
	global_load_dwordx4 v[0:3], v[26:27], off offset:-3072 nt
	global_load_dwordx4 v[4:7], v[26:27], off offset:-2048 nt
	global_load_dwordx4 v[8:11], v[26:27], off offset:-1024 nt
	global_load_dwordx4 v[12:15], v[26:27], off nt
	s_waitcnt vmcnt(0)
.LBB0_190:
	v_add_u32_e32 v28, s4, v28
	v_cmp_lt_i32_e32 vcc, s10, v28
	s_or_b64 s[8:9], vcc, s[8:9]
	s_cbranch_vccnz .Lnr2_npa
	v_lshl_add_u64 v[26:27], v[26:27], 0, s[14:15]
	global_load_dwordx4 v[168:171], v[26:27], off offset:-3072 nt
	global_load_dwordx4 v[172:175], v[26:27], off offset:-2048 nt
	global_load_dwordx4 v[176:179], v[26:27], off offset:-1024 nt
	global_load_dwordx4 v[180:183], v[26:27], off nt
	s_waitcnt vmcnt(8)
	s_branch .Lnr2_ja
.Lnr2_npa:
	s_waitcnt vmcnt(4)
.Lnr2_ja:
	v_mul_f32_e32 v144, v1, v1
	v_mul_f32_e32 v145, v5, v5
	v_mul_f32_e32 v146, v9, v9
	v_mul_f32_e32 v147, v13, v13
	v_fmac_f32_e32 v144, v0, v0
	v_fmac_f32_e32 v145, v4, v4
	v_fmac_f32_e32 v146, v8, v8
	v_fmac_f32_e32 v147, v12, v12
	v_fmac_f32_e32 v144, v2, v2
	v_fmac_f32_e32 v145, v6, v6
	v_fmac_f32_e32 v146, v10, v10
	v_fmac_f32_e32 v147, v14, v14
	v_fmac_f32_e32 v144, v3, v3
	v_fmac_f32_e32 v145, v7, v7
	v_fmac_f32_e32 v146, v11, v11
	v_fmac_f32_e32 v147, v15, v15
	v_add_f32_e32 v148, v144, v145
	v_add_f32_e32 v148, v148, v146
	v_add_f32_e32 v148, v148, v147
	s_nop 1
	v_add_f32_dpp v148, v148, v148 quad_perm:[1,0,3,2] row_mask:0xf bank_mask:0xf bound_ctrl:1
	s_nop 1
	v_add_f32_dpp v148, v148, v148 quad_perm:[2,3,0,1] row_mask:0xf bank_mask:0xf bound_ctrl:1
	s_nop 1
	v_add_f32_dpp v148, v148, v148 row_half_mirror row_mask:0xf bank_mask:0xf bound_ctrl:1
	s_nop 1
	v_add_f32_dpp v148, v148, v148 row_mirror row_mask:0xf bank_mask:0xf bound_ctrl:1
	v_mov_b32_e32 v149, v148
	s_nop 1
	v_permlane16_swap_b32_e32 v148, v149
	v_add_f32_e32 v148, v148, v149
	v_mov_b32_e32 v149, v148
	s_nop 1
	v_permlane32_swap_b32_e32 v148, v149
	v_add_f32_e32 v148, v148, v149
	v_fmamk_f32 v148, v148, 0x3a800000, v136
	v_cmp_gt_f32_e32 vcc, s85, v148
	v_mul_f32_e32 v149, 0x4b800000, v148
	s_nop 0
	v_cndmask_b32_e32 v148, v148, v149, vcc
	v_rsq_f32_e32 v148, v148
	s_nop 0
	v_mul_f32_e32 v149, 0x45800000, v148
	v_cndmask_b32_e32 v150, v148, v149, vcc
	s_nop 0
	v_pk_mul_f32 v[0:1], v[0:1], v[150:151] op_sel_hi:[1,0]
	v_pk_mul_f32 v[2:3], v[2:3], v[150:151] op_sel_hi:[1,0]
	v_pk_mul_f32 v[4:5], v[4:5], v[150:151] op_sel_hi:[1,0]
	v_pk_mul_f32 v[6:7], v[6:7], v[150:151] op_sel_hi:[1,0]
	v_pk_mul_f32 v[8:9], v[8:9], v[150:151] op_sel_hi:[1,0]
	v_pk_mul_f32 v[10:11], v[10:11], v[150:151] op_sel_hi:[1,0]
	v_pk_mul_f32 v[12:13], v[12:13], v[150:151] op_sel_hi:[1,0]
	v_pk_mul_f32 v[14:15], v[14:15], v[150:151] op_sel_hi:[1,0]
	v_pk_mul_f32 v[0:1], v[152:153], v[0:1]
	v_pk_mul_f32 v[2:3], v[154:155], v[2:3]
	v_pk_mul_f32 v[4:5], v[156:157], v[4:5]
	v_pk_mul_f32 v[6:7], v[158:159], v[6:7]
	v_pk_mul_f32 v[8:9], v[160:161], v[8:9]
	v_pk_mul_f32 v[10:11], v[162:163], v[10:11]
	v_pk_mul_f32 v[12:13], v[164:165], v[12:13]
	v_pk_mul_f32 v[14:15], v[166:167], v[14:15]
	v_cvt_pk_bf16_f32 v0, v0, v1
	v_cvt_pk_bf16_f32 v1, v2, v3
	v_cvt_pk_bf16_f32 v4, v4, v5
	v_cvt_pk_bf16_f32 v5, v6, v7
	v_cvt_pk_bf16_f32 v8, v8, v9
	v_cvt_pk_bf16_f32 v9, v10, v11
	v_cvt_pk_bf16_f32 v12, v12, v13
	v_cvt_pk_bf16_f32 v13, v14, v15
	global_store_dwordx2 v[24:25], v[0:1], off offset:-1024
	global_store_dwordx2 v[24:25], v[4:5], off offset:-512
	global_store_dwordx2 v[24:25], v[8:9], off
	global_store_dwordx2 v[24:25], v[12:13], off offset:512
	v_lshl_add_u64 v[24:25], v[24:25], 0, s[12:13]
	s_andn2_b64 exec, exec, s[8:9]
	s_cbranch_execz .Lnr2_done
	v_add_u32_e32 v28, s4, v28
	v_cmp_lt_i32_e32 vcc, s10, v28
	s_or_b64 s[8:9], vcc, s[8:9]
	s_cbranch_vccnz .Lnr2_npb
	v_lshl_add_u64 v[26:27], v[26:27], 0, s[14:15]
	global_load_dwordx4 v[0:3], v[26:27], off offset:-3072 nt
	global_load_dwordx4 v[4:7], v[26:27], off offset:-2048 nt
	global_load_dwordx4 v[8:11], v[26:27], off offset:-1024 nt
	global_load_dwordx4 v[12:15], v[26:27], off nt
	s_waitcnt vmcnt(8)
	s_branch .Lnr2_jb

; __device__ __forceinline__ uint2 pack4(float a, float b, float c, float d) { return make_uint2(pack2(a, b), pack2(c, d)); }
; __device__ __forceinline__ void norm_rows(const float* in, const float* gain, u16* outb, int nrows, int job0w, int jstridew) {
;     ...
;     float ss = 0.f;
; #pragma unroll
;     for (int i = 0; i < 4; i++) {
;       { const f32x4 t_ = __builtin_nontemporal_load((const f32x4*)ip + lane + i * 64); v[i] = make_float4(t_[0], t_[1], t_[2], t_[3]); }
;       ss += v[i].x * v[i].x + v[i].y * v[i].y + v[i].z * v[i].z + v[i].w * v[i].w;
;     }
;     ss = wave_sum(ss);
;     float sc = rsqrtf(ss * (1.f / 1024.f) + 1e-6f);
; #pragma unroll
;     for (int i = 0; i < 4; i++) {
;       float4 g = ((const float4*)gain)[lane + i * 64];
;       *(uint2*)(outb + (size_t)r * 1024 + (lane + i * 64) * 4) =
;           pack4(v[i].x * sc * g.x, v[i].y * sc * g.y, v[i].z * sc * g.z, v[i].w * sc * g.w);
;     }
.Lnr2_jb:
	v_mul_f32_e32 v144, v169, v169
	v_mul_f32_e32 v145, v173, v173
	v_mul_f32_e32 v146, v177, v177
	v_mul_f32_e32 v147, v181, v181
	v_fmac_f32_e32 v144, v168, v168
	v_fmac_f32_e32 v145, v172, v172
	v_fmac_f32_e32 v146, v176, v176
	v_fmac_f32_e32 v147, v180, v180
	v_fmac_f32_e32 v144, v170, v170
	v_fmac_f32_e32 v145, v174, v174
	v_fmac_f32_e32 v146, v178, v178
	v_fmac_f32_e32 v147, v182, v182
	v_fmac_f32_e32 v144, v171, v171
	v_fmac_f32_e32 v145, v175, v175
	v_fmac_f32_e32 v146, v179, v179
	v_fmac_f32_e32 v147, v183, v183
	v_add_f32_e32 v148, v144, v145
	v_add_f32_e32 v148, v148, v146
	v_add_f32_e32 v148, v148, v147
	s_nop 1
	v_add_f32_dpp v148, v148, v148 quad_perm:[1,0,3,2] row_mask:0xf bank_mask:0xf bound_ctrl:1
	s_nop 1
	v_add_f32_dpp v148, v148, v148 quad_perm:[2,3,0,1] row_mask:0xf bank_mask:0xf bound_ctrl:1
	s_nop 1
	v_add_f32_dpp v148, v148, v148 row_half_mirror row_mask:0xf bank_mask:0xf bound_ctrl:1
	s_nop 1
	v_add_f32_dpp v148, v148, v148 row_mirror row_mask:0xf bank_mask:0xf bound_ctrl:1
	v_mov_b32_e32 v149, v148
	s_nop 1
	v_permlane16_swap_b32_e32 v148, v149
	v_add_f32_e32 v148, v148, v149
	v_mov_b32_e32 v149, v148
	s_nop 1
	v_permlane32_swap_b32_e32 v148, v149
	v_add_f32_e32 v148, v148, v149
	v_fmamk_f32 v148, v148, 0x3a800000, v136
	v_cmp_gt_f32_e32 vcc, s85, v148
	v_mul_f32_e32 v149, 0x4b800000, v148
	s_nop 0
	v_cndmask_b32_e32 v148, v148, v149, vcc
	v_rsq_f32_e32 v148, v148
	s_nop 0
	v_mul_f32_e32 v149, 0x45800000, v148
	v_cndmask_b32_e32 v150, v148, v149, vcc
	s_nop 0
	v_pk_mul_f32 v[168:169], v[168:169], v[150:151] op_sel_hi:[1,0]
	v_pk_mul_f32 v[170:171], v[170:171], v[150:151] op_sel_hi:[1,0]
	v_pk_mul_f32 v[172:173], v[172:173], v[150:151] op_sel_hi:[1,0]
	v_pk_mul_f32 v[174:175], v[174:175], v[150:151] op_sel_hi:[1,0]
	v_pk_mul_f32 v[176:177], v[176:177], v[150:151] op_sel_hi:[1,0]
	v_pk_mul_f32 v[178:179], v[178:179], v[150:151] op_sel_hi:[1,0]
	v_pk_mul_f32 v[180:181], v[180:181], v[150:151] op_sel_hi:[1,0]
	v_pk_mul_f32 v[182:183], v[182:183], v[150:151] op_sel_hi:[1,0]
	v_pk_mul_f32 v[168:169], v[152:153], v[168:169]
	v_pk_mul_f32 v[170:171], v[154:155], v[170:171]
	v_pk_mul_f32 v[172:173], v[156:157], v[172:173]
	v_pk_mul_f32 v[174:175], v[158:159], v[174:175]
	v_pk_mul_f32 v[176:177], v[160:161], v[176:177]
	v_pk_mul_f32 v[178:179], v[162:163], v[178:179]
	v_pk_mul_f32 v[180:181], v[164:165], v[180:181]
	v_pk_mul_f32 v[182:183], v[166:167], v[182:183]
	v_cvt_pk_bf16_f32 v168, v168, v169
	v_cvt_pk_bf16_f32 v169, v170, v171
	v_cvt_pk_bf16_f32 v172, v172, v173
	v_cvt_pk_bf16_f32 v173, v174, v175
	v_cvt_pk_bf16_f32 v176, v176, v177
	v_cvt_pk_bf16_f32 v177, v178, v179
	v_cvt_pk_bf16_f32 v180, v180, v181
	v_cvt_pk_bf16_f32 v181, v182, v183
	global_store_dwordx2 v[24:25], v[168:169], off offset:-1024
	global_store_dwordx2 v[24:25], v[172:173], off offset:-512
	global_store_dwordx2 v[24:25], v[176:177], off
	global_store_dwordx2 v[24:25], v[180:181], off offset:512
	v_lshl_add_u64 v[24:25], v[24:25], 0, s[12:13]
	s_andn2_b64 exec, exec, s[8:9]
	s_cbranch_execnz .LBB0_190
.Lnr2_done:
.LBB0_191:
	s_or_b64 exec, exec, s[6:7]
	s_cmpk_gt_i32 s16, 0x57f
	s_cbranch_scc1 .LBB0_202
	s_lshl_b32 s4, s16, 1
	s_lshl_b32 s12, s16, 8
	s_mov_b32 s13, s16
	s_waitcnt vmcnt(0)
	s_branch .LBB0_194

; __device__ __forceinline__ uint2 pack4(float a, float b, float c, float d) { return make_uint2(pack2(a, b), pack2(c, d)); }
; __device__ __forceinline__ float frcp(float x) { return __builtin_amdgcn_rcpf(x); }
; __device__ __forceinline__ float sigmoidf_(float x) { return frcp(1.f + __expf(-x)); }
; __device__ __forceinline__ float gelu_tanh(float x) {
;   const float u2 = 1.5957691216057308f * (x + 0.044715f * x * x * x);
;   return x * frcp(1.f + __expf(-u2));
; }
; __global__ void __launch_bounds__(NTHR, 2) mega(P p, int ph_lo, int ph_hi) {
;     ...
;         auto f = [=] __device__(int m, int n, const f32x4& a, int) {
;           float4 y = *(const float4*)(ybuf + (size_t)m * 512 + n);
;           float4 bg = *(const float4*)(p.s5_bglu + n);
;           *(uint2*)(p.A + (size_t)m * 1024 + 512 + n) =
;               pack4(gelu_tanh(y.x) * sigmoidf_(a[0] + bg.x), gelu_tanh(y.y) * sigmoidf_(a[1] + bg.y),
;                     gelu_tanh(y.z) * sigmoidf_(a[2] + bg.z), gelu_tanh(y.w) * sigmoidf_(a[3] + bg.w));
;         };
.LBB0_334:
	s_waitcnt vmcnt(0)
	v_or_b32_e32 v61, s11, v109
	v_lshlrev_b32_e32 v60, 6, v108
	s_nop 0
	v_lshl_add_u32 v70, v107, 6, v61
	v_and_b32_e32 v61, 12, v106
	v_or3_b32 v68, v60, v61, s10
	v_ashrrev_i32_e32 v71, 31, v70
	v_ashrrev_i32_e32 v69, 31, v68
	s_nop 0
	v_lshlrev_b64 v[78:79], 11, v[70:71]
	v_lshl_add_u64 v[60:61], s[2:3], 0, v[78:79]
	v_lshlrev_b64 v[72:73], 2, v[68:69]
	v_lshl_add_u64 v[66:67], v[60:61], 0, v[72:73]
	global_load_dwordx4 v[144:147], v[66:67], off
	global_load_dwordx4 v[168:171], v[66:67], off offset:64
	global_load_dwordx4 v[188:191], v[66:67], off offset:128
	global_load_dwordx4 v[248:251], v[66:67], off offset:192
	s_nop 0
	s_load_dwordx2 s[8:9], s[0:1], 0xb0
	v_lshlrev_b64 v[68:69], 1, v[68:69]
	s_add_i32 s4, s4, s82
	s_cmpk_gt_i32 s4, 0x1ff
	s_waitcnt lgkmcnt(0)
	v_lshl_add_u64 v[60:61], s[8:9], 0, v[72:73]
	global_load_dwordx4 v[148:151], v[60:61], off
	global_load_dwordx4 v[152:155], v[60:61], off
	global_load_dwordx4 v[156:159], v[60:61], off
	global_load_dwordx4 v[160:163], v[60:61], off
	global_load_dwordx4 v[164:167], v[60:61], off offset:64
	global_load_dwordx4 v[172:175], v[60:61], off offset:64
	global_load_dwordx4 v[176:179], v[60:61], off offset:64
	global_load_dwordx4 v[180:183], v[60:61], off offset:64
	global_load_dwordx4 v[184:187], v[60:61], off offset:128
	global_load_dwordx4 v[192:195], v[60:61], off offset:128
	global_load_dwordx4 v[224:227], v[60:61], off offset:128
	global_load_dwordx4 v[236:239], v[60:61], off offset:128
	global_load_dwordx4 v[244:247], v[60:61], off offset:192
	global_load_dwordx4 v[252:255], v[60:61], off offset:192
	s_nop 0
	s_nop 0
	s_waitcnt vmcnt(17)
	v_mul_f32_e32 v71, 0x3d372713, v144
	v_mul_f32_e32 v71, v144, v71
	v_fma_f32 v71, v144, v71, v144
	v_mul_f32_e32 v71, 0xbfcc422a, v71
	v_mul_f32_e32 v71, 0x3fb8aa3b, v71
	v_exp_f32_e32 v71, v71
	s_nop 0
	s_waitcnt vmcnt(13)
	v_add_f32_e32 v148, v92, v148
	v_add_f32_e32 v149, v93, v149
	v_add_f32_e32 v71, 1.0, v71
	v_rcp_f32_e32 v80, v71
	v_mul_f32_e32 v71, 0x3d372713, v145
	v_mul_f32_e32 v71, v145, v71
	v_fma_f32 v71, v145, v71, v145
	v_mul_f32_e32 v71, 0xbfcc422a, v71
	v_mul_f32_e32 v71, 0x3fb8aa3b, v71
	v_exp_f32_e32 v71, v71
	v_mul_f32_e32 v148, 0xbfb8aa3b, v148
	v_mul_f32_e32 v149, 0xbfb8aa3b, v149
	v_exp_f32_e32 v148, v148
	v_add_f32_e32 v71, 1.0, v71
	v_rcp_f32_e32 v81, v71
	v_mul_f32_e32 v71, 0x3d372713, v146
	v_exp_f32_e32 v149, v149
	v_mul_f32_e32 v71, v146, v71
	v_fma_f32 v71, v146, v71, v146
	v_mul_f32_e32 v71, 0xbfcc422a, v71
	v_mul_f32_e32 v71, 0x3fb8aa3b, v71
	v_add_f32_e32 v148, 1.0, v148
	v_add_f32_e32 v149, 1.0, v149
	v_exp_f32_e32 v71, v71
	v_rcp_f32_e32 v148, v148
	v_rcp_f32_e32 v149, v149
	v_pk_mul_f32 v[144:145], v[144:145], v[80:81]
	v_add_f32_e32 v71, 1.0, v71
	v_add_f32_e32 v150, v94, v150
	v_pk_mul_f32 v[148:149], v[148:149], v[144:145]
	v_rcp_f32_e32 v74, v71
	v_mul_f32_e32 v71, 0x3d372713, v147
	v_mul_f32_e32 v71, v147, v71
	v_mov_b32_e32 v75, v147
	v_fmac_f32_e32 v75, v75, v71
	v_mul_f32_e32 v71, 0xbfcc422a, v75
	v_add_f32_e32 v151, v95, v151
	v_mul_f32_e32 v71, 0x3fb8aa3b, v71
	v_mul_f32_e32 v150, 0xbfb8aa3b, v150
	v_mul_f32_e32 v151, 0xbfb8aa3b, v151
	v_exp_f32_e32 v71, v71
	v_exp_f32_e32 v150, v150
	v_exp_f32_e32 v151, v151
	v_add_f32_e32 v71, 1.0, v71
	v_add_f32_e32 v150, 1.0, v150
	v_add_f32_e32 v151, 1.0, v151
	v_rcp_f32_e32 v75, v71
	v_rcp_f32_e32 v150, v150
	v_rcp_f32_e32 v151, v151
	v_pk_mul_f32 v[74:75], v[146:147], v[74:75]
	s_nop 0
	v_pk_mul_f32 v[150:151], v[150:151], v[74:75]
	v_cvt_pk_bf16_f32 v74, v148, v149
	v_cvt_pk_bf16_f32 v75, v150, v151
	v_lshl_add_u64 v[62:63], s[30:31], 0, v[78:79]
	v_or_b32_e32 v64, 16, v70
	v_lshl_add_u64 v[62:63], v[62:63], 0, v[68:69]
	v_ashrrev_i32_e32 v65, 31, v64
	global_store_dwordx2 v[62:63], v[74:75], off offset:1024
	v_lshlrev_b64 v[74:75], 11, v[64:65]
	v_lshl_add_u64 v[64:65], s[2:3], 0, v[74:75]
	v_lshl_add_u64 v[64:65], v[64:65], 0, v[72:73]
	global_load_dwordx4 v[144:147], v[64:65], off
	global_load_dwordx4 v[148:151], v[64:65], off offset:64
	global_load_dwordx4 v[220:223], v[64:65], off offset:128
	s_nop 0
	s_nop 0
	s_nop 0
	s_waitcnt vmcnt(2)
	v_mul_f32_e32 v71, 0x3d372713, v144
	v_mul_f32_e32 v71, v144, v71
	v_fma_f32 v71, v144, v71, v144
	v_mul_f32_e32 v71, 0xbfcc422a, v71
	v_mul_f32_e32 v71, 0x3fb8aa3b, v71
	v_exp_f32_e32 v71, v71
	s_nop 0
	v_add_f32_e32 v56, v56, v152
	v_add_f32_e32 v57, v57, v153
	v_mul_f32_e32 v56, 0xbfb8aa3b, v56
	v_add_f32_e32 v71, 1.0, v71
	v_rcp_f32_e32 v76, v71
	v_mul_f32_e32 v71, 0x3d372713, v145
	v_mul_f32_e32 v71, v145, v71
	v_fma_f32 v71, v145, v71, v145
	v_mul_f32_e32 v71, 0xbfcc422a, v71
	v_mul_f32_e32 v71, 0x3fb8aa3b, v71
	v_exp_f32_e32 v71, v71
	v_mul_f32_e32 v57, 0xbfb8aa3b, v57
	v_exp_f32_e32 v56, v56
	v_exp_f32_e32 v57, v57
	v_add_f32_e32 v71, 1.0, v71
	v_rcp_f32_e32 v77, v71
	v_mul_f32_e32 v71, 0x3d372713, v146
	v_mul_f32_e32 v71, v146, v71
	v_fma_f32 v71, v146, v71, v146
	v_mul_f32_e32 v71, 0xbfcc422a, v71
	v_mul_f32_e32 v71, 0x3fb8aa3b, v71
	v_add_f32_e32 v56, 1.0, v56
	v_add_f32_e32 v57, 1.0, v57
	v_exp_f32_e32 v71, v71
	v_rcp_f32_e32 v56, v56
	v_rcp_f32_e32 v57, v57
	v_pk_mul_f32 v[76:77], v[144:145], v[76:77]
	v_add_f32_e32 v71, 1.0, v71
	v_add_f32_e32 v58, v58, v154
	v_pk_mul_f32 v[56:57], v[56:57], v[76:77]
	v_rcp_f32_e32 v76, v71
	v_mul_f32_e32 v71, 0x3d372713, v147
	v_mul_f32_e32 v71, v147, v71
	v_mov_b32_e32 v77, v147
	v_fmac_f32_e32 v77, v77, v71
	v_mul_f32_e32 v71, 0xbfcc422a, v77
	v_add_f32_e32 v59, v59, v155
	v_mul_f32_e32 v71, 0x3fb8aa3b, v71
	v_mul_f32_e32 v58, 0xbfb8aa3b, v58
	v_mul_f32_e32 v59, 0xbfb8aa3b, v59
	v_exp_f32_e32 v71, v71
	v_exp_f32_e32 v58, v58
	v_exp_f32_e32 v59, v59
	v_add_f32_e32 v71, 1.0, v71
	v_add_f32_e32 v58, 1.0, v58
	v_add_f32_e32 v59, 1.0, v59
	v_rcp_f32_e32 v77, v71
	v_rcp_f32_e32 v58, v58
	v_rcp_f32_e32 v59, v59
	v_pk_mul_f32 v[76:77], v[146:147], v[76:77]
	s_nop 0
	v_pk_mul_f32 v[58:59], v[58:59], v[76:77]
	s_nop 0
	v_cvt_pk_bf16_f32 v77, v58, v59
	v_or_b32_e32 v58, 32, v70
	v_ashrrev_i32_e32 v59, 31, v58
	v_cvt_pk_bf16_f32 v76, v56, v57
	v_lshl_add_u64 v[56:57], s[30:31], 0, v[74:75]
	v_lshlrev_b64 v[74:75], 11, v[58:59]
	v_lshl_add_u64 v[56:57], v[56:57], 0, v[68:69]
	v_lshl_add_u64 v[58:59], s[2:3], 0, v[74:75]
	global_store_dwordx2 v[56:57], v[76:77], off offset:1024
	v_lshl_add_u64 v[58:59], v[58:59], 0, v[72:73]
	global_load_dwordx4 v[144:147], v[58:59], off
	global_load_dwordx4 v[152:155], v[58:59], off offset:64
	global_load_dwordx4 v[232:235], v[58:59], off offset:128
	s_nop 0
	s_nop 0
	s_nop 0
	s_waitcnt vmcnt(2)
; __device__ __forceinline__ uint2 pack4(float a, float b, float c, float d) { return make_uint2(pack2(a, b), pack2(c, d)); }
; __device__ __forceinline__ float frcp(float x) { return __builtin_amdgcn_rcpf(x); }
; __device__ __forceinline__ float sigmoidf_(float x) { return frcp(1.f + __expf(-x)); }
; __device__ __forceinline__ float gelu_tanh(float x) {
;   const float u2 = 1.5957691216057308f * (x + 0.044715f * x * x * x);
;   return x * frcp(1.f + __expf(-u2));
; }
; __global__ void __launch_bounds__(NTHR, 2) mega(P p, int ph_lo, int ph_hi) {
;     ...
;         auto f = [=] __device__(int m, int n, const f32x4& a, int) {
;           float4 y = *(const float4*)(ybuf + (size_t)m * 512 + n);
;           float4 bg = *(const float4*)(p.s5_bglu + n);
;           *(uint2*)(p.A + (size_t)m * 1024 + 512 + n) =
;               pack4(gelu_tanh(y.x) * sigmoidf_(a[0] + bg.x), gelu_tanh(y.y) * sigmoidf_(a[1] + bg.y),
;                     gelu_tanh(y.z) * sigmoidf_(a[2] + bg.z), gelu_tanh(y.w) * sigmoidf_(a[3] + bg.w));
;         };
	v_mul_f32_e32 v71, 0x3d372713, v144
	v_mul_f32_e32 v71, v144, v71
	v_fma_f32 v71, v144, v71, v144
	v_mul_f32_e32 v71, 0xbfcc422a, v71
	v_mul_f32_e32 v71, 0x3fb8aa3b, v71
	v_exp_f32_e32 v71, v71
	s_nop 0
	v_add_f32_e32 v52, v52, v156
	v_add_f32_e32 v53, v53, v157
	v_mul_f32_e32 v52, 0xbfb8aa3b, v52
	v_add_f32_e32 v71, 1.0, v71
	v_rcp_f32_e32 v76, v71
	v_mul_f32_e32 v71, 0x3d372713, v145
	v_mul_f32_e32 v71, v145, v71
	v_fma_f32 v71, v145, v71, v145
	v_mul_f32_e32 v71, 0xbfcc422a, v71
	v_mul_f32_e32 v71, 0x3fb8aa3b, v71
	v_exp_f32_e32 v71, v71
	v_mul_f32_e32 v53, 0xbfb8aa3b, v53
	v_exp_f32_e32 v52, v52
	v_exp_f32_e32 v53, v53
	v_add_f32_e32 v71, 1.0, v71
	v_rcp_f32_e32 v77, v71
	v_mul_f32_e32 v71, 0x3d372713, v146
	v_mul_f32_e32 v71, v146, v71
	v_fma_f32 v71, v146, v71, v146
	v_mul_f32_e32 v71, 0xbfcc422a, v71
	v_mul_f32_e32 v71, 0x3fb8aa3b, v71
	v_add_f32_e32 v52, 1.0, v52
	v_add_f32_e32 v53, 1.0, v53
	v_exp_f32_e32 v71, v71
	v_rcp_f32_e32 v52, v52
	v_rcp_f32_e32 v53, v53
	v_pk_mul_f32 v[76:77], v[144:145], v[76:77]
	v_add_f32_e32 v71, 1.0, v71
	v_add_f32_e32 v54, v54, v158
	v_pk_mul_f32 v[52:53], v[52:53], v[76:77]
	v_rcp_f32_e32 v76, v71
	v_mul_f32_e32 v71, 0x3d372713, v147
	v_mul_f32_e32 v71, v147, v71
	v_mov_b32_e32 v77, v147
	v_fmac_f32_e32 v77, v77, v71
	v_mul_f32_e32 v71, 0xbfcc422a, v77
	v_add_f32_e32 v55, v55, v159
	v_mul_f32_e32 v71, 0x3fb8aa3b, v71
	v_mul_f32_e32 v54, 0xbfb8aa3b, v54
	v_mul_f32_e32 v55, 0xbfb8aa3b, v55
	v_exp_f32_e32 v71, v71
	v_exp_f32_e32 v54, v54
	v_exp_f32_e32 v55, v55
	v_add_f32_e32 v71, 1.0, v71
	v_add_f32_e32 v54, 1.0, v54
	v_add_f32_e32 v55, 1.0, v55
	v_rcp_f32_e32 v77, v71
	v_rcp_f32_e32 v54, v54
	v_rcp_f32_e32 v55, v55
	v_pk_mul_f32 v[76:77], v[146:147], v[76:77]
	v_mov_b32_e32 v80, v144
	v_mov_b32_e32 v81, v145
	v_mov_b32_e32 v82, v146
	v_mov_b32_e32 v83, v147
	s_nop 0
	v_pk_mul_f32 v[54:55], v[54:55], v[76:77]
	s_nop 0
	v_cvt_pk_bf16_f32 v77, v54, v55
	v_or_b32_e32 v54, 48, v70
	v_ashrrev_i32_e32 v55, 31, v54
	v_cvt_pk_bf16_f32 v76, v52, v53
	v_lshl_add_u64 v[52:53], s[30:31], 0, v[74:75]
	v_lshlrev_b64 v[70:71], 11, v[54:55]
	v_lshl_add_u64 v[52:53], v[52:53], 0, v[68:69]
	v_lshl_add_u64 v[54:55], s[2:3], 0, v[70:71]
	global_store_dwordx2 v[52:53], v[76:77], off offset:1024
	v_lshl_add_u64 v[54:55], v[54:55], 0, v[72:73]
	global_load_dwordx4 v[144:147], v[54:55], off
	global_load_dwordx4 v[156:159], v[54:55], off offset:64
	global_load_dwordx4 v[240:243], v[54:55], off offset:128
	s_nop 0
	s_nop 0
	s_nop 0
	v_add_f32_e32 v48, v48, v160
	v_add_f32_e32 v49, v49, v161
	s_nop 0
	s_waitcnt vmcnt(2)
	v_mul_f32_e32 v72, 0x3d372713, v144
	v_mul_f32_e32 v73, 0x3d372713, v145
	v_mul_f32_e32 v72, v144, v72
	v_mul_f32_e32 v73, v145, v73
	v_fma_f32 v72, v144, v72, v144
	v_fma_f32 v73, v145, v73, v145
	v_mul_f32_e32 v72, 0xbfcc422a, v72
	v_mul_f32_e32 v73, 0xbfcc422a, v73
	v_mul_f32_e32 v72, 0x3fb8aa3b, v72
	v_mul_f32_e32 v73, 0x3fb8aa3b, v73
	v_mul_f32_e32 v48, 0xbfb8aa3b, v48
	v_mul_f32_e32 v49, 0xbfb8aa3b, v49
	v_exp_f32_e32 v72, v72
	v_exp_f32_e32 v73, v73
	v_exp_f32_e32 v48, v48
	v_exp_f32_e32 v49, v49
	v_add_f32_e32 v72, 1.0, v72
	v_add_f32_e32 v73, 1.0, v73
	v_add_f32_e32 v48, 1.0, v48
	v_add_f32_e32 v49, 1.0, v49
	v_rcp_f32_e32 v72, v72
	v_rcp_f32_e32 v73, v73
	v_rcp_f32_e32 v48, v48
	v_rcp_f32_e32 v49, v49
	v_add_f32_e32 v50, v50, v162
	v_pk_mul_f32 v[72:73], v[144:145], v[72:73]
	v_mov_b32_e32 v74, v147
	v_pk_mul_f32 v[48:49], v[48:49], v[72:73]
	v_mul_f32_e32 v72, 0x3d372713, v146
	v_mul_f32_e32 v73, 0x3d372713, v147
	v_mul_f32_e32 v72, v146, v72
	v_mul_f32_e32 v73, v147, v73
	v_fma_f32 v72, v146, v72, v146
	v_fmac_f32_e32 v74, v74, v73
	v_mul_f32_e32 v72, 0xbfcc422a, v72
	v_mul_f32_e32 v73, 0xbfcc422a, v74
	v_add_f32_e32 v51, v51, v163
	v_mov_b32_e32 v75, v163
	v_mul_f32_e32 v72, 0x3fb8aa3b, v72
	v_mul_f32_e32 v73, 0x3fb8aa3b, v73
	v_mul_f32_e32 v50, 0xbfb8aa3b, v50
	v_mul_f32_e32 v51, 0xbfb8aa3b, v51
	v_exp_f32_e32 v72, v72
	v_exp_f32_e32 v73, v73
	v_exp_f32_e32 v50, v50
	v_exp_f32_e32 v51, v51
	v_add_f32_e32 v72, 1.0, v72
	v_add_f32_e32 v73, 1.0, v73
	v_add_f32_e32 v50, 1.0, v50
	v_add_f32_e32 v51, 1.0, v51
	v_rcp_f32_e32 v72, v72
	v_rcp_f32_e32 v73, v73
	v_rcp_f32_e32 v50, v50
	v_rcp_f32_e32 v51, v51
	v_cvt_pk_bf16_f32 v48, v48, v49
	v_pk_mul_f32 v[72:73], v[146:147], v[72:73]
	v_mov_b32_e32 v76, v144
	v_mov_b32_e32 v77, v145
	v_mov_b32_e32 v78, v146
	v_mov_b32_e32 v79, v147
	s_nop 0
	v_pk_mul_f32 v[50:51], v[50:51], v[72:73]
	s_nop 0
	v_cvt_pk_bf16_f32 v49, v50, v51
	v_lshl_add_u64 v[50:51], s[30:31], 0, v[70:71]
	v_lshl_add_u64 v[68:69], v[50:51], 0, v[68:69]
	global_store_dwordx2 v[68:69], v[48:49], off offset:1024
	s_nop 0
	s_nop 0
	v_add_f32_e32 v44, v44, v164
	s_nop 0
	v_add_f32_e32 v45, v45, v165
	v_mul_f32_e32 v44, 0xbfb8aa3b, v44
	v_mul_f32_e32 v45, 0xbfb8aa3b, v45
	v_exp_f32_e32 v44, v44
	v_exp_f32_e32 v45, v45
	v_add_f32_e32 v46, v46, v166
	v_add_f32_e32 v47, v47, v167
	v_mov_b32_e32 v72, v166
	v_mov_b32_e32 v73, v167
	v_add_f32_e32 v44, 1.0, v44
	v_add_f32_e32 v45, 1.0, v45
	v_rcp_f32_e32 v44, v44
	v_rcp_f32_e32 v45, v45
	v_mul_f32_e32 v46, 0xbfb8aa3b, v46
	v_mul_f32_e32 v47, 0xbfb8aa3b, v47
	v_exp_f32_e32 v46, v46
	v_exp_f32_e32 v47, v47
	v_add_f32_e32 v46, 1.0, v46
	v_add_f32_e32 v47, 1.0, v47
	v_rcp_f32_e32 v46, v46
	v_rcp_f32_e32 v47, v47
	s_nop 0
	v_mul_f32_e32 v70, 0x3d372713, v168
	v_mul_f32_e32 v71, 0x3d372713, v169
	v_mul_f32_e32 v70, v168, v70
	v_mul_f32_e32 v71, v169, v71
	v_fma_f32 v70, v168, v70, v168
	v_fma_f32 v71, v169, v71, v169
	v_mul_f32_e32 v70, 0xbfcc422a, v70
	v_mul_f32_e32 v71, 0xbfcc422a, v71
	v_mul_f32_e32 v70, 0x3fb8aa3b, v70
	v_mul_f32_e32 v71, 0x3fb8aa3b, v71
; __device__ __forceinline__ uint2 pack4(float a, float b, float c, float d) { return make_uint2(pack2(a, b), pack2(c, d)); }
; __device__ __forceinline__ float frcp(float x) { return __builtin_amdgcn_rcpf(x); }
; __device__ __forceinline__ float sigmoidf_(float x) { return frcp(1.f + __expf(-x)); }
; __device__ __forceinline__ float gelu_tanh(float x) {
;   const float u2 = 1.5957691216057308f * (x + 0.044715f * x * x * x);
;   return x * frcp(1.f + __expf(-u2));
; }
; __global__ void __launch_bounds__(NTHR, 2) mega(P p, int ph_lo, int ph_hi) {
;     ...
;         auto f = [=] __device__(int m, int n, const f32x4& a, int) {
;           float4 y = *(const float4*)(ybuf + (size_t)m * 512 + n);
;           float4 bg = *(const float4*)(p.s5_bglu + n);
;           *(uint2*)(p.A + (size_t)m * 1024 + 512 + n) =
;               pack4(gelu_tanh(y.x) * sigmoidf_(a[0] + bg.x), gelu_tanh(y.y) * sigmoidf_(a[1] + bg.y),
;                     gelu_tanh(y.z) * sigmoidf_(a[2] + bg.z), gelu_tanh(y.w) * sigmoidf_(a[3] + bg.w));
;         };
	v_exp_f32_e32 v70, v70
	v_exp_f32_e32 v71, v71
	v_add_f32_e32 v70, 1.0, v70
	v_add_f32_e32 v71, 1.0, v71
	v_rcp_f32_e32 v70, v70
	v_rcp_f32_e32 v71, v71
	s_nop 0
	v_pk_mul_f32 v[168:169], v[168:169], v[70:71]
	s_nop 0
	v_pk_mul_f32 v[44:45], v[44:45], v[168:169]
	v_mul_f32_e32 v48, 0x3d372713, v170
	v_mul_f32_e32 v49, 0x3d372713, v171
	v_mul_f32_e32 v48, v170, v48
	v_mul_f32_e32 v49, v171, v49
	v_mov_b32_e32 v70, v171
	v_fma_f32 v48, v170, v48, v170
	v_fmac_f32_e32 v70, v70, v49
	v_mul_f32_e32 v48, 0xbfcc422a, v48
	v_mul_f32_e32 v49, 0xbfcc422a, v70
	v_mul_f32_e32 v48, 0x3fb8aa3b, v48
	v_mul_f32_e32 v49, 0x3fb8aa3b, v49
	v_exp_f32_e32 v48, v48
	v_exp_f32_e32 v49, v49
	v_cvt_pk_bf16_f32 v44, v44, v45
	v_add_f32_e32 v48, 1.0, v48
	v_add_f32_e32 v49, 1.0, v49
	v_rcp_f32_e32 v48, v48
	v_rcp_f32_e32 v49, v49
	s_nop 0
	v_pk_mul_f32 v[48:49], v[170:171], v[48:49]
	s_nop 0
	v_pk_mul_f32 v[46:47], v[46:47], v[48:49]
	s_nop 0
	v_cvt_pk_bf16_f32 v45, v46, v47
	global_store_dwordx2 v[62:63], v[44:45], off offset:1056
	s_nop 0
	s_nop 0
	v_add_f32_e32 v40, v40, v172
	v_add_f32_e32 v41, v41, v173
	s_nop 0
	v_mul_f32_e32 v40, 0xbfb8aa3b, v40
	v_mul_f32_e32 v41, 0xbfb8aa3b, v41
	v_exp_f32_e32 v40, v40
	v_exp_f32_e32 v41, v41
	v_add_f32_e32 v42, v42, v174
	v_add_f32_e32 v43, v43, v175
	v_mov_b32_e32 v49, v175
	v_add_f32_e32 v40, 1.0, v40
	v_add_f32_e32 v41, 1.0, v41
	v_rcp_f32_e32 v40, v40
	v_rcp_f32_e32 v41, v41
	v_mul_f32_e32 v42, 0xbfb8aa3b, v42
	v_mul_f32_e32 v43, 0xbfb8aa3b, v43
	v_exp_f32_e32 v42, v42
	v_exp_f32_e32 v43, v43
	v_add_f32_e32 v42, 1.0, v42
	v_add_f32_e32 v43, 1.0, v43
	v_rcp_f32_e32 v42, v42
	v_rcp_f32_e32 v43, v43
	s_nop 0
	v_mul_f32_e32 v50, 0x3d372713, v148
	v_mul_f32_e32 v51, 0x3d372713, v149
	v_mul_f32_e32 v50, v148, v50
	v_mul_f32_e32 v51, v149, v51
	v_fma_f32 v50, v148, v50, v148
	v_fma_f32 v51, v149, v51, v149
	v_mul_f32_e32 v50, 0xbfcc422a, v50
	v_mul_f32_e32 v51, 0xbfcc422a, v51
	v_mul_f32_e32 v50, 0x3fb8aa3b, v50
	v_mul_f32_e32 v51, 0x3fb8aa3b, v51
	v_exp_f32_e32 v50, v50
	v_exp_f32_e32 v51, v51
	v_mov_b32_e32 v48, v151
	v_add_f32_e32 v50, 1.0, v50
	v_add_f32_e32 v51, 1.0, v51
	v_rcp_f32_e32 v50, v50
	v_rcp_f32_e32 v51, v51
	s_nop 0
	v_pk_mul_f32 v[148:149], v[148:149], v[50:51]
	s_nop 0
	v_pk_mul_f32 v[40:41], v[40:41], v[148:149]
	v_mul_f32_e32 v44, 0x3d372713, v150
	v_mul_f32_e32 v45, 0x3d372713, v151
	v_mul_f32_e32 v44, v150, v44
	v_mul_f32_e32 v45, v151, v45
	v_fma_f32 v44, v150, v44, v150
	v_fmac_f32_e32 v48, v48, v45
	v_mul_f32_e32 v44, 0xbfcc422a, v44
	v_mul_f32_e32 v45, 0xbfcc422a, v48
	v_mul_f32_e32 v44, 0x3fb8aa3b, v44
	v_mul_f32_e32 v45, 0x3fb8aa3b, v45
	v_exp_f32_e32 v44, v44
	v_exp_f32_e32 v45, v45
	v_cvt_pk_bf16_f32 v40, v40, v41
	v_add_f32_e32 v44, 1.0, v44
	v_add_f32_e32 v45, 1.0, v45
	v_rcp_f32_e32 v44, v44
	v_rcp_f32_e32 v45, v45
	s_nop 0
	v_pk_mul_f32 v[44:45], v[150:151], v[44:45]
	s_nop 0
	v_pk_mul_f32 v[42:43], v[42:43], v[44:45]
	s_nop 0
	v_cvt_pk_bf16_f32 v41, v42, v43
	global_store_dwordx2 v[56:57], v[40:41], off offset:1056
	s_nop 0
	s_nop 0
	v_add_f32_e32 v36, v36, v176
	v_add_f32_e32 v37, v37, v177
	s_nop 0
	v_mul_f32_e32 v36, 0xbfb8aa3b, v36
	v_mul_f32_e32 v37, 0xbfb8aa3b, v37
	v_exp_f32_e32 v36, v36
	v_exp_f32_e32 v37, v37
	v_add_f32_e32 v38, v38, v178
	v_add_f32_e32 v39, v39, v179
	v_mov_b32_e32 v45, v179
	v_add_f32_e32 v36, 1.0, v36
	v_add_f32_e32 v37, 1.0, v37
	v_rcp_f32_e32 v36, v36
	v_rcp_f32_e32 v37, v37
	v_mul_f32_e32 v38, 0xbfb8aa3b, v38
	v_mul_f32_e32 v39, 0xbfb8aa3b, v39
	v_exp_f32_e32 v38, v38
	v_exp_f32_e32 v39, v39
	v_add_f32_e32 v38, 1.0, v38
	v_add_f32_e32 v39, 1.0, v39
	v_rcp_f32_e32 v38, v38
	v_rcp_f32_e32 v39, v39
	s_nop 0
	v_mul_f32_e32 v46, 0x3d372713, v152
	v_mul_f32_e32 v47, 0x3d372713, v153
	v_mul_f32_e32 v46, v152, v46
	v_mul_f32_e32 v47, v153, v47
	v_fma_f32 v46, v152, v46, v152
	v_fma_f32 v47, v153, v47, v153
	v_mul_f32_e32 v46, 0xbfcc422a, v46
	v_mul_f32_e32 v47, 0xbfcc422a, v47
	v_mul_f32_e32 v46, 0x3fb8aa3b, v46
	v_mul_f32_e32 v47, 0x3fb8aa3b, v47
	v_exp_f32_e32 v46, v46
	v_exp_f32_e32 v47, v47
	v_mov_b32_e32 v44, v155
	v_add_f32_e32 v46, 1.0, v46
	v_add_f32_e32 v47, 1.0, v47
	v_rcp_f32_e32 v46, v46
	v_rcp_f32_e32 v47, v47
	s_nop 0
	v_pk_mul_f32 v[152:153], v[152:153], v[46:47]
	s_nop 0
	v_pk_mul_f32 v[36:37], v[36:37], v[152:153]
	v_mul_f32_e32 v40, 0x3d372713, v154
	v_mul_f32_e32 v41, 0x3d372713, v155
	v_mul_f32_e32 v40, v154, v40
	v_mul_f32_e32 v41, v155, v41
	v_fma_f32 v40, v154, v40, v154
	v_fmac_f32_e32 v44, v44, v41
	v_mul_f32_e32 v40, 0xbfcc422a, v40
	v_mul_f32_e32 v41, 0xbfcc422a, v44
	v_mul_f32_e32 v40, 0x3fb8aa3b, v40
	v_mul_f32_e32 v41, 0x3fb8aa3b, v41
	v_exp_f32_e32 v40, v40
	v_exp_f32_e32 v41, v41
	v_cvt_pk_bf16_f32 v36, v36, v37
	v_add_f32_e32 v40, 1.0, v40
	v_add_f32_e32 v41, 1.0, v41
	v_rcp_f32_e32 v40, v40
	v_rcp_f32_e32 v41, v41
	s_nop 0
	v_pk_mul_f32 v[40:41], v[154:155], v[40:41]
	s_nop 0
	v_pk_mul_f32 v[38:39], v[38:39], v[40:41]
	s_nop 0
	v_cvt_pk_bf16_f32 v37, v38, v39
	global_store_dwordx2 v[52:53], v[36:37], off offset:1056
	s_nop 0
	s_nop 0
	v_add_f32_e32 v32, v32, v180
	v_add_f32_e32 v33, v33, v181
	s_nop 0
	v_mul_f32_e32 v32, 0xbfb8aa3b, v32
	v_mul_f32_e32 v33, 0xbfb8aa3b, v33
	v_exp_f32_e32 v32, v32
	v_exp_f32_e32 v33, v33
	v_add_f32_e32 v34, v34, v182
	v_add_f32_e32 v35, v35, v183
	v_mov_b32_e32 v41, v183
	v_add_f32_e32 v32, 1.0, v32
	v_add_f32_e32 v33, 1.0, v33
	v_rcp_f32_e32 v32, v32
	v_rcp_f32_e32 v33, v33
	v_mul_f32_e32 v34, 0xbfb8aa3b, v34
	v_mul_f32_e32 v35, 0xbfb8aa3b, v35
	v_exp_f32_e32 v34, v34
	v_exp_f32_e32 v35, v35
	v_add_f32_e32 v34, 1.0, v34
	v_add_f32_e32 v35, 1.0, v35
	v_rcp_f32_e32 v34, v34
	v_rcp_f32_e32 v35, v35
	s_nop 0
	s_waitcnt vmcnt(5)
; __device__ __forceinline__ uint2 pack4(float a, float b, float c, float d) { return make_uint2(pack2(a, b), pack2(c, d)); }
; __device__ __forceinline__ float frcp(float x) { return __builtin_amdgcn_rcpf(x); }
; __device__ __forceinline__ float sigmoidf_(float x) { return frcp(1.f + __expf(-x)); }
; __device__ __forceinline__ float gelu_tanh(float x) {
;   const float u2 = 1.5957691216057308f * (x + 0.044715f * x * x * x);
;   return x * frcp(1.f + __expf(-u2));
; }
; __global__ void __launch_bounds__(NTHR, 2) mega(P p, int ph_lo, int ph_hi) {
;     ...
;         auto f = [=] __device__(int m, int n, const f32x4& a, int) {
;           float4 y = *(const float4*)(ybuf + (size_t)m * 512 + n);
;           float4 bg = *(const float4*)(p.s5_bglu + n);
;           *(uint2*)(p.A + (size_t)m * 1024 + 512 + n) =
;               pack4(gelu_tanh(y.x) * sigmoidf_(a[0] + bg.x), gelu_tanh(y.y) * sigmoidf_(a[1] + bg.y),
;                     gelu_tanh(y.z) * sigmoidf_(a[2] + bg.z), gelu_tanh(y.w) * sigmoidf_(a[3] + bg.w));
;         };
	v_mul_f32_e32 v42, 0x3d372713, v156
	v_mul_f32_e32 v43, 0x3d372713, v157
	v_mul_f32_e32 v42, v156, v42
	v_mul_f32_e32 v43, v157, v43
	v_fma_f32 v42, v156, v42, v156
	v_fma_f32 v43, v157, v43, v157
	v_mul_f32_e32 v42, 0xbfcc422a, v42
	v_mul_f32_e32 v43, 0xbfcc422a, v43
	v_mul_f32_e32 v42, 0x3fb8aa3b, v42
	v_mul_f32_e32 v43, 0x3fb8aa3b, v43
	v_exp_f32_e32 v42, v42
	v_exp_f32_e32 v43, v43
	v_mov_b32_e32 v40, v159
	v_add_f32_e32 v42, 1.0, v42
	v_add_f32_e32 v43, 1.0, v43
	v_rcp_f32_e32 v42, v42
	v_rcp_f32_e32 v43, v43
	s_nop 0
	v_pk_mul_f32 v[156:157], v[156:157], v[42:43]
	s_nop 0
	v_pk_mul_f32 v[32:33], v[32:33], v[156:157]
	v_mul_f32_e32 v36, 0x3d372713, v158
	v_mul_f32_e32 v37, 0x3d372713, v159
	v_mul_f32_e32 v36, v158, v36
	v_mul_f32_e32 v37, v159, v37
	v_fma_f32 v36, v158, v36, v158
	v_fmac_f32_e32 v40, v40, v37
	v_mul_f32_e32 v36, 0xbfcc422a, v36
	v_mul_f32_e32 v37, 0xbfcc422a, v40
	v_mul_f32_e32 v36, 0x3fb8aa3b, v36
	v_mul_f32_e32 v37, 0x3fb8aa3b, v37
	v_exp_f32_e32 v36, v36
	v_exp_f32_e32 v37, v37
	v_cvt_pk_bf16_f32 v32, v32, v33
	v_add_f32_e32 v36, 1.0, v36
	v_add_f32_e32 v37, 1.0, v37
	v_rcp_f32_e32 v36, v36
	v_rcp_f32_e32 v37, v37
	s_nop 0
	v_pk_mul_f32 v[36:37], v[158:159], v[36:37]
	s_nop 0
	v_pk_mul_f32 v[34:35], v[34:35], v[36:37]
	s_nop 0
	v_cvt_pk_bf16_f32 v33, v34, v35
	global_store_dwordx2 v[68:69], v[32:33], off offset:1056
	s_nop 0
	s_nop 0
	v_add_f32_e32 v28, v28, v184
	v_add_f32_e32 v29, v29, v185
	s_nop 0
	v_mul_f32_e32 v28, 0xbfb8aa3b, v28
	v_mul_f32_e32 v29, 0xbfb8aa3b, v29
	v_exp_f32_e32 v28, v28
	v_exp_f32_e32 v29, v29
	v_add_f32_e32 v30, v30, v186
	v_add_f32_e32 v31, v31, v187
	v_mov_b32_e32 v37, v187
	v_add_f32_e32 v28, 1.0, v28
	v_add_f32_e32 v29, 1.0, v29
	v_rcp_f32_e32 v28, v28
	v_rcp_f32_e32 v29, v29
	v_mul_f32_e32 v30, 0xbfb8aa3b, v30
	v_mul_f32_e32 v31, 0xbfb8aa3b, v31
	v_exp_f32_e32 v30, v30
	v_exp_f32_e32 v31, v31
	v_add_f32_e32 v30, 1.0, v30
	v_add_f32_e32 v31, 1.0, v31
	v_rcp_f32_e32 v30, v30
	v_rcp_f32_e32 v31, v31
	s_nop 0
	v_mul_f32_e32 v38, 0x3d372713, v188
	v_mul_f32_e32 v39, 0x3d372713, v189
	v_mul_f32_e32 v38, v188, v38
	v_mul_f32_e32 v39, v189, v39
	v_fma_f32 v38, v188, v38, v188
	v_fma_f32 v39, v189, v39, v189
	v_mul_f32_e32 v38, 0xbfcc422a, v38
	v_mul_f32_e32 v39, 0xbfcc422a, v39
	v_mul_f32_e32 v38, 0x3fb8aa3b, v38
	v_mul_f32_e32 v39, 0x3fb8aa3b, v39
	v_exp_f32_e32 v38, v38
	v_exp_f32_e32 v39, v39
	v_mov_b32_e32 v36, v191
	v_add_f32_e32 v38, 1.0, v38
	v_add_f32_e32 v39, 1.0, v39
	v_rcp_f32_e32 v38, v38
	v_rcp_f32_e32 v39, v39
	s_nop 0
	v_pk_mul_f32 v[188:189], v[188:189], v[38:39]
	s_nop 0
	v_pk_mul_f32 v[28:29], v[28:29], v[188:189]
	v_mul_f32_e32 v32, 0x3d372713, v190
	v_mul_f32_e32 v33, 0x3d372713, v191
	v_mul_f32_e32 v32, v190, v32
	v_mul_f32_e32 v33, v191, v33
	v_fma_f32 v32, v190, v32, v190
	v_fmac_f32_e32 v36, v36, v33
	v_mul_f32_e32 v32, 0xbfcc422a, v32
	v_mul_f32_e32 v33, 0xbfcc422a, v36
	v_mul_f32_e32 v32, 0x3fb8aa3b, v32
	v_mul_f32_e32 v33, 0x3fb8aa3b, v33
	v_exp_f32_e32 v32, v32
	v_exp_f32_e32 v33, v33
	v_cvt_pk_bf16_f32 v28, v28, v29
	v_add_f32_e32 v32, 1.0, v32
	v_add_f32_e32 v33, 1.0, v33
	v_rcp_f32_e32 v32, v32
	v_rcp_f32_e32 v33, v33
	s_nop 0
	v_pk_mul_f32 v[32:33], v[190:191], v[32:33]
	s_nop 0
	v_pk_mul_f32 v[30:31], v[30:31], v[32:33]
	s_nop 0
	v_cvt_pk_bf16_f32 v29, v30, v31
	global_store_dwordx2 v[62:63], v[28:29], off offset:1088
	s_nop 0
	s_nop 0
	v_add_f32_e32 v24, v24, v192
	v_add_f32_e32 v25, v25, v193
	s_nop 0
	v_mul_f32_e32 v24, 0xbfb8aa3b, v24
	v_mul_f32_e32 v25, 0xbfb8aa3b, v25
	v_exp_f32_e32 v24, v24
	v_exp_f32_e32 v25, v25
	v_add_f32_e32 v26, v26, v194
	v_add_f32_e32 v27, v27, v195
	v_mov_b32_e32 v33, v195
	v_add_f32_e32 v24, 1.0, v24
	v_add_f32_e32 v25, 1.0, v25
	v_rcp_f32_e32 v24, v24
	v_rcp_f32_e32 v25, v25
	v_mul_f32_e32 v26, 0xbfb8aa3b, v26
	v_mul_f32_e32 v27, 0xbfb8aa3b, v27
	v_exp_f32_e32 v26, v26
	v_exp_f32_e32 v27, v27
	v_add_f32_e32 v26, 1.0, v26
	v_add_f32_e32 v27, 1.0, v27
	v_rcp_f32_e32 v26, v26
	v_rcp_f32_e32 v27, v27
	s_nop 0
	v_mul_f32_e32 v34, 0x3d372713, v220
	v_mul_f32_e32 v35, 0x3d372713, v221
	v_mul_f32_e32 v34, v220, v34
	v_mul_f32_e32 v35, v221, v35
	v_fma_f32 v34, v220, v34, v220
	v_fma_f32 v35, v221, v35, v221
	v_mul_f32_e32 v34, 0xbfcc422a, v34
	v_mul_f32_e32 v35, 0xbfcc422a, v35
	v_mul_f32_e32 v34, 0x3fb8aa3b, v34
	v_mul_f32_e32 v35, 0x3fb8aa3b, v35
	v_exp_f32_e32 v34, v34
	v_exp_f32_e32 v35, v35
	v_mov_b32_e32 v32, v223
	v_add_f32_e32 v34, 1.0, v34
	v_add_f32_e32 v35, 1.0, v35
	v_rcp_f32_e32 v34, v34
	v_rcp_f32_e32 v35, v35
	s_nop 0
	v_pk_mul_f32 v[220:221], v[220:221], v[34:35]
	s_nop 0
	v_pk_mul_f32 v[24:25], v[24:25], v[220:221]
	v_mul_f32_e32 v28, 0x3d372713, v222
	v_mul_f32_e32 v29, 0x3d372713, v223
	v_mul_f32_e32 v28, v222, v28
	v_mul_f32_e32 v29, v223, v29
	v_fma_f32 v28, v222, v28, v222
	v_fmac_f32_e32 v32, v32, v29
	v_mul_f32_e32 v28, 0xbfcc422a, v28
	v_mul_f32_e32 v29, 0xbfcc422a, v32
	v_mul_f32_e32 v28, 0x3fb8aa3b, v28
	v_mul_f32_e32 v29, 0x3fb8aa3b, v29
	v_exp_f32_e32 v28, v28
	v_exp_f32_e32 v29, v29
	v_cvt_pk_bf16_f32 v24, v24, v25
	v_add_f32_e32 v28, 1.0, v28
	v_add_f32_e32 v29, 1.0, v29
	v_rcp_f32_e32 v28, v28
	v_rcp_f32_e32 v29, v29
	s_nop 0
	v_pk_mul_f32 v[28:29], v[222:223], v[28:29]
	s_nop 0
	v_pk_mul_f32 v[26:27], v[26:27], v[28:29]
	s_nop 0
	v_cvt_pk_bf16_f32 v25, v26, v27
	global_store_dwordx2 v[56:57], v[24:25], off offset:1088
	s_nop 0
	s_nop 0
	v_add_f32_e32 v20, v20, v224
	v_add_f32_e32 v21, v21, v225
	s_nop 0
	v_mul_f32_e32 v20, 0xbfb8aa3b, v20
	v_mul_f32_e32 v21, 0xbfb8aa3b, v21
	v_exp_f32_e32 v20, v20
	v_exp_f32_e32 v21, v21
	v_add_f32_e32 v22, v22, v226
	v_add_f32_e32 v23, v23, v227
	v_mov_b32_e32 v29, v227
; __device__ __forceinline__ uint2 pack4(float a, float b, float c, float d) { return make_uint2(pack2(a, b), pack2(c, d)); }
; __device__ __forceinline__ float frcp(float x) { return __builtin_amdgcn_rcpf(x); }
; __device__ __forceinline__ float sigmoidf_(float x) { return frcp(1.f + __expf(-x)); }
; __device__ __forceinline__ float gelu_tanh(float x) {
;   const float u2 = 1.5957691216057308f * (x + 0.044715f * x * x * x);
;   return x * frcp(1.f + __expf(-u2));
; }
; __global__ void __launch_bounds__(NTHR, 2) mega(P p, int ph_lo, int ph_hi) {
;     ...
;         auto f = [=] __device__(int m, int n, const f32x4& a, int) {
;           float4 y = *(const float4*)(ybuf + (size_t)m * 512 + n);
;           float4 bg = *(const float4*)(p.s5_bglu + n);
;           *(uint2*)(p.A + (size_t)m * 1024 + 512 + n) =
;               pack4(gelu_tanh(y.x) * sigmoidf_(a[0] + bg.x), gelu_tanh(y.y) * sigmoidf_(a[1] + bg.y),
;                     gelu_tanh(y.z) * sigmoidf_(a[2] + bg.z), gelu_tanh(y.w) * sigmoidf_(a[3] + bg.w));
;         };
	v_add_f32_e32 v20, 1.0, v20
	v_add_f32_e32 v21, 1.0, v21
	v_rcp_f32_e32 v20, v20
	v_rcp_f32_e32 v21, v21
	v_mul_f32_e32 v22, 0xbfb8aa3b, v22
	v_mul_f32_e32 v23, 0xbfb8aa3b, v23
	v_exp_f32_e32 v22, v22
	v_exp_f32_e32 v23, v23
	v_add_f32_e32 v22, 1.0, v22
	v_add_f32_e32 v23, 1.0, v23
	v_rcp_f32_e32 v22, v22
	v_rcp_f32_e32 v23, v23
	s_nop 0
	v_mul_f32_e32 v30, 0x3d372713, v232
	v_mul_f32_e32 v31, 0x3d372713, v233
	v_mul_f32_e32 v30, v232, v30
	v_mul_f32_e32 v31, v233, v31
	v_fma_f32 v30, v232, v30, v232
	v_fma_f32 v31, v233, v31, v233
	v_mul_f32_e32 v30, 0xbfcc422a, v30
	v_mul_f32_e32 v31, 0xbfcc422a, v31
	v_mul_f32_e32 v30, 0x3fb8aa3b, v30
	v_mul_f32_e32 v31, 0x3fb8aa3b, v31
	v_exp_f32_e32 v30, v30
	v_exp_f32_e32 v31, v31
	v_mov_b32_e32 v28, v235
	v_add_f32_e32 v30, 1.0, v30
	v_add_f32_e32 v31, 1.0, v31
	v_rcp_f32_e32 v30, v30
	v_rcp_f32_e32 v31, v31
	s_nop 0
	v_pk_mul_f32 v[232:233], v[232:233], v[30:31]
	s_nop 0
	v_pk_mul_f32 v[20:21], v[20:21], v[232:233]
	v_mul_f32_e32 v24, 0x3d372713, v234
	v_mul_f32_e32 v25, 0x3d372713, v235
	v_mul_f32_e32 v24, v234, v24
	v_mul_f32_e32 v25, v235, v25
	v_fma_f32 v24, v234, v24, v234
	v_fmac_f32_e32 v28, v28, v25
	v_mul_f32_e32 v24, 0xbfcc422a, v24
	v_mul_f32_e32 v25, 0xbfcc422a, v28
	v_mul_f32_e32 v24, 0x3fb8aa3b, v24
	v_mul_f32_e32 v25, 0x3fb8aa3b, v25
	v_exp_f32_e32 v24, v24
	v_exp_f32_e32 v25, v25
	v_cvt_pk_bf16_f32 v20, v20, v21
	v_add_f32_e32 v24, 1.0, v24
	v_add_f32_e32 v25, 1.0, v25
	v_rcp_f32_e32 v24, v24
	v_rcp_f32_e32 v25, v25
	s_nop 0
	v_pk_mul_f32 v[24:25], v[234:235], v[24:25]
	s_nop 0
	v_pk_mul_f32 v[22:23], v[22:23], v[24:25]
	s_nop 0
	v_cvt_pk_bf16_f32 v21, v22, v23
	global_store_dwordx2 v[52:53], v[20:21], off offset:1088
	s_nop 0
	s_nop 0
	v_add_f32_e32 v16, v16, v236
	v_add_f32_e32 v17, v17, v237
	s_nop 0
	v_mul_f32_e32 v16, 0xbfb8aa3b, v16
	v_mul_f32_e32 v17, 0xbfb8aa3b, v17
	v_exp_f32_e32 v16, v16
	v_exp_f32_e32 v17, v17
	v_add_f32_e32 v18, v18, v238
	v_add_f32_e32 v19, v19, v239
	v_mov_b32_e32 v25, v239
	v_add_f32_e32 v16, 1.0, v16
	v_add_f32_e32 v17, 1.0, v17
	v_rcp_f32_e32 v16, v16
	v_rcp_f32_e32 v17, v17
	v_mul_f32_e32 v18, 0xbfb8aa3b, v18
	v_mul_f32_e32 v19, 0xbfb8aa3b, v19
	v_exp_f32_e32 v18, v18
	v_exp_f32_e32 v19, v19
	v_add_f32_e32 v18, 1.0, v18
	v_add_f32_e32 v19, 1.0, v19
	v_rcp_f32_e32 v18, v18
	v_rcp_f32_e32 v19, v19
	s_nop 0
	s_waitcnt vmcnt(8)
	v_mul_f32_e32 v26, 0x3d372713, v240
	v_mul_f32_e32 v27, 0x3d372713, v241
	v_mul_f32_e32 v26, v240, v26
	v_mul_f32_e32 v27, v241, v27
	v_fma_f32 v26, v240, v26, v240
	v_fma_f32 v27, v241, v27, v241
	v_mul_f32_e32 v26, 0xbfcc422a, v26
	v_mul_f32_e32 v27, 0xbfcc422a, v27
	v_mul_f32_e32 v26, 0x3fb8aa3b, v26
	v_mul_f32_e32 v27, 0x3fb8aa3b, v27
	v_exp_f32_e32 v26, v26
	v_exp_f32_e32 v27, v27
	v_mov_b32_e32 v24, v243
	v_add_f32_e32 v26, 1.0, v26
	v_add_f32_e32 v27, 1.0, v27
	v_rcp_f32_e32 v26, v26
	v_rcp_f32_e32 v27, v27
	s_nop 0
	v_pk_mul_f32 v[240:241], v[240:241], v[26:27]
	s_nop 0
	v_pk_mul_f32 v[16:17], v[16:17], v[240:241]
	v_mul_f32_e32 v20, 0x3d372713, v242
	v_mul_f32_e32 v21, 0x3d372713, v243
	v_mul_f32_e32 v20, v242, v20
	v_mul_f32_e32 v21, v243, v21
	v_fma_f32 v20, v242, v20, v242
	v_fmac_f32_e32 v24, v24, v21
	v_mul_f32_e32 v20, 0xbfcc422a, v20
	v_mul_f32_e32 v21, 0xbfcc422a, v24
	v_mul_f32_e32 v20, 0x3fb8aa3b, v20
	v_mul_f32_e32 v21, 0x3fb8aa3b, v21
	v_exp_f32_e32 v20, v20
	v_exp_f32_e32 v21, v21
	v_cvt_pk_bf16_f32 v16, v16, v17
	v_add_f32_e32 v20, 1.0, v20
	v_add_f32_e32 v21, 1.0, v21
	v_rcp_f32_e32 v20, v20
	v_rcp_f32_e32 v21, v21
	s_nop 0
	v_pk_mul_f32 v[20:21], v[242:243], v[20:21]
	s_nop 0
	v_pk_mul_f32 v[18:19], v[18:19], v[20:21]
	s_nop 0
	v_cvt_pk_bf16_f32 v17, v18, v19
	global_store_dwordx2 v[68:69], v[16:17], off offset:1088
	s_nop 0
	s_nop 0
	v_add_f32_e32 v12, v12, v244
	v_add_f32_e32 v13, v13, v245
	s_nop 0
	v_mul_f32_e32 v12, 0xbfb8aa3b, v12
	v_mul_f32_e32 v13, 0xbfb8aa3b, v13
	v_exp_f32_e32 v12, v12
	v_exp_f32_e32 v13, v13
	v_add_f32_e32 v14, v14, v246
	v_add_f32_e32 v15, v15, v247
	v_mov_b32_e32 v21, v247
	v_add_f32_e32 v12, 1.0, v12
	v_add_f32_e32 v13, 1.0, v13
	v_rcp_f32_e32 v12, v12
	v_rcp_f32_e32 v13, v13
	v_mul_f32_e32 v14, 0xbfb8aa3b, v14
	v_mul_f32_e32 v15, 0xbfb8aa3b, v15
	v_exp_f32_e32 v14, v14
	v_exp_f32_e32 v15, v15
	v_add_f32_e32 v14, 1.0, v14
	v_add_f32_e32 v15, 1.0, v15
	v_rcp_f32_e32 v14, v14
	v_rcp_f32_e32 v15, v15
	s_nop 0
	v_mul_f32_e32 v22, 0x3d372713, v248
	v_mul_f32_e32 v23, 0x3d372713, v249
	v_mul_f32_e32 v22, v248, v22
	v_mul_f32_e32 v23, v249, v23
	v_fma_f32 v22, v248, v22, v248
	v_fma_f32 v23, v249, v23, v249
	v_mul_f32_e32 v22, 0xbfcc422a, v22
	v_mul_f32_e32 v23, 0xbfcc422a, v23
	v_mul_f32_e32 v22, 0x3fb8aa3b, v22
	v_mul_f32_e32 v23, 0x3fb8aa3b, v23
	v_exp_f32_e32 v22, v22
	v_exp_f32_e32 v23, v23
	v_mov_b32_e32 v20, v251
	v_add_f32_e32 v22, 1.0, v22
	v_add_f32_e32 v23, 1.0, v23
	v_rcp_f32_e32 v22, v22
	v_rcp_f32_e32 v23, v23
	s_nop 0
	v_pk_mul_f32 v[248:249], v[248:249], v[22:23]
	s_nop 0
	v_pk_mul_f32 v[12:13], v[12:13], v[248:249]
	v_mul_f32_e32 v16, 0x3d372713, v250
	v_mul_f32_e32 v17, 0x3d372713, v251
	v_mul_f32_e32 v16, v250, v16
	v_mul_f32_e32 v17, v251, v17
	v_fma_f32 v16, v250, v16, v250
	v_fmac_f32_e32 v20, v20, v17
	v_mul_f32_e32 v16, 0xbfcc422a, v16
	v_mul_f32_e32 v17, 0xbfcc422a, v20
	v_mul_f32_e32 v16, 0x3fb8aa3b, v16
	v_mul_f32_e32 v17, 0x3fb8aa3b, v17
	v_exp_f32_e32 v16, v16
	v_exp_f32_e32 v17, v17
	v_cvt_pk_bf16_f32 v12, v12, v13
	v_add_f32_e32 v16, 1.0, v16
	v_add_f32_e32 v17, 1.0, v17
	v_rcp_f32_e32 v16, v16
	v_rcp_f32_e32 v17, v17
	s_nop 0
	v_pk_mul_f32 v[16:17], v[250:251], v[16:17]
	s_nop 0
	v_pk_mul_f32 v[14:15], v[14:15], v[16:17]
	s_nop 0
	v_cvt_pk_bf16_f32 v13, v14, v15
	global_store_dwordx2 v[62:63], v[12:13], off offset:1120
	s_nop 0
	s_nop 0
	v_add_f32_e32 v8, v8, v252
	v_add_f32_e32 v9, v9, v253
	global_load_dwordx4 v[12:15], v[64:65], off offset:192
	v_mul_f32_e32 v8, 0xbfb8aa3b, v8
	v_mul_f32_e32 v9, 0xbfb8aa3b, v9
	v_exp_f32_e32 v8, v8
	v_exp_f32_e32 v9, v9
	v_add_f32_e32 v10, v10, v254
	v_add_f32_e32 v11, v11, v255
	v_mov_b32_e32 v17, v255
	v_add_f32_e32 v8, 1.0, v8
	v_add_f32_e32 v9, 1.0, v9
	v_rcp_f32_e32 v8, v8
	v_rcp_f32_e32 v9, v9
	v_mul_f32_e32 v10, 0xbfb8aa3b, v10
	v_mul_f32_e32 v11, 0xbfb8aa3b, v11
	v_exp_f32_e32 v10, v10
	v_exp_f32_e32 v11, v11
	v_add_f32_e32 v10, 1.0, v10
	v_add_f32_e32 v11, 1.0, v11
	v_rcp_f32_e32 v10, v10
	v_rcp_f32_e32 v11, v11
	s_nop 0
	s_waitcnt vmcnt(0)
; __device__ __forceinline__ uint2 pack4(float a, float b, float c, float d) { return make_uint2(pack2(a, b), pack2(c, d)); }
; __device__ __forceinline__ float frcp(float x) { return __builtin_amdgcn_rcpf(x); }
; __device__ __forceinline__ float sigmoidf_(float x) { return frcp(1.f + __expf(-x)); }
; __device__ __forceinline__ float gelu_tanh(float x) {
;   const float u2 = 1.5957691216057308f * (x + 0.044715f * x * x * x);
;   return x * frcp(1.f + __expf(-u2));
; }
; __global__ void __launch_bounds__(NTHR, 2) mega(P p, int ph_lo, int ph_hi) {
;     ...
;         auto f = [=] __device__(int m, int n, const f32x4& a, int) {
;           float4 y = *(const float4*)(ybuf + (size_t)m * 512 + n);
;           float4 bg = *(const float4*)(p.s5_bglu + n);
;           *(uint2*)(p.A + (size_t)m * 1024 + 512 + n) =
;               pack4(gelu_tanh(y.x) * sigmoidf_(a[0] + bg.x), gelu_tanh(y.y) * sigmoidf_(a[1] + bg.y),
;                     gelu_tanh(y.z) * sigmoidf_(a[2] + bg.z), gelu_tanh(y.w) * sigmoidf_(a[3] + bg.w));
;         };
	v_mul_f32_e32 v18, 0x3d372713, v12
	v_mul_f32_e32 v19, 0x3d372713, v13
	v_mul_f32_e32 v18, v12, v18
	v_mul_f32_e32 v19, v13, v19
	v_fma_f32 v18, v12, v18, v12
	v_fma_f32 v19, v13, v19, v13
	v_mul_f32_e32 v18, 0xbfcc422a, v18
	v_mul_f32_e32 v19, 0xbfcc422a, v19
	v_mul_f32_e32 v18, 0x3fb8aa3b, v18
	v_mul_f32_e32 v19, 0x3fb8aa3b, v19
	v_exp_f32_e32 v18, v18
	v_exp_f32_e32 v19, v19
	v_mov_b32_e32 v16, v15
	v_add_f32_e32 v18, 1.0, v18
	v_add_f32_e32 v19, 1.0, v19
	v_rcp_f32_e32 v18, v18
	v_rcp_f32_e32 v19, v19
	s_nop 0
	v_pk_mul_f32 v[12:13], v[12:13], v[18:19]
	s_nop 0
	v_pk_mul_f32 v[8:9], v[8:9], v[12:13]
	v_mul_f32_e32 v12, 0x3d372713, v14
	v_mul_f32_e32 v13, 0x3d372713, v15
	v_mul_f32_e32 v12, v14, v12
	v_mul_f32_e32 v13, v15, v13
	v_fma_f32 v12, v14, v12, v14
	v_fmac_f32_e32 v16, v16, v13
	v_mul_f32_e32 v12, 0xbfcc422a, v12
	v_mul_f32_e32 v13, 0xbfcc422a, v16
	v_mul_f32_e32 v12, 0x3fb8aa3b, v12
	v_mul_f32_e32 v13, 0x3fb8aa3b, v13
	v_exp_f32_e32 v12, v12
	v_exp_f32_e32 v13, v13
	v_cvt_pk_bf16_f32 v8, v8, v9
	v_add_f32_e32 v12, 1.0, v12
	v_add_f32_e32 v13, 1.0, v13
	v_rcp_f32_e32 v12, v12
	v_rcp_f32_e32 v13, v13
	s_nop 0
	v_pk_mul_f32 v[12:13], v[14:15], v[12:13]
	s_nop 0
	v_pk_mul_f32 v[10:11], v[10:11], v[12:13]
	s_nop 0
	v_cvt_pk_bf16_f32 v9, v10, v11
	global_store_dwordx2 v[56:57], v[8:9], off offset:1120
	global_load_dwordx4 v[10:13], v[60:61], off offset:192
	s_nop 0
	s_waitcnt vmcnt(0)
	v_add_f32_e32 v4, v4, v10
	v_add_f32_e32 v5, v5, v11
	global_load_dwordx4 v[8:11], v[58:59], off offset:192
	v_mul_f32_e32 v4, 0xbfb8aa3b, v4
	v_mul_f32_e32 v5, 0xbfb8aa3b, v5
	v_exp_f32_e32 v4, v4
	v_exp_f32_e32 v5, v5
	v_add_f32_e32 v6, v6, v12
	v_add_f32_e32 v7, v7, v13
	v_add_f32_e32 v4, 1.0, v4
	v_add_f32_e32 v5, 1.0, v5
	v_rcp_f32_e32 v4, v4
	v_rcp_f32_e32 v5, v5
	v_mul_f32_e32 v6, 0xbfb8aa3b, v6
	v_mul_f32_e32 v7, 0xbfb8aa3b, v7
	v_exp_f32_e32 v6, v6
	v_exp_f32_e32 v7, v7
	v_add_f32_e32 v6, 1.0, v6
	v_add_f32_e32 v7, 1.0, v7
	v_rcp_f32_e32 v6, v6
	v_rcp_f32_e32 v7, v7
	s_nop 0
	s_waitcnt vmcnt(0)
	v_mul_f32_e32 v14, 0x3d372713, v8
	v_mul_f32_e32 v15, 0x3d372713, v9
	v_mul_f32_e32 v14, v8, v14
	v_mul_f32_e32 v15, v9, v15
	v_fma_f32 v14, v8, v14, v8
	v_fma_f32 v15, v9, v15, v9
	v_mul_f32_e32 v14, 0xbfcc422a, v14
	v_mul_f32_e32 v15, 0xbfcc422a, v15
	v_mul_f32_e32 v14, 0x3fb8aa3b, v14
	v_mul_f32_e32 v15, 0x3fb8aa3b, v15
	v_exp_f32_e32 v14, v14
	v_exp_f32_e32 v15, v15
	v_mov_b32_e32 v12, v11
	v_add_f32_e32 v14, 1.0, v14
	v_add_f32_e32 v15, 1.0, v15
	v_rcp_f32_e32 v14, v14
	v_rcp_f32_e32 v15, v15
	s_nop 0
	v_pk_mul_f32 v[8:9], v[8:9], v[14:15]
	s_nop 0
	v_pk_mul_f32 v[4:5], v[4:5], v[8:9]
	v_mul_f32_e32 v8, 0x3d372713, v10
	v_mul_f32_e32 v9, 0x3d372713, v11
	v_mul_f32_e32 v8, v10, v8
	v_mul_f32_e32 v9, v11, v9
	v_fma_f32 v8, v10, v8, v10
	v_fmac_f32_e32 v12, v12, v9
	v_mul_f32_e32 v8, 0xbfcc422a, v8
	v_mul_f32_e32 v9, 0xbfcc422a, v12
	v_mul_f32_e32 v8, 0x3fb8aa3b, v8
	v_mul_f32_e32 v9, 0x3fb8aa3b, v9
	v_exp_f32_e32 v8, v8
	v_exp_f32_e32 v9, v9
	v_cvt_pk_bf16_f32 v4, v4, v5
	v_add_f32_e32 v8, 1.0, v8
	v_add_f32_e32 v9, 1.0, v9
	v_rcp_f32_e32 v8, v8
	v_rcp_f32_e32 v9, v9
	s_nop 0
	v_pk_mul_f32 v[8:9], v[10:11], v[8:9]
	s_nop 0
	v_pk_mul_f32 v[6:7], v[6:7], v[8:9]
	s_nop 0
	v_cvt_pk_bf16_f32 v5, v6, v7
	global_store_dwordx2 v[52:53], v[4:5], off offset:1120
	global_load_dwordx4 v[4:7], v[60:61], off offset:192
	s_nop 0
	s_waitcnt vmcnt(0)
	v_add_f32_e32 v0, v0, v4
	global_load_dwordx4 v[8:11], v[54:55], off offset:192
	v_add_f32_e32 v1, v1, v5
	v_mul_f32_e32 v0, 0xbfb8aa3b, v0
	v_mul_f32_e32 v1, 0xbfb8aa3b, v1
	v_exp_f32_e32 v0, v0
	v_exp_f32_e32 v1, v1
	v_add_f32_e32 v2, v2, v6
	v_add_f32_e32 v3, v3, v7
	v_add_f32_e32 v0, 1.0, v0
	v_add_f32_e32 v1, 1.0, v1
	v_rcp_f32_e32 v0, v0
	v_rcp_f32_e32 v1, v1
	v_mul_f32_e32 v2, 0xbfb8aa3b, v2
	v_mul_f32_e32 v3, 0xbfb8aa3b, v3
	v_exp_f32_e32 v2, v2
	v_exp_f32_e32 v3, v3
	v_add_f32_e32 v2, 1.0, v2
	v_add_f32_e32 v3, 1.0, v3
	v_rcp_f32_e32 v2, v2
	v_rcp_f32_e32 v3, v3
	s_nop 0
	s_waitcnt vmcnt(0)
	v_mul_f32_e32 v4, 0x3d372713, v8
	v_mul_f32_e32 v5, 0x3d372713, v9
	v_mul_f32_e32 v4, v8, v4
	v_mul_f32_e32 v5, v9, v5
	v_fma_f32 v4, v8, v4, v8
	v_fma_f32 v5, v9, v5, v9
	v_mul_f32_e32 v4, 0xbfcc422a, v4
	v_mul_f32_e32 v5, 0xbfcc422a, v5
	v_mul_f32_e32 v4, 0x3fb8aa3b, v4
	v_mul_f32_e32 v5, 0x3fb8aa3b, v5
	v_exp_f32_e32 v4, v4
	v_exp_f32_e32 v5, v5
	v_mov_b32_e32 v6, v11
	v_add_f32_e32 v4, 1.0, v4
	v_add_f32_e32 v5, 1.0, v5
	v_rcp_f32_e32 v4, v4
	v_rcp_f32_e32 v5, v5
	s_nop 0
	v_pk_mul_f32 v[4:5], v[8:9], v[4:5]
	s_nop 0
	v_pk_mul_f32 v[0:1], v[0:1], v[4:5]
	v_mul_f32_e32 v4, 0x3d372713, v10
	v_mul_f32_e32 v5, 0x3d372713, v11
	v_mul_f32_e32 v4, v10, v4
	v_mul_f32_e32 v5, v11, v5
	v_fma_f32 v4, v10, v4, v10
	v_fmac_f32_e32 v6, v6, v5
	v_mul_f32_e32 v4, 0xbfcc422a, v4
	v_mul_f32_e32 v5, 0xbfcc422a, v6
	v_mul_f32_e32 v4, 0x3fb8aa3b, v4
	v_mul_f32_e32 v5, 0x3fb8aa3b, v5
	v_exp_f32_e32 v4, v4
	v_exp_f32_e32 v5, v5
	v_cvt_pk_bf16_f32 v0, v0, v1
	v_add_f32_e32 v4, 1.0, v4
	v_add_f32_e32 v5, 1.0, v5
	v_rcp_f32_e32 v4, v4
	v_rcp_f32_e32 v5, v5
	s_nop 0
	v_pk_mul_f32 v[4:5], v[10:11], v[4:5]
	s_nop 0
	v_pk_mul_f32 v[2:3], v[2:3], v[4:5]
	s_nop 0
	v_cvt_pk_bf16_f32 v1, v2, v3
	global_store_dwordx2 v[68:69], v[0:1], off offset:1120
	s_cbranch_scc1 .LBB0_342

; #define G_LOAD(r0, r1, r2, r3, kt_)                                                    \
;   { const int k0_ = (kt_) * 32; r0 = al(m0 + lr0, k0_ + lkc, nt); r1 = al(m0 + lr0 + 64, k0_ + lkc, nt); \
;     r2 = *(const bf16x8*)(wp0 + k0_); r3 = *(const bf16x8*)(wp1 + k0_); }
; template <class AL, class EP>
; __device__ __forceinline__ void gemm_tile(const AL& al, const u16* __restrict__ Wt, int K, int m0, int n0, int nt,
;                                           const EP& ep, u16* sm) {
;     ...
;   G_LOAD(e0, e1, e2, e3, 0);
;   G_LOAD(o0, o1, o2, o3, 1);
;   G_STORE(e0, e1, e2, e3, 0);
;   if (nk > 2) G_LOAD(e0, e1, e2, e3, 2);
;   __syncthreads();
;   for (int kt = 0; kt < nk; kt += 2) {
;     G_COMPUTE(0);
;     G_STORE(o0, o1, o2, o3, 1);
;     if (kt + 3 < nk) G_LOAD(o0, o1, o2, o3, kt + 3);
;     __syncthreads();
;     G_COMPUTE(1);
;     if (kt + 2 < nk) {
;       G_STORE(e0, e1, e2, e3, 0);
;       if (kt + 4 < nk) G_LOAD(e0, e1, e2, e3, kt + 4);
;     }
;     __syncthreads();
;   }
.LBB0_347:
	s_ashr_i32 s8, s7, 4
	s_ashr_i32 s9, s8, 31
	s_lshl_b64 s[10:11], s[8:9], 8
	v_mov_b32_e32 v2, v132
	s_add_u32 s10, s16, s10
	s_addc_u32 s11, s17, s11
	v_ashrrev_i32_e32 v32, 2, v2
	s_lshl_b64 s[8:9], s[8:9], 16
	v_lshrrev_b32_e32 v0, 2, v32
	s_add_u32 s14, s62, s8
	v_sub_u32_e32 v0, 0, v0
	v_lshrrev_b32_e32 v140, 2, v2
	s_addc_u32 s15, s63, s9
	s_and_b32 s9, s6, 0x80
	v_xor_b32_e32 v33, v2, v0
	v_lshrrev_b32_e32 v0, 4, v2
	v_sub_u32_e32 v1, 0, v140
	v_xor_b32_e32 v34, v0, v1
	v_add_u32_e32 v0, s9, v32
	v_ashrrev_i32_e32 v1, 31, v0
	v_ashrrev_i32_e32 v138, 7, v2
	v_bfe_u32 v143, v2, 6, 1
	v_and_b32_e32 v148, 15, v2
	v_lshlrev_b64 v[0:1], 8, v[0:1]
	v_lshlrev_b32_e32 v2, 4, v2
	s_and_b32 s8, s4, 0x380
	v_lshl_add_u64 v[0:1], s[14:15], 0, v[0:1]
	v_and_b32_e32 v134, 48, v2
	v_lshl_add_u64 v[100:101], v[0:1], 0, v[134:135]
	v_add_u32_e32 v0, s8, v32
	v_ashrrev_i32_e32 v1, 31, v0
	v_lshlrev_b64 v[0:1], 13, v[0:1]
	v_lshl_add_u64 v[0:1], s[10:11], 0, v[0:1]
	v_lshl_add_u64 v[104:105], v[0:1], 0, v[134:135]
	v_add_co_u32_e32 v4, vcc, s34, v104
	global_load_dwordx4 v[0:3], v[104:105], off
	s_nop 0
	v_addc_co_u32_e32 v5, vcc, 0, v105, vcc
	global_load_dwordx4 v[4:7], v[4:5], off
	s_nop 0
	global_load_dwordx4 v[8:11], v[100:101], off
	v_add_co_u32_e32 v12, vcc, s56, v100
	v_lshl_add_u64 v[102:103], v[100:101], 0, s[94:95]
	s_nop 0
	v_addc_co_u32_e32 v13, vcc, 0, v101, vcc
	v_lshl_add_u64 v[106:107], v[104:105], 0, s[12:13]
	global_load_dwordx4 v[12:15], v[12:13], off
	s_nop 0
	global_load_dwordx4 v[16:19], v[104:105], off offset:64
	global_load_dwordx4 v[20:23], v[106:107], off offset:64
	global_load_dwordx4 v[24:27], v[100:101], off offset:64
	global_load_dwordx4 v[28:31], v[102:103], off offset:64
	v_lshlrev_b32_e32 v33, 4, v33
	v_and_b32_e32 v33, 48, v33
	v_lshl_or_b32 v128, v32, 6, v33
	v_lshlrev_b32_e32 v32, 4, v34
	v_and_b32_e32 v48, 48, v32
	v_lshlrev_b32_e32 v32, 12, v143
	v_lshlrev_b32_e32 v49, 6, v148
	v_lshlrev_b32_e32 v50, 12, v138
	v_or3_b32 v129, v48, v32, v49
	v_or3_b32 v134, v48, v50, v49
	s_add_i32 s4, s4, s58
	s_add_i32 s6, s6, s35
	s_waitcnt vmcnt(7)
	ds_write_b128 v128, v[0:3]
	s_waitcnt vmcnt(6)
	ds_write_b128 v128, v[4:7] offset:4096
	s_waitcnt vmcnt(5)
	ds_write_b128 v128, v[8:11] offset:16384
	s_waitcnt vmcnt(4)
	ds_write_b128 v128, v[12:15] offset:20480
	global_load_dwordx4 v[0:3], v[104:105], off offset:128
	global_load_dwordx4 v[4:7], v[106:107], off offset:128
	global_load_dwordx4 v[8:11], v[102:103], off offset:128
	global_load_dwordx4 v[12:15], v[100:101], off offset:128
	s_waitcnt lgkmcnt(0)
	s_barrier
	ds_read_b128 v[32:35], v129 offset:16384
	ds_read_b128 v[36:39], v129 offset:17408
	ds_read_b128 v[40:43], v129 offset:18432
	ds_read_b128 v[44:47], v129 offset:19456
	ds_read_b128 v[48:51], v134
	ds_read_b128 v[52:55], v134 offset:1024
	ds_read_b128 v[56:59], v134 offset:2048
	ds_read_b128 v[60:63], v134 offset:3072
	s_waitcnt vmcnt(7)
	ds_write_b128 v128, v[16:19] offset:8192
	s_waitcnt vmcnt(6)
	ds_write_b128 v128, v[20:23] offset:12288
	s_waitcnt vmcnt(5)
	ds_write_b128 v128, v[24:27] offset:24576
	s_waitcnt vmcnt(4)
	ds_write_b128 v128, v[28:31] offset:28672
	global_load_dwordx4 v[16:19], v[104:105], off offset:192
	global_load_dwordx4 v[20:23], v[106:107], off offset:192
	global_load_dwordx4 v[24:27], v[100:101], off offset:192
	global_load_dwordx4 v[28:31], v[102:103], off offset:192
	s_waitcnt lgkmcnt(7)
	v_mfma_f32_16x16x32_bf16 v[64:67], v[32:35], v[48:51], 0
	s_waitcnt lgkmcnt(0)
	s_barrier
	v_mfma_f32_16x16x32_bf16 v[68:71], v[32:35], v[52:55], 0
	v_mfma_f32_16x16x32_bf16 v[72:75], v[32:35], v[56:59], 0
	v_mfma_f32_16x16x32_bf16 v[32:35], v[32:35], v[60:63], 0
	v_mfma_f32_16x16x32_bf16 v[76:79], v[36:39], v[48:51], 0
	v_mfma_f32_16x16x32_bf16 v[80:83], v[36:39], v[52:55], 0
	v_mfma_f32_16x16x32_bf16 v[84:87], v[36:39], v[56:59], 0
	v_mfma_f32_16x16x32_bf16 v[36:39], v[36:39], v[60:63], 0
	v_mfma_f32_16x16x32_bf16 v[88:91], v[40:43], v[48:51], 0
	v_mfma_f32_16x16x32_bf16 v[92:95], v[40:43], v[52:55], 0
	v_mfma_f32_16x16x32_bf16 v[96:99], v[40:43], v[56:59], 0
	v_mfma_f32_16x16x32_bf16 v[40:43], v[40:43], v[60:63], 0
	v_mfma_f32_16x16x32_bf16 v[48:51], v[44:47], v[48:51], 0
	v_mfma_f32_16x16x32_bf16 v[52:55], v[44:47], v[52:55], 0
	v_mfma_f32_16x16x32_bf16 v[56:59], v[44:47], v[56:59], 0
	v_mfma_f32_16x16x32_bf16 v[44:47], v[44:47], v[60:63], 0
	ds_read_b128 v[60:63], v129 offset:24576
	ds_read_b128 v[100:103], v129 offset:25600
	ds_read_b128 v[104:107], v129 offset:26624
	ds_read_b128 v[108:111], v129 offset:27648
	ds_read_b128 v[112:115], v134 offset:8192
	ds_read_b128 v[116:119], v134 offset:9216
	ds_read_b128 v[120:123], v134 offset:10240
	ds_read_b128 v[124:127], v134 offset:11264
	s_waitcnt vmcnt(7)
	ds_write_b128 v128, v[0:3]
	s_waitcnt vmcnt(6)
	ds_write_b128 v128, v[4:7] offset:4096
	s_waitcnt vmcnt(4)
	ds_write_b128 v128, v[12:15] offset:16384
	ds_write_b128 v128, v[8:11] offset:20480
	s_waitcnt lgkmcnt(7)
	v_mfma_f32_16x16x32_bf16 v[64:67], v[60:63], v[112:115], v[64:67]
	s_waitcnt lgkmcnt(0)
	s_barrier
; __device__ __forceinline__ void unpack4(uint2 u, float* f) { f[0] = bflo(u.x); f[1] = bfhi(u.x); f[2] = bflo(u.y); f[3] = bfhi(u.y); }
; #define G_LOAD(r0, r1, r2, r3, kt_)                                                    \
;   { const int k0_ = (kt_) * 32; r0 = al(m0 + lr0, k0_ + lkc, nt); r1 = al(m0 + lr0 + 64, k0_ + lkc, nt); \
;     r2 = *(const bf16x8*)(wp0 + k0_); r3 = *(const bf16x8*)(wp1 + k0_); }
; template <class AL, class EP>
; __device__ __forceinline__ void gemm_tile(const AL& al, const u16* __restrict__ Wt, int K, int m0, int n0, int nt,
;                                           const EP& ep, u16* sm) {
;     ...
;   for (int kt = 0; kt < nk; kt += 2) {
;     G_COMPUTE(0);
;     G_STORE(o0, o1, o2, o3, 1);
;     if (kt + 3 < nk) G_LOAD(o0, o1, o2, o3, kt + 3);
;     __syncthreads();
;     G_COMPUTE(1);
;     if (kt + 2 < nk) {
;       G_STORE(e0, e1, e2, e3, 0);
;       if (kt + 4 < nk) G_LOAD(e0, e1, e2, e3, kt + 4);
;     }
;     __syncthreads();
;   }
;     ...
;   ep(acc, m0 + wm * 64, n0 + wn * 64, lane, nt);
; __global__ void __launch_bounds__(NTHR, 2) mega(P p, int ph_lo, int ph_hi) {
;     ...
;           auto f = [=] __device__(int m, int n, const f32x4& a, int) {
;             const int tok = m * 16 + (n >> 4), ch = g * 16 + (n & 15);
;             float* yp = ybuf + (size_t)tok * 512 + ch;
;             float4 y0 = *(const float4*)yp;
;             float u[4];
;             unpack4(*(const uint2*)(proj + (size_t)tok * PROJ0_LD + 1552 + ch), u);
;             float4 d = *(const float4*)(p.s5_d + ch);
;             *(float4*)yp = make_float4(y0.x + a[0] + d.x * u[0], y0.y + a[1] + d.y * u[1], y0.z + a[2] + d.z * u[2], y0.w + a[3] + d.w * u[3]);
;           };
	v_mfma_f32_16x16x32_bf16 v[68:71], v[60:63], v[116:119], v[68:71]
	v_mfma_f32_16x16x32_bf16 v[72:75], v[60:63], v[120:123], v[72:75]
	v_mfma_f32_16x16x32_bf16 v[32:35], v[60:63], v[124:127], v[32:35]
	v_mfma_f32_16x16x32_bf16 v[60:63], v[100:103], v[112:115], v[76:79]
	v_mfma_f32_16x16x32_bf16 v[76:79], v[100:103], v[116:119], v[80:83]
	v_mfma_f32_16x16x32_bf16 v[80:83], v[100:103], v[120:123], v[84:87]
	v_mfma_f32_16x16x32_bf16 v[36:39], v[100:103], v[124:127], v[36:39]
	v_mfma_f32_16x16x32_bf16 v[84:87], v[104:107], v[112:115], v[88:91]
	v_mfma_f32_16x16x32_bf16 v[88:91], v[104:107], v[116:119], v[92:95]
	v_mfma_f32_16x16x32_bf16 v[92:95], v[104:107], v[120:123], v[96:99]
	v_mfma_f32_16x16x32_bf16 v[40:43], v[104:107], v[124:127], v[40:43]
	v_mfma_f32_16x16x32_bf16 v[48:51], v[108:111], v[112:115], v[48:51]
	v_mfma_f32_16x16x32_bf16 v[52:55], v[108:111], v[116:119], v[52:55]
	v_mfma_f32_16x16x32_bf16 v[56:59], v[108:111], v[120:123], v[56:59]
	v_mfma_f32_16x16x32_bf16 v[44:47], v[108:111], v[124:127], v[44:47]
	ds_read_b128 v[0:3], v129 offset:16384
	ds_read_b128 v[4:7], v129 offset:17408
	ds_read_b128 v[8:11], v129 offset:18432
	ds_read_b128 v[12:15], v129 offset:19456
	ds_read_b128 v[96:99], v134
	ds_read_b128 v[100:103], v134 offset:1024
	ds_read_b128 v[104:107], v134 offset:2048
	ds_read_b128 v[108:111], v134 offset:3072
	s_waitcnt vmcnt(3)
	ds_write_b128 v128, v[16:19] offset:8192
	s_waitcnt vmcnt(2)
	ds_write_b128 v128, v[20:23] offset:12288
	s_waitcnt vmcnt(1)
	ds_write_b128 v128, v[24:27] offset:24576
	s_waitcnt vmcnt(0)
	ds_write_b128 v128, v[28:31] offset:28672
	s_waitcnt lgkmcnt(0)
	v_mfma_f32_16x16x32_bf16 v[64:67], v[0:3], v[96:99], v[64:67]
	s_barrier
	v_mfma_f32_16x16x32_bf16 v[68:71], v[0:3], v[100:103], v[68:71]
	v_mfma_f32_16x16x32_bf16 v[72:75], v[0:3], v[104:107], v[72:75]
	v_mfma_f32_16x16x32_bf16 v[0:3], v[0:3], v[108:111], v[32:35]
	v_mfma_f32_16x16x32_bf16 v[32:35], v[4:7], v[96:99], v[60:63]
	v_mfma_f32_16x16x32_bf16 v[76:79], v[4:7], v[100:103], v[76:79]
	v_mfma_f32_16x16x32_bf16 v[80:83], v[4:7], v[104:107], v[80:83]
	v_mfma_f32_16x16x32_bf16 v[4:7], v[4:7], v[108:111], v[36:39]
	v_mfma_f32_16x16x32_bf16 v[84:87], v[8:11], v[96:99], v[84:87]
	v_mfma_f32_16x16x32_bf16 v[88:91], v[8:11], v[100:103], v[88:91]
	v_mfma_f32_16x16x32_bf16 v[92:95], v[8:11], v[104:107], v[92:95]
	v_mfma_f32_16x16x32_bf16 v[8:11], v[8:11], v[108:111], v[40:43]
	v_mfma_f32_16x16x32_bf16 v[96:99], v[12:15], v[96:99], v[48:51]
	v_mfma_f32_16x16x32_bf16 v[100:103], v[12:15], v[100:103], v[52:55]
	v_mfma_f32_16x16x32_bf16 v[104:107], v[12:15], v[104:107], v[56:59]
	v_mfma_f32_16x16x32_bf16 v[108:111], v[12:15], v[108:111], v[44:47]
	ds_read_b128 v[12:15], v129 offset:24576
	ds_read_b128 v[16:19], v129 offset:25600
	ds_read_b128 v[112:115], v129 offset:26624
	ds_read_b128 v[116:119], v129 offset:27648
	ds_read_b128 v[120:123], v134 offset:8192
	ds_read_b128 v[124:127], v134 offset:9216
	ds_read_b128 v[128:131], v134 offset:10240
	ds_read_b128 v[144:147], v134 offset:11264
	s_waitcnt lgkmcnt(0)
	s_barrier
	s_waitcnt vmcnt(0)
	v_mfma_f32_16x16x32_bf16 v[60:63], v[12:15], v[120:123], v[64:67]
	s_nop 2
	v_lshl_or_b32 v65, v143, 6, s9
	v_mfma_f32_16x16x32_bf16 v[52:55], v[12:15], v[128:131], v[72:75]
	v_or_b32_e32 v64, s8, v148
	s_and_b32 s8, s7, -16
	s_add_i32 s7, s7, s82
	v_lshrrev_b32_e32 v74, 4, v65
	v_lshlrev_b32_e32 v65, 10, v138
	v_lshl_add_u32 v75, v64, 4, v65
	v_mfma_f32_16x16x32_bf16 v[56:59], v[12:15], v[124:127], v[68:71]
	s_cmpk_gt_i32 s7, 0x1ff
	s_nop 1
	v_or_b32_e32 v70, v74, v75
	v_and_or_b32 v68, v140, 12, s8
	v_ashrrev_i32_e32 v71, 31, v70
	v_lshlrev_b64 v[64:65], 11, v[70:71]
	v_ashrrev_i32_e32 v69, 31, v68
	v_lshl_add_u64 v[66:67], s[2:3], 0, v[64:65]
	v_lshlrev_b64 v[64:65], 2, v[68:69]
	v_lshl_add_u64 v[72:73], v[66:67], 0, v[64:65]
	global_load_dwordx4 v[152:155], v[72:73], off
	v_mov_b64_e32 v[66:67], s[22:23]
	v_mfma_f32_16x16x32_bf16 v[40:43], v[16:19], v[124:127], v[76:79]
	s_nop 2
	v_mad_i64_i32 v[76:77], s[8:9], v70, s52, v[66:67]
	v_lshlrev_b64 v[70:71], 1, v[68:69]
	v_lshl_add_u64 v[68:69], v[76:77], 0, v[70:71]
	global_load_dwordx2 v[150:151], v[68:69], off offset:3104
	s_nop 0
	s_load_dwordx2 s[8:9], s[0:1], 0xa0
	v_mfma_f32_16x16x32_bf16 v[36:39], v[16:19], v[128:131], v[80:83]
	v_mfma_f32_16x16x32_bf16 v[28:31], v[112:115], v[120:123], v[84:87]
	v_mfma_f32_16x16x32_bf16 v[48:51], v[12:15], v[144:147], v[0:3]
	s_nop 0
	s_nop 0
	s_waitcnt vmcnt(0)
	v_lshlrev_b32_e32 v84, 16, v150
	v_and_b32_e32 v85, 0xffff0000, v150
	v_lshlrev_b32_e32 v86, 16, v151
	v_and_b32_e32 v87, 0xffff0000, v151
	s_waitcnt lgkmcnt(0)
	v_lshl_add_u64 v[68:69], s[8:9], 0, v[64:65]
	global_load_dwordx4 v[156:159], v[68:69], off
	global_load_dwordx4 v[160:163], v[68:69], off
	global_load_dwordx4 v[164:167], v[68:69], off
	global_load_dwordx4 v[168:171], v[68:69], off
	global_load_dwordx4 v[172:175], v[68:69], off
	global_load_dwordx4 v[176:179], v[68:69], off
	global_load_dwordx4 v[180:183], v[68:69], off
	global_load_dwordx4 v[184:187], v[68:69], off
	global_load_dwordx4 v[188:191], v[68:69], off
	global_load_dwordx4 v[192:195], v[68:69], off
	global_load_dwordx4 v[220:223], v[68:69], off
	global_load_dwordx4 v[224:227], v[68:69], off
	global_load_dwordx4 v[232:235], v[68:69], off
	global_load_dwordx4 v[236:239], v[68:69], off
	global_load_dwordx4 v[240:243], v[68:69], off
	global_load_dwordx4 v[244:247], v[68:69], off
	s_nop 0
	s_nop 0
	v_mfma_f32_16x16x32_bf16 v[44:47], v[16:19], v[120:123], v[32:35]
	s_nop 0
	v_pk_add_f32 v[60:61], v[60:61], v[152:153]
	v_pk_add_f32 v[62:63], v[62:63], v[154:155]
	s_nop 0
	s_waitcnt vmcnt(15)
; __device__ __forceinline__ void unpack4(uint2 u, float* f) { f[0] = bflo(u.x); f[1] = bfhi(u.x); f[2] = bflo(u.y); f[3] = bfhi(u.y); }
;   __device__ __forceinline__ void operator()(f32x4 (&acc)[4][4], int mw, int nw, int lane, int nt) const {
; #pragma unroll
;     for (int i = 0; i < 4; i++)
; #pragma unroll
;       for (int j = 0; j < 4; j++) f(mw + j * 16 + (lane & 15), nw + i * 16 + (lane >> 4) * 4, acc[i][j], nt);
; __global__ void __launch_bounds__(NTHR, 2) mega(P p, int ph_lo, int ph_hi) {
;     ...
;           auto f = [=] __device__(int m, int n, const f32x4& a, int) {
;             const int tok = m * 16 + (n >> 4), ch = g * 16 + (n & 15);
;             float* yp = ybuf + (size_t)tok * 512 + ch;
;             float4 y0 = *(const float4*)yp;
;             float u[4];
;             unpack4(*(const uint2*)(proj + (size_t)tok * PROJ0_LD + 1552 + ch), u);
;             float4 d = *(const float4*)(p.s5_d + ch);
;             *(float4*)yp = make_float4(y0.x + a[0] + d.x * u[0], y0.y + a[1] + d.y * u[1], y0.z + a[2] + d.z * u[2], y0.w + a[3] + d.w * u[3]);
;           };
	v_pk_fma_f32 v[60:61], v[156:157], v[84:85], v[60:61]
	v_pk_fma_f32 v[62:63], v[158:159], v[86:87], v[62:63]
	global_store_dwordx4 v[72:73], v[60:63], off
	v_mfma_f32_16x16x32_bf16 v[32:35], v[16:19], v[144:147], v[4:7]
	s_nop 0
	v_or_b32_e32 v60, 0x100, v75
	v_or_b32_e32 v62, v60, v74
	v_ashrrev_i32_e32 v63, 31, v62
	v_lshlrev_b64 v[72:73], 11, v[62:63]
	v_mad_i64_i32 v[62:63], s[8:9], v62, s52, v[66:67]
	v_lshl_add_u64 v[72:73], s[2:3], 0, v[72:73]
	v_lshl_add_u64 v[62:63], v[62:63], 0, v[70:71]
	v_lshl_add_u64 v[72:73], v[72:73], 0, v[64:65]
	global_load_dwordx4 v[150:153], v[72:73], off
	global_load_dwordx2 v[62:63], v[62:63], off offset:3104
	s_nop 0
	s_nop 0
	s_nop 0
	v_mfma_f32_16x16x32_bf16 v[24:27], v[112:115], v[124:127], v[88:91]
	s_nop 0
	s_waitcnt vmcnt(0)
	v_lshlrev_b32_e32 v84, 16, v62
	v_and_b32_e32 v85, 0xffff0000, v62
	v_lshlrev_b32_e32 v62, 16, v63
	v_and_b32_e32 v63, 0xffff0000, v63
	s_nop 0
	v_pk_add_f32 v[56:57], v[56:57], v[150:151]
	v_pk_add_f32 v[58:59], v[58:59], v[152:153]
	s_nop 0
	v_pk_fma_f32 v[56:57], v[160:161], v[84:85], v[56:57]
	v_pk_fma_f32 v[58:59], v[162:163], v[62:63], v[58:59]
	global_store_dwordx4 v[72:73], v[56:59], off
	v_mfma_f32_16x16x32_bf16 v[20:23], v[112:115], v[128:131], v[92:95]
	s_nop 0
	v_or_b32_e32 v56, 0x200, v75
	v_or_b32_e32 v58, v56, v74
	v_ashrrev_i32_e32 v59, 31, v58
	v_lshlrev_b64 v[62:63], 11, v[58:59]
	v_mad_i64_i32 v[58:59], s[8:9], v58, s52, v[66:67]
	v_lshl_add_u64 v[62:63], s[2:3], 0, v[62:63]
	v_lshl_add_u64 v[58:59], v[58:59], 0, v[70:71]
	v_lshl_add_u64 v[62:63], v[62:63], 0, v[64:65]
	global_load_dwordx4 v[150:153], v[62:63], off
	global_load_dwordx2 v[58:59], v[58:59], off offset:3104
	s_nop 0
	s_nop 0
	s_nop 0
	v_mfma_f32_16x16x32_bf16 v[16:19], v[112:115], v[144:147], v[8:11]
	s_nop 0
	s_waitcnt vmcnt(0)
	v_lshlrev_b32_e32 v72, 16, v58
	v_and_b32_e32 v73, 0xffff0000, v58
	v_lshlrev_b32_e32 v58, 16, v59
	v_and_b32_e32 v59, 0xffff0000, v59
	s_nop 0
	v_pk_add_f32 v[52:53], v[52:53], v[150:151]
	v_pk_add_f32 v[54:55], v[54:55], v[152:153]
	s_nop 0
	v_pk_fma_f32 v[52:53], v[164:165], v[72:73], v[52:53]
	v_pk_fma_f32 v[54:55], v[166:167], v[58:59], v[54:55]
	global_store_dwordx4 v[62:63], v[52:55], off
	v_mfma_f32_16x16x32_bf16 v[12:15], v[116:119], v[120:123], v[96:99]
	s_nop 0
	v_or_b32_e32 v52, 0x300, v75
	v_or_b32_e32 v54, v52, v74
	v_ashrrev_i32_e32 v55, 31, v54
	v_lshlrev_b64 v[58:59], 11, v[54:55]
	v_mad_i64_i32 v[54:55], s[8:9], v54, s52, v[66:67]
	v_lshl_add_u64 v[58:59], s[2:3], 0, v[58:59]
	v_lshl_add_u64 v[54:55], v[54:55], 0, v[70:71]
	v_lshl_add_u64 v[58:59], v[58:59], 0, v[64:65]
	global_load_dwordx4 v[150:153], v[58:59], off
	global_load_dwordx2 v[54:55], v[54:55], off offset:3104
	s_nop 0
	s_nop 0
	s_nop 0
	v_mfma_f32_16x16x32_bf16 v[8:11], v[116:119], v[124:127], v[100:103]
	s_nop 0
	s_waitcnt vmcnt(0)
	v_lshlrev_b32_e32 v62, 16, v54
	v_and_b32_e32 v63, 0xffff0000, v54
	v_lshlrev_b32_e32 v54, 16, v55
	v_and_b32_e32 v55, 0xffff0000, v55
	s_nop 0
	v_pk_add_f32 v[48:49], v[48:49], v[150:151]
	v_pk_add_f32 v[50:51], v[50:51], v[152:153]
	s_nop 0
	v_pk_fma_f32 v[48:49], v[168:169], v[62:63], v[48:49]
	v_pk_fma_f32 v[50:51], v[170:171], v[54:55], v[50:51]
	global_store_dwordx4 v[58:59], v[48:51], off
	v_mfma_f32_16x16x32_bf16 v[4:7], v[116:119], v[128:131], v[104:107]
	s_nop 0
	v_or_b32_e32 v48, 1, v74
	v_or_b32_e32 v50, v48, v75
	v_ashrrev_i32_e32 v51, 31, v50
	v_lshlrev_b64 v[54:55], 11, v[50:51]
	v_mad_i64_i32 v[50:51], s[8:9], v50, s52, v[66:67]
	v_lshl_add_u64 v[54:55], s[2:3], 0, v[54:55]
	v_lshl_add_u64 v[50:51], v[50:51], 0, v[70:71]
	v_lshl_add_u64 v[54:55], v[54:55], 0, v[64:65]
	global_load_dwordx4 v[150:153], v[54:55], off
	global_load_dwordx2 v[50:51], v[50:51], off offset:3104
	s_nop 0
	s_nop 0
	s_nop 0
	v_mfma_f32_16x16x32_bf16 v[0:3], v[116:119], v[144:147], v[108:111]
	s_nop 0
	s_waitcnt vmcnt(0)
	v_lshlrev_b32_e32 v58, 16, v50
	v_and_b32_e32 v59, 0xffff0000, v50
	v_lshlrev_b32_e32 v50, 16, v51
	v_and_b32_e32 v51, 0xffff0000, v51
	s_nop 0
	v_pk_add_f32 v[44:45], v[44:45], v[150:151]
	v_pk_add_f32 v[46:47], v[46:47], v[152:153]
	s_nop 0
	v_pk_fma_f32 v[44:45], v[172:173], v[58:59], v[44:45]
	v_pk_fma_f32 v[46:47], v[174:175], v[50:51], v[46:47]
	global_store_dwordx4 v[54:55], v[44:47], off
	s_nop 1
	v_or_b32_e32 v46, v48, v60
	v_ashrrev_i32_e32 v47, 31, v46
	v_lshlrev_b64 v[44:45], 11, v[46:47]
	v_mad_i64_i32 v[46:47], s[8:9], v46, s52, v[66:67]
	v_lshl_add_u64 v[44:45], s[2:3], 0, v[44:45]
	v_lshl_add_u64 v[46:47], v[46:47], 0, v[70:71]
	v_lshl_add_u64 v[44:45], v[44:45], 0, v[64:65]
	global_load_dwordx4 v[150:153], v[44:45], off
	global_load_dwordx2 v[46:47], v[46:47], off offset:3104
	s_nop 0
	s_nop 0
	s_nop 0
	s_nop 0
	s_waitcnt vmcnt(0)
	v_lshlrev_b32_e32 v50, 16, v46
	v_and_b32_e32 v51, 0xffff0000, v46
	v_lshlrev_b32_e32 v46, 16, v47
	v_and_b32_e32 v47, 0xffff0000, v47
	s_nop 0
	v_pk_add_f32 v[40:41], v[40:41], v[150:151]
	v_pk_add_f32 v[42:43], v[42:43], v[152:153]
	v_mov_b32_e32 v76, v150
	v_mov_b32_e32 v77, v151
	v_mov_b32_e32 v78, v152
	v_mov_b32_e32 v79, v153
	s_nop 0
	v_pk_fma_f32 v[40:41], v[176:177], v[50:51], v[40:41]
	v_pk_fma_f32 v[42:43], v[178:179], v[46:47], v[42:43]
	v_mov_b32_e32 v80, v176
	v_mov_b32_e32 v81, v177
	v_mov_b32_e32 v82, v178
	v_mov_b32_e32 v83, v179
	global_store_dwordx4 v[44:45], v[40:43], off
	s_nop 1
	v_or_b32_e32 v40, v48, v56
	v_ashrrev_i32_e32 v41, 31, v40
	v_lshlrev_b64 v[42:43], 11, v[40:41]
	v_mad_i64_i32 v[40:41], s[8:9], v40, s52, v[66:67]
	v_lshl_add_u64 v[40:41], v[40:41], 0, v[70:71]
	global_load_dwordx2 v[150:151], v[40:41], off offset:3104
	s_nop 0
	v_lshl_add_u64 v[42:43], s[2:3], 0, v[42:43]
	v_lshl_add_u64 v[50:51], v[42:43], 0, v[64:65]
	global_load_dwordx4 v[152:155], v[50:51], off
	s_nop 0
	s_waitcnt vmcnt(1)
; __device__ __forceinline__ void unpack4(uint2 u, float* f) { f[0] = bflo(u.x); f[1] = bfhi(u.x); f[2] = bflo(u.y); f[3] = bfhi(u.y); }
;   __device__ __forceinline__ void operator()(f32x4 (&acc)[4][4], int mw, int nw, int lane, int nt) const {
; #pragma unroll
;     for (int i = 0; i < 4; i++)
; #pragma unroll
;       for (int j = 0; j < 4; j++) f(mw + j * 16 + (lane & 15), nw + i * 16 + (lane >> 4) * 4, acc[i][j], nt);
; __global__ void __launch_bounds__(NTHR, 2) mega(P p, int ph_lo, int ph_hi) {
;     ...
;           auto f = [=] __device__(int m, int n, const f32x4& a, int) {
;             const int tok = m * 16 + (n >> 4), ch = g * 16 + (n & 15);
;             float* yp = ybuf + (size_t)tok * 512 + ch;
;             float4 y0 = *(const float4*)yp;
;             float u[4];
;             unpack4(*(const uint2*)(proj + (size_t)tok * PROJ0_LD + 1552 + ch), u);
;             float4 d = *(const float4*)(p.s5_d + ch);
;             *(float4*)yp = make_float4(y0.x + a[0] + d.x * u[0], y0.y + a[1] + d.y * u[1], y0.z + a[2] + d.z * u[2], y0.w + a[3] + d.w * u[3]);
;           };
	v_lshlrev_b32_e32 v54, 16, v150
	v_and_b32_e32 v55, 0xffff0000, v150
	v_lshlrev_b32_e32 v58, 16, v151
	v_and_b32_e32 v59, 0xffff0000, v151
	s_nop 0
	s_nop 0
	s_nop 0
	s_waitcnt vmcnt(0)
	v_pk_add_f32 v[36:37], v[36:37], v[152:153]
	v_pk_add_f32 v[38:39], v[38:39], v[154:155]
	s_nop 0
	v_pk_fma_f32 v[36:37], v[180:181], v[54:55], v[36:37]
	v_pk_fma_f32 v[38:39], v[182:183], v[58:59], v[38:39]
	global_store_dwordx4 v[50:51], v[36:39], off
	s_nop 1
	v_or_b32_e32 v36, v48, v52
	v_ashrrev_i32_e32 v37, 31, v36
	v_lshlrev_b64 v[38:39], 11, v[36:37]
	v_mad_i64_i32 v[36:37], s[8:9], v36, s52, v[66:67]
	v_lshl_add_u64 v[36:37], v[36:37], 0, v[70:71]
	global_load_dwordx2 v[150:151], v[36:37], off offset:3104
	s_nop 0
	v_lshl_add_u64 v[38:39], s[2:3], 0, v[38:39]
	v_lshl_add_u64 v[44:45], v[38:39], 0, v[64:65]
	global_load_dwordx4 v[152:155], v[44:45], off
	s_nop 0
	s_waitcnt vmcnt(1)
	v_lshlrev_b32_e32 v46, 16, v150
	v_and_b32_e32 v47, 0xffff0000, v150
	v_lshlrev_b32_e32 v48, 16, v151
	v_and_b32_e32 v49, 0xffff0000, v151
	s_nop 0
	s_nop 0
	s_nop 0
	s_waitcnt vmcnt(0)
	v_pk_add_f32 v[32:33], v[32:33], v[152:153]
	v_pk_add_f32 v[34:35], v[34:35], v[154:155]
	s_nop 0
	v_pk_fma_f32 v[32:33], v[184:185], v[46:47], v[32:33]
	v_pk_fma_f32 v[34:35], v[186:187], v[48:49], v[34:35]
	v_or_b32_e32 v46, 2, v74
	global_store_dwordx4 v[44:45], v[32:35], off
	s_nop 1
	v_or_b32_e32 v32, v46, v75
	v_ashrrev_i32_e32 v33, 31, v32
	v_lshlrev_b64 v[34:35], 11, v[32:33]
	v_mad_i64_i32 v[32:33], s[8:9], v32, s52, v[66:67]
	v_lshl_add_u64 v[32:33], v[32:33], 0, v[70:71]
	global_load_dwordx2 v[150:151], v[32:33], off offset:3104
	s_nop 0
	v_lshl_add_u64 v[34:35], s[2:3], 0, v[34:35]
	v_lshl_add_u64 v[40:41], v[34:35], 0, v[64:65]
	global_load_dwordx4 v[152:155], v[40:41], off
	s_nop 0
	s_waitcnt vmcnt(1)
	v_lshlrev_b32_e32 v42, 16, v150
	v_and_b32_e32 v43, 0xffff0000, v150
	v_lshlrev_b32_e32 v44, 16, v151
	v_and_b32_e32 v45, 0xffff0000, v151
	s_nop 0
	s_nop 0
	s_nop 0
	s_waitcnt vmcnt(0)
	v_pk_add_f32 v[28:29], v[28:29], v[152:153]
	v_pk_add_f32 v[30:31], v[30:31], v[154:155]
	s_nop 0
	v_pk_fma_f32 v[28:29], v[188:189], v[42:43], v[28:29]
	v_pk_fma_f32 v[30:31], v[190:191], v[44:45], v[30:31]
	global_store_dwordx4 v[40:41], v[28:31], off
	s_nop 1
	v_or_b32_e32 v28, v46, v60
	v_ashrrev_i32_e32 v29, 31, v28
	v_lshlrev_b64 v[30:31], 11, v[28:29]
	v_mad_i64_i32 v[28:29], s[8:9], v28, s52, v[66:67]
	v_lshl_add_u64 v[28:29], v[28:29], 0, v[70:71]
	global_load_dwordx2 v[150:151], v[28:29], off offset:3104
	s_nop 0
	v_lshl_add_u64 v[30:31], s[2:3], 0, v[30:31]
	v_lshl_add_u64 v[36:37], v[30:31], 0, v[64:65]
	global_load_dwordx4 v[152:155], v[36:37], off
	s_nop 0
	s_waitcnt vmcnt(1)
	v_lshlrev_b32_e32 v38, 16, v150
	v_and_b32_e32 v39, 0xffff0000, v150
	v_lshlrev_b32_e32 v40, 16, v151
	v_and_b32_e32 v41, 0xffff0000, v151
	s_nop 0
	s_nop 0
	s_nop 0
	s_waitcnt vmcnt(0)
	v_pk_add_f32 v[24:25], v[24:25], v[152:153]
	v_pk_add_f32 v[26:27], v[26:27], v[154:155]
	s_nop 0
	v_pk_fma_f32 v[24:25], v[192:193], v[38:39], v[24:25]
	v_pk_fma_f32 v[26:27], v[194:195], v[40:41], v[26:27]
	global_store_dwordx4 v[36:37], v[24:27], off
	s_nop 1
	v_or_b32_e32 v24, v46, v56
	v_ashrrev_i32_e32 v25, 31, v24
	v_lshlrev_b64 v[26:27], 11, v[24:25]
	v_mad_i64_i32 v[24:25], s[8:9], v24, s52, v[66:67]
	v_lshl_add_u64 v[24:25], v[24:25], 0, v[70:71]
	global_load_dwordx2 v[150:151], v[24:25], off offset:3104
	s_nop 0
	v_lshl_add_u64 v[26:27], s[2:3], 0, v[26:27]
	v_lshl_add_u64 v[32:33], v[26:27], 0, v[64:65]
	global_load_dwordx4 v[152:155], v[32:33], off
	s_nop 0
	s_waitcnt vmcnt(1)
	v_lshlrev_b32_e32 v34, 16, v150
	v_and_b32_e32 v35, 0xffff0000, v150
	v_lshlrev_b32_e32 v36, 16, v151
	v_and_b32_e32 v37, 0xffff0000, v151
	s_nop 0
	s_nop 0
	s_nop 0
	s_waitcnt vmcnt(0)
	v_pk_add_f32 v[20:21], v[20:21], v[152:153]
	v_pk_add_f32 v[22:23], v[22:23], v[154:155]
	s_nop 0
	v_pk_fma_f32 v[20:21], v[220:221], v[34:35], v[20:21]
	v_pk_fma_f32 v[22:23], v[222:223], v[36:37], v[22:23]
	global_store_dwordx4 v[32:33], v[20:23], off
	s_nop 1
	v_or_b32_e32 v20, v46, v52
	v_ashrrev_i32_e32 v21, 31, v20
	v_lshlrev_b64 v[22:23], 11, v[20:21]
	v_mad_i64_i32 v[20:21], s[8:9], v20, s52, v[66:67]
	v_lshl_add_u64 v[20:21], v[20:21], 0, v[70:71]
	global_load_dwordx2 v[150:151], v[20:21], off offset:3104
	s_nop 0
	v_lshl_add_u64 v[22:23], s[2:3], 0, v[22:23]
	v_lshl_add_u64 v[28:29], v[22:23], 0, v[64:65]
	global_load_dwordx4 v[152:155], v[28:29], off
	s_nop 0
	s_waitcnt vmcnt(1)
; __device__ __forceinline__ void unpack4(uint2 u, float* f) { f[0] = bflo(u.x); f[1] = bfhi(u.x); f[2] = bflo(u.y); f[3] = bfhi(u.y); }
;   __device__ __forceinline__ void operator()(f32x4 (&acc)[4][4], int mw, int nw, int lane, int nt) const {
; #pragma unroll
;     for (int i = 0; i < 4; i++)
; #pragma unroll
;       for (int j = 0; j < 4; j++) f(mw + j * 16 + (lane & 15), nw + i * 16 + (lane >> 4) * 4, acc[i][j], nt);
; __global__ void __launch_bounds__(NTHR, 2) mega(P p, int ph_lo, int ph_hi) {
;     ...
;           auto f = [=] __device__(int m, int n, const f32x4& a, int) {
;             const int tok = m * 16 + (n >> 4), ch = g * 16 + (n & 15);
;             float* yp = ybuf + (size_t)tok * 512 + ch;
;             float4 y0 = *(const float4*)yp;
;             float u[4];
;             unpack4(*(const uint2*)(proj + (size_t)tok * PROJ0_LD + 1552 + ch), u);
;             float4 d = *(const float4*)(p.s5_d + ch);
;             *(float4*)yp = make_float4(y0.x + a[0] + d.x * u[0], y0.y + a[1] + d.y * u[1], y0.z + a[2] + d.z * u[2], y0.w + a[3] + d.w * u[3]);
;           };
	v_lshlrev_b32_e32 v30, 16, v150
	v_and_b32_e32 v31, 0xffff0000, v150
	v_lshlrev_b32_e32 v32, 16, v151
	v_and_b32_e32 v33, 0xffff0000, v151
	s_nop 0
	s_nop 0
	s_nop 0
	s_waitcnt vmcnt(0)
	v_pk_add_f32 v[16:17], v[16:17], v[152:153]
	v_pk_add_f32 v[18:19], v[18:19], v[154:155]
	s_nop 0
	v_pk_fma_f32 v[16:17], v[224:225], v[30:31], v[16:17]
	v_pk_fma_f32 v[18:19], v[226:227], v[32:33], v[18:19]
	v_or_b32_e32 v30, 3, v74
	global_store_dwordx4 v[28:29], v[16:19], off
	s_nop 1
	v_or_b32_e32 v16, v30, v75
	v_ashrrev_i32_e32 v17, 31, v16
	v_lshlrev_b64 v[18:19], 11, v[16:17]
	v_mad_i64_i32 v[16:17], s[8:9], v16, s52, v[66:67]
	v_lshl_add_u64 v[16:17], v[16:17], 0, v[70:71]
	global_load_dwordx2 v[150:151], v[16:17], off offset:3104
	s_nop 0
	v_lshl_add_u64 v[18:19], s[2:3], 0, v[18:19]
	v_lshl_add_u64 v[24:25], v[18:19], 0, v[64:65]
	global_load_dwordx4 v[152:155], v[24:25], off
	s_nop 0
	s_waitcnt vmcnt(1)
	v_lshlrev_b32_e32 v26, 16, v150
	v_and_b32_e32 v27, 0xffff0000, v150
	v_lshlrev_b32_e32 v28, 16, v151
	v_and_b32_e32 v29, 0xffff0000, v151
	s_nop 0
	s_nop 0
	s_nop 0
	s_waitcnt vmcnt(0)
	v_pk_add_f32 v[12:13], v[12:13], v[152:153]
	v_pk_add_f32 v[14:15], v[14:15], v[154:155]
	s_nop 0
	v_pk_fma_f32 v[12:13], v[232:233], v[26:27], v[12:13]
	v_pk_fma_f32 v[14:15], v[234:235], v[28:29], v[14:15]
	global_store_dwordx4 v[24:25], v[12:15], off
	s_nop 1
	v_or_b32_e32 v12, v30, v60
	v_ashrrev_i32_e32 v13, 31, v12
	v_lshlrev_b64 v[14:15], 11, v[12:13]
	v_mad_i64_i32 v[12:13], s[8:9], v12, s52, v[66:67]
	v_lshl_add_u64 v[12:13], v[12:13], 0, v[70:71]
	global_load_dwordx2 v[150:151], v[12:13], off offset:3104
	s_nop 0
	v_lshl_add_u64 v[14:15], s[2:3], 0, v[14:15]
	v_lshl_add_u64 v[20:21], v[14:15], 0, v[64:65]
	global_load_dwordx4 v[152:155], v[20:21], off
	s_nop 0
	s_waitcnt vmcnt(1)
	v_lshlrev_b32_e32 v22, 16, v150
	v_and_b32_e32 v23, 0xffff0000, v150
	v_lshlrev_b32_e32 v24, 16, v151
	v_and_b32_e32 v25, 0xffff0000, v151
	s_nop 0
	s_nop 0
	s_nop 0
	s_waitcnt vmcnt(0)
	v_pk_add_f32 v[8:9], v[8:9], v[152:153]
	v_pk_add_f32 v[10:11], v[10:11], v[154:155]
	s_nop 0
	v_pk_fma_f32 v[8:9], v[236:237], v[22:23], v[8:9]
	v_pk_fma_f32 v[10:11], v[238:239], v[24:25], v[10:11]
	global_store_dwordx4 v[20:21], v[8:11], off
	s_nop 1
	v_or_b32_e32 v8, v30, v56
	v_ashrrev_i32_e32 v9, 31, v8
	v_lshlrev_b64 v[10:11], 11, v[8:9]
	v_mad_i64_i32 v[8:9], s[8:9], v8, s52, v[66:67]
	v_lshl_add_u64 v[8:9], v[8:9], 0, v[70:71]
	global_load_dwordx2 v[150:151], v[8:9], off offset:3104
	s_nop 0
	v_lshl_add_u64 v[10:11], s[2:3], 0, v[10:11]
	v_lshl_add_u64 v[16:17], v[10:11], 0, v[64:65]
	global_load_dwordx4 v[152:155], v[16:17], off
	s_nop 0
	s_waitcnt vmcnt(1)
	v_lshlrev_b32_e32 v18, 16, v150
	v_and_b32_e32 v19, 0xffff0000, v150
	v_lshlrev_b32_e32 v20, 16, v151
	v_and_b32_e32 v21, 0xffff0000, v151
	s_nop 0
	s_nop 0
	s_nop 0
	s_waitcnt vmcnt(0)
	v_pk_add_f32 v[4:5], v[4:5], v[152:153]
	v_pk_add_f32 v[6:7], v[6:7], v[154:155]
	s_nop 0
	v_pk_fma_f32 v[4:5], v[240:241], v[18:19], v[4:5]
	v_pk_fma_f32 v[6:7], v[242:243], v[20:21], v[6:7]
	global_store_dwordx4 v[16:17], v[4:7], off
	s_nop 1
	v_or_b32_e32 v4, v30, v52
	v_ashrrev_i32_e32 v5, 31, v4
	v_lshlrev_b64 v[6:7], 11, v[4:5]
	v_mad_i64_i32 v[4:5], s[8:9], v4, s52, v[66:67]
	v_lshl_add_u64 v[4:5], v[4:5], 0, v[70:71]
	global_load_dwordx2 v[150:151], v[4:5], off offset:3104
	s_nop 0
	v_lshl_add_u64 v[6:7], s[2:3], 0, v[6:7]
	v_lshl_add_u64 v[12:13], v[6:7], 0, v[64:65]
	global_load_dwordx4 v[152:155], v[12:13], off
	s_nop 0
	s_waitcnt vmcnt(1)
	v_lshlrev_b32_e32 v14, 16, v150
	v_and_b32_e32 v15, 0xffff0000, v150
	v_lshlrev_b32_e32 v16, 16, v151
	v_and_b32_e32 v17, 0xffff0000, v151
	s_nop 0
	s_nop 0
	s_nop 0
	s_waitcnt vmcnt(0)
	v_pk_add_f32 v[0:1], v[0:1], v[152:153]
	v_pk_add_f32 v[2:3], v[2:3], v[154:155]
	v_mov_b32_e32 v4, v152
	v_mov_b32_e32 v5, v153
	v_mov_b32_e32 v6, v154
	v_mov_b32_e32 v7, v155
	s_nop 0
	v_pk_fma_f32 v[0:1], v[244:245], v[14:15], v[0:1]
	v_pk_fma_f32 v[2:3], v[246:247], v[16:17], v[2:3]
	v_mov_b32_e32 v8, v244
	v_mov_b32_e32 v9, v245
	v_mov_b32_e32 v10, v246
	v_mov_b32_e32 v11, v247
	global_store_dwordx4 v[12:13], v[0:3], off
	s_cbranch_scc0 .LBB0_347

; #define MFMA16(a, b, c) __builtin_amdgcn_mfma_f32_16x16x32_bf16((a), (b), (c), 0, 0, 0)
; __device__ __forceinline__ void gla_out_job(const P& p, int job, char* smc) {
;     ...
;   f32x4 O[8];
; #pragma unroll
;   for (int i = 0; i < 8; i++) O[i] = (f32x4){0.f, 0.f, 0.f, 0.f};
; #pragma unroll
;   for (int kb = 0; kb < 2; kb++) {
;     union { bf16x8 v; unsigned u[4]; } pb;
;     pb.u[0] = pack2(S[2 * kb][0], S[2 * kb][1]); pb.u[1] = pack2(S[2 * kb][2], S[2 * kb][3]);
;     pb.u[2] = pack2(S[2 * kb + 1][0], S[2 * kb + 1][1]); pb.u[3] = pack2(S[2 * kb + 1][2], S[2 * kb + 1][3]);
; #pragma unroll
;     for (int vt = 0; vt < 8; vt++) {
;       union { bf16x8 v; uint2 h[2]; } va;
;       const u16* vr = VtL + (vt * 16 + (lane & 15)) * GL_ST + kb * 32 + (lane >> 4) * 4;
;       va.h[0] = *(const uint2*)vr;
;       va.h[1] = *(const uint2*)(vr + 16);
;       O[vt] = MFMA16(va.v, pb.v, O[vt]);
;     }
;   }
;   const float* sp = stbuf + ((size_t)((b * 4 + h) * 64 + c)) * 8192;
; #pragma unroll
;   for (int vt = 0; vt < 8; vt++) {
;     const float* sr = sp + (vt * 16 + (lane & 15)) * 64 + (lane >> 4) * 8;
;     float f[8];
;     float4 a0 = *(const float4*)sr, a1 = *(const float4*)(sr + 4);
;     f[0] = a0.x; f[1] = a0.y; f[2] = a0.z; f[3] = a0.w; f[4] = a1.x; f[5] = a1.y; f[6] = a1.z; f[7] = a1.w;
;     O[vt] = MFMA16(pack8(f), qf0, O[vt]);
;     a0 = *(const float4*)(sr + 32); a1 = *(const float4*)(sr + 36);
;     f[0] = a0.x; f[1] = a0.y; f[2] = a0.z; f[3] = a0.w; f[4] = a1.x; f[5] = a1.y; f[6] = a1.z; f[7] = a1.w;
;     O[vt] = MFMA16(pack8(f), qf1, O[vt]);
.LBB0_388:
	s_or_b64 exec, exec, s[6:7]
	s_waitcnt vmcnt(0)
	v_add_u32_e32 v29, v28, v20
	v_add_u32_e32 v40, 0x9800, v29
	ds_read2_b64 v[24:27], v40 offset0:64 offset1:68
	v_cvt_pk_bf16_f32 v4, v4, v5
	v_cvt_pk_bf16_f32 v5, v6, v7
	v_cvt_pk_bf16_f32 v6, v16, v17
	v_cvt_pk_bf16_f32 v7, v18, v19
	v_add_u32_e32 v41, 0xa000, v29
	v_add_u32_e32 v45, 0xa800, v29
	v_add_u32_e32 v74, 0xb000, v29
	v_add_u32_e32 v75, 0xb800, v29
	s_waitcnt lgkmcnt(0)
	v_mfma_f32_16x16x32_bf16 v[36:39], v[24:27], v[4:7], 0
	ds_read2_b64 v[24:27], v41 offset0:96 offset1:100
	v_add_u32_e32 v30, 0x8800, v29
	v_add_u32_e32 v31, 0x9000, v29
	v_add_u32_e32 v29, 0xc000, v29
	ds_read2_b64 v[16:19], v30 offset1:4
	ds_read2_b64 v[20:23], v31 offset0:32 offset1:36
	s_waitcnt lgkmcnt(1)
	v_mfma_f32_16x16x32_bf16 v[16:19], v[16:19], v[4:7], 0
	v_cvt_pk_bf16_f32 v66, v12, v13
	v_cvt_pk_bf16_f32 v67, v14, v15
	v_cvt_pk_bf16_f32 v68, v8, v9
	v_mfma_f32_16x16x32_bf16 v[46:49], v[24:27], v[4:7], 0
	ds_read2_b64 v[24:27], v45 offset0:128 offset1:132
	v_cvt_pk_bf16_f32 v69, v10, v11
	s_and_b32 s4, s14, 0xffffff00
	s_waitcnt lgkmcnt(0)
	v_mfma_f32_16x16x32_bf16 v[50:53], v[24:27], v[4:7], 0
	ds_read2_b64 v[24:27], v74 offset0:160 offset1:164
	s_or_b32 s4, s16, s4
	s_or_b32 s6, s4, s17
	s_waitcnt lgkmcnt(0)
	v_mfma_f32_16x16x32_bf16 v[54:57], v[24:27], v[4:7], 0
	ds_read2_b64 v[24:27], v75 offset0:192 offset1:196
	s_ashr_i32 s7, s6, 31
	s_lshl_b64 s[6:7], s[6:7], 15
	s_waitcnt lgkmcnt(0)
	v_mfma_f32_16x16x32_bf16 v[58:61], v[24:27], v[4:7], 0
	ds_read2_b64 v[24:27], v29 offset0:224 offset1:228
	s_add_u32 s6, s56, s6
	s_addc_u32 s7, s57, s7
	v_mfma_f32_16x16x32_bf16 v[20:23], v[20:23], v[4:7], 0
	v_lshlrev_b32_e32 v134, 2, v28
	s_movk_i32 s4, 0x1000
	s_waitcnt lgkmcnt(0)
	v_mfma_f32_16x16x32_bf16 v[62:65], v[24:27], v[4:7], 0
	ds_read2_b64 v[4:7], v30 offset0:8 offset1:12
	s_waitcnt lgkmcnt(0)
	v_mfma_f32_16x16x32_bf16 v[70:73], v[4:7], v[66:69], v[16:19]
	ds_read2_b64 v[4:7], v31 offset0:40 offset1:44
	s_waitcnt lgkmcnt(0)
	v_mfma_f32_16x16x32_bf16 v[24:27], v[4:7], v[66:69], v[20:23]
	ds_read2_b64 v[4:7], v40 offset0:72 offset1:76
	s_waitcnt lgkmcnt(0)
	v_mfma_f32_16x16x32_bf16 v[20:23], v[4:7], v[66:69], v[36:39]
	ds_read2_b64 v[4:7], v41 offset0:104 offset1:108
	s_nop 1
	ds_read2_b64 v[36:39], v29 offset0:232 offset1:236
	v_lshl_add_u64 v[28:29], s[6:7], 0, v[134:135]
	s_waitcnt lgkmcnt(1)
	v_mfma_f32_16x16x32_bf16 v[16:19], v[4:7], v[66:69], v[46:49]
	ds_read2_b64 v[4:7], v45 offset0:136 offset1:140
	v_lshlrev_b32_e32 v134, 8, v44
	v_lshl_add_u64 v[40:41], v[28:29], 0, v[134:135]
	global_load_dwordx4 v[144:147], v[40:41], off offset:16
	global_load_dwordx4 v[148:151], v[40:41], off offset:144
	s_waitcnt lgkmcnt(0)
	v_mfma_f32_16x16x32_bf16 v[12:15], v[4:7], v[66:69], v[50:53]
	ds_read2_b64 v[4:7], v74 offset0:168 offset1:172
	s_mov_b64 s[6:7], 0x1000
	v_lshlrev_b32_e32 v134, 1, v42
	s_waitcnt lgkmcnt(0)
	v_mfma_f32_16x16x32_bf16 v[8:11], v[4:7], v[66:69], v[54:57]
	ds_read2_b64 v[4:7], v75 offset0:200 offset1:204
	s_nop 0
	global_load_dwordx4 v[46:49], v[40:41], off
	v_add_co_u32_e32 v54, vcc, s4, v40
	s_movk_i32 s4, 0x3000
	s_nop 0
	v_addc_co_u32_e32 v55, vcc, 0, v41, vcc
	v_add_co_u32_e32 v56, vcc, s83, v40
	s_waitcnt lgkmcnt(0)
	v_mfma_f32_16x16x32_bf16 v[4:7], v[4:7], v[66:69], v[58:61]
	v_addc_co_u32_e32 v57, vcc, 0, v41, vcc
	s_nop 0
	s_waitcnt vmcnt(0)
	v_cvt_pk_bf16_f32 v46, v46, v47
	v_cvt_pk_bf16_f32 v47, v48, v49
	v_cvt_pk_bf16_f32 v48, v144, v145
	v_cvt_pk_bf16_f32 v49, v146, v147
	v_mfma_f32_16x16x32_bf16 v[36:39], v[36:39], v[66:69], v[62:65]
	s_nop 0
	v_mfma_f32_16x16x32_bf16 v[28:31], v[46:49], v[32:35], v[70:73]
	s_nop 0
	global_load_dwordx4 v[50:53], v[40:41], off offset:128
	s_nop 0
	s_waitcnt vmcnt(0)
	v_cvt_pk_bf16_f32 v50, v50, v51
	v_cvt_pk_bf16_f32 v51, v52, v53
	v_cvt_pk_bf16_f32 v52, v148, v149
	v_cvt_pk_bf16_f32 v53, v150, v151
	s_nop 1
	v_mfma_f32_16x16x32_bf16 v[28:31], v[50:53], v[0:3], v[28:31]
	v_lshl_add_u64 v[50:51], v[40:41], 0, s[6:7]
	global_load_dwordx4 v[144:147], v[50:51], off offset:16
	global_load_dwordx4 v[46:49], v[56:57], off offset:-4096
	s_nop 0
	s_nop 0
	s_mov_b64 s[6:7], 0x1080
	s_nop 0
	s_waitcnt vmcnt(0)
	v_cvt_pk_bf16_f32 v46, v46, v47
	v_cvt_pk_bf16_f32 v47, v48, v49
	s_nop 0
	v_cvt_pk_bf16_f32 v48, v144, v145
	v_cvt_pk_bf16_f32 v49, v146, v147
	v_lshl_add_u64 v[50:51], v[40:41], 0, s[6:7]
	global_load_dwordx4 v[144:147], v[50:51], off offset:16
	s_mov_b64 s[6:7], 0x2000
	v_mfma_f32_16x16x32_bf16 v[24:27], v[46:49], v[32:35], v[24:27]
	global_load_dwordx4 v[46:49], v[54:55], off offset:128
	s_nop 0
	s_nop 0
	v_add_co_u32_e32 v54, vcc, s4, v40
	s_movk_i32 s4, 0x4000
	s_nop 0
	v_addc_co_u32_e32 v55, vcc, 0, v41, vcc
	s_nop 0
	s_waitcnt vmcnt(0)
	v_cvt_pk_bf16_f32 v46, v46, v47
	v_cvt_pk_bf16_f32 v47, v48, v49
	s_nop 0
	v_cvt_pk_bf16_f32 v48, v144, v145
	v_cvt_pk_bf16_f32 v49, v146, v147
	v_lshl_add_u64 v[50:51], v[40:41], 0, s[6:7]
	global_load_dwordx4 v[144:147], v[50:51], off offset:16
	s_mov_b64 s[6:7], 0x2080
	v_mfma_f32_16x16x32_bf16 v[24:27], v[46:49], v[0:3], v[24:27]
	global_load_dwordx4 v[46:49], v[56:57], off
	s_nop 0
	s_nop 0
	s_nop 0
	s_waitcnt vmcnt(0)
	v_cvt_pk_bf16_f32 v46, v46, v47
	v_cvt_pk_bf16_f32 v47, v48, v49
	s_nop 0
	v_cvt_pk_bf16_f32 v48, v144, v145
	v_cvt_pk_bf16_f32 v49, v146, v147
	v_lshl_add_u64 v[50:51], v[40:41], 0, s[6:7]
	global_load_dwordx4 v[144:147], v[50:51], off offset:16
	s_mov_b64 s[6:7], 0x3000
	v_mfma_f32_16x16x32_bf16 v[20:23], v[46:49], v[32:35], v[20:23]
	global_load_dwordx4 v[46:49], v[56:57], off offset:128
	s_nop 0
	s_nop 0
	v_add_co_u32_e32 v56, vcc, s4, v40
	s_movk_i32 s4, 0x5000
	s_nop 0
	v_addc_co_u32_e32 v57, vcc, 0, v41, vcc
	s_nop 0
	s_waitcnt vmcnt(0)
; #define MFMA16(a, b, c) __builtin_amdgcn_mfma_f32_16x16x32_bf16((a), (b), (c), 0, 0, 0)
; __device__ __forceinline__ void gla_out_job(const P& p, int job, char* smc) {
;     ...
;   const float* sp = stbuf + ((size_t)((b * 4 + h) * 64 + c)) * 8192;
; #pragma unroll
;   for (int vt = 0; vt < 8; vt++) {
;     const float* sr = sp + (vt * 16 + (lane & 15)) * 64 + (lane >> 4) * 8;
;     float f[8];
;     float4 a0 = *(const float4*)sr, a1 = *(const float4*)(sr + 4);
;     f[0] = a0.x; f[1] = a0.y; f[2] = a0.z; f[3] = a0.w; f[4] = a1.x; f[5] = a1.y; f[6] = a1.z; f[7] = a1.w;
;     O[vt] = MFMA16(pack8(f), qf0, O[vt]);
;     a0 = *(const float4*)(sr + 32); a1 = *(const float4*)(sr + 36);
;     f[0] = a0.x; f[1] = a0.y; f[2] = a0.z; f[3] = a0.w; f[4] = a1.x; f[5] = a1.y; f[6] = a1.z; f[7] = a1.w;
;     O[vt] = MFMA16(pack8(f), qf1, O[vt]);
;   }
	v_cvt_pk_bf16_f32 v46, v46, v47
	v_cvt_pk_bf16_f32 v47, v48, v49
	s_nop 0
	v_cvt_pk_bf16_f32 v48, v144, v145
	v_cvt_pk_bf16_f32 v49, v146, v147
	v_lshl_add_u64 v[50:51], v[40:41], 0, s[6:7]
	global_load_dwordx4 v[144:147], v[50:51], off offset:16
	s_mov_b64 s[6:7], 0x3080
	v_mfma_f32_16x16x32_bf16 v[20:23], v[46:49], v[0:3], v[20:23]
	global_load_dwordx4 v[46:49], v[56:57], off offset:-4096
	s_nop 0
	s_nop 0
	s_nop 0
	s_waitcnt vmcnt(0)
	v_cvt_pk_bf16_f32 v46, v46, v47
	v_cvt_pk_bf16_f32 v47, v48, v49
	s_nop 0
	v_cvt_pk_bf16_f32 v48, v144, v145
	v_cvt_pk_bf16_f32 v49, v146, v147
	v_lshl_add_u64 v[50:51], v[40:41], 0, s[6:7]
	global_load_dwordx4 v[144:147], v[50:51], off offset:16
	s_mov_b64 s[6:7], 0x4080
	v_mfma_f32_16x16x32_bf16 v[16:19], v[46:49], v[32:35], v[16:19]
	global_load_dwordx4 v[46:49], v[54:55], off offset:128
	s_nop 0
	s_nop 0
	v_add_co_u32_e32 v54, vcc, s4, v40
	s_movk_i32 s4, 0x6000
	s_nop 0
	v_addc_co_u32_e32 v55, vcc, 0, v41, vcc
	s_nop 0
	s_waitcnt vmcnt(0)
	v_cvt_pk_bf16_f32 v46, v46, v47
	v_cvt_pk_bf16_f32 v47, v48, v49
	s_nop 0
	v_cvt_pk_bf16_f32 v48, v144, v145
	v_cvt_pk_bf16_f32 v49, v146, v147
	v_lshl_add_u64 v[50:51], v[40:41], 0, s[94:95]
	global_load_dwordx4 v[144:147], v[50:51], off offset:16
	s_nop 0
	v_mfma_f32_16x16x32_bf16 v[16:19], v[46:49], v[0:3], v[16:19]
	global_load_dwordx4 v[46:49], v[56:57], off
	s_nop 0
	s_nop 0
	s_nop 0
	s_waitcnt vmcnt(0)
	v_cvt_pk_bf16_f32 v46, v46, v47
	v_cvt_pk_bf16_f32 v47, v48, v49
	s_nop 0
	v_cvt_pk_bf16_f32 v48, v144, v145
	v_cvt_pk_bf16_f32 v49, v146, v147
	v_lshl_add_u64 v[50:51], v[40:41], 0, s[6:7]
	global_load_dwordx4 v[144:147], v[50:51], off offset:16
	s_mov_b64 s[6:7], 0x5000
	v_mfma_f32_16x16x32_bf16 v[12:15], v[46:49], v[32:35], v[12:15]
	global_load_dwordx4 v[46:49], v[56:57], off offset:128
	s_nop 0
	s_nop 0
	v_add_co_u32_e32 v56, vcc, s4, v40
	s_lshl_b32 s4, s10, 1
	s_nop 0
	v_addc_co_u32_e32 v57, vcc, 0, v41, vcc
	s_nop 0
	s_waitcnt vmcnt(0)
	v_cvt_pk_bf16_f32 v46, v46, v47
	v_cvt_pk_bf16_f32 v47, v48, v49
	s_nop 0
	v_cvt_pk_bf16_f32 v48, v144, v145
	v_cvt_pk_bf16_f32 v49, v146, v147
	v_lshl_add_u64 v[50:51], v[40:41], 0, s[6:7]
	global_load_dwordx4 v[144:147], v[50:51], off offset:16
	s_mov_b64 s[6:7], 0x5080
	v_mfma_f32_16x16x32_bf16 v[12:15], v[46:49], v[0:3], v[12:15]
	global_load_dwordx4 v[46:49], v[56:57], off offset:-4096
	s_nop 0
	s_nop 0
	s_nop 0
	s_waitcnt vmcnt(0)
	v_cvt_pk_bf16_f32 v46, v46, v47
	v_cvt_pk_bf16_f32 v47, v48, v49
	s_nop 0
	v_cvt_pk_bf16_f32 v48, v144, v145
	v_cvt_pk_bf16_f32 v49, v146, v147
	v_lshl_add_u64 v[50:51], v[40:41], 0, s[6:7]
	global_load_dwordx4 v[144:147], v[50:51], off offset:16
	s_mov_b64 s[6:7], 0x6000
	v_mfma_f32_16x16x32_bf16 v[8:11], v[46:49], v[32:35], v[8:11]
	global_load_dwordx4 v[46:49], v[54:55], off offset:128
	s_nop 0
	s_nop 0
	v_add_co_u32_e32 v54, vcc, s58, v40
	s_nop 0
	s_waitcnt vmcnt(0)
	v_cvt_pk_bf16_f32 v46, v46, v47
	v_cvt_pk_bf16_f32 v47, v48, v49
	s_nop 0
	v_cvt_pk_bf16_f32 v48, v144, v145
	v_cvt_pk_bf16_f32 v49, v146, v147
	v_lshl_add_u64 v[50:51], v[40:41], 0, s[6:7]
	global_load_dwordx4 v[144:147], v[50:51], off offset:16
	s_mov_b64 s[6:7], 0x6080
	v_mfma_f32_16x16x32_bf16 v[8:11], v[46:49], v[0:3], v[8:11]
	global_load_dwordx4 v[46:49], v[56:57], off
	s_nop 0
	s_nop 0
	v_addc_co_u32_e32 v55, vcc, 0, v41, vcc
	s_nop 0
	s_waitcnt vmcnt(0)
	v_cvt_pk_bf16_f32 v46, v46, v47
	v_cvt_pk_bf16_f32 v47, v48, v49
	s_nop 0
	v_cvt_pk_bf16_f32 v48, v144, v145
	v_cvt_pk_bf16_f32 v49, v146, v147
	v_lshl_add_u64 v[50:51], v[40:41], 0, s[6:7]
	global_load_dwordx4 v[144:147], v[50:51], off offset:16
	s_mov_b64 s[6:7], 0x7000
	v_mfma_f32_16x16x32_bf16 v[4:7], v[46:49], v[32:35], v[4:7]
	global_load_dwordx4 v[46:49], v[56:57], off offset:128
	s_nop 0
	s_nop 0
	s_nop 0
	s_waitcnt vmcnt(0)
	v_cvt_pk_bf16_f32 v46, v46, v47
	v_cvt_pk_bf16_f32 v47, v48, v49
	s_nop 0
	v_cvt_pk_bf16_f32 v48, v144, v145
	v_cvt_pk_bf16_f32 v49, v146, v147
	v_lshl_add_u64 v[50:51], v[40:41], 0, s[6:7]
	global_load_dwordx4 v[144:147], v[50:51], off offset:16
	s_mov_b64 s[6:7], 0x7080
	v_mfma_f32_16x16x32_bf16 v[4:7], v[46:49], v[0:3], v[4:7]
	global_load_dwordx4 v[46:49], v[54:55], off
	s_nop 0
	s_nop 0
	v_lshl_add_u64 v[40:41], v[40:41], 0, s[6:7]
	global_load_dwordx4 v[148:151], v[40:41], off offset:16
	s_nop 0
	s_waitcnt vmcnt(1)
	v_cvt_pk_bf16_f32 v46, v46, v47
	v_cvt_pk_bf16_f32 v47, v48, v49
	s_nop 0
	v_cvt_pk_bf16_f32 v48, v144, v145
	v_cvt_pk_bf16_f32 v49, v146, v147
	v_mov_b32_e32 v50, v144
	v_mov_b32_e32 v51, v145
	v_mov_b32_e32 v52, v146
	v_mov_b32_e32 v53, v147
	s_nop 1
	v_mfma_f32_16x16x32_bf16 v[32:35], v[46:49], v[32:35], v[36:39]
	s_nop 2
	global_load_dwordx4 v[36:39], v[54:55], off offset:128
	s_nop 0
	s_load_dwordx16 s[60:75], s[0:1], 0x50
	s_nop 0
	s_waitcnt vmcnt(0)
; __device__ __forceinline__ void unpack4(uint2 u, float* f) { f[0] = bflo(u.x); f[1] = bfhi(u.x); f[2] = bflo(u.y); f[3] = bfhi(u.y); }
; __device__ __forceinline__ uint2 pack4(float a, float b, float c, float d) { return make_uint2(pack2(a, b), pack2(c, d)); }
; __device__ __forceinline__ float sigmoidf_(float x) { return frcp(1.f + __expf(-x)); }
; __device__ __forceinline__ float xadd16(float x) { unsigned a = __float_as_uint(x); auto r = __builtin_amdgcn_permlane16_swap(a, a, false, false); return __uint_as_float(r[0]) + __uint_as_float(r[1]); }
; __device__ __forceinline__ float xadd32(float x) { unsigned a = __float_as_uint(x); auto r = __builtin_amdgcn_permlane32_swap(a, a, false, false); return __uint_as_float(r[0]) + __uint_as_float(r[1]); }
; #define MFMA16(a, b, c) __builtin_amdgcn_mfma_f32_16x16x32_bf16((a), (b), (c), 0, 0, 0)
; __device__ __forceinline__ void gla_out_job(const P& p, int job, char* smc) {
;     ...
;     O[vt] = MFMA16(pack8(f), qf0, O[vt]);
;     a0 = *(const float4*)(sr + 32); a1 = *(const float4*)(sr + 36);
;     f[0] = a0.x; f[1] = a0.y; f[2] = a0.z; f[3] = a0.w; f[4] = a1.x; f[5] = a1.y; f[6] = a1.z; f[7] = a1.w;
;     O[vt] = MFMA16(pack8(f), qf1, O[vt]);
;   }
;   float ss = 0.f;
; #pragma unroll
;   for (int vt = 0; vt < 8; vt++)
; #pragma unroll
;     for (int r = 0; r < 4; r++) ss += O[vt][r] * O[vt][r];
;   ss = xadd32(xadd16(ss));
;   const float sc = rsqrtf(ss * (1.f / 128.f) + 1e-6f);
;   const int tok = t0 + wave * 16 + (lane & 15);
; #pragma unroll
;   for (int vt = 0; vt < 8; vt++) {
;     const int v = vt * 16 + (lane >> 4) * 4;
;     float gt[4];
;     unpack4(*(const uint2*)(proj + (size_t)tok * PROJ0_LD + 1024 + h * 128 + v), gt);
;     float4 ng = *(const float4*)(p.gla_ng + h * 128 + v);
;     float o0 = O[vt][0] * sc * ng.x * (gt[0] * sigmoidf_(gt[0]));
;     float o1 = O[vt][1] * sc * ng.y * (gt[1] * sigmoidf_(gt[1]));
;     float o2 = O[vt][2] * sc * ng.z * (gt[2] * sigmoidf_(gt[2]));
;     float o3 = O[vt][3] * sc * ng.w * (gt[3] * sigmoidf_(gt[3]));
;     *(uint2*)(p.A + (size_t)tok * 1024 + h * 128 + v) = pack4(o0, o1, o2, o3);
;   }
	v_cvt_pk_bf16_f32 v36, v36, v37
	v_cvt_pk_bf16_f32 v37, v38, v39
	s_nop 0
	v_cvt_pk_bf16_f32 v38, v148, v149
	v_cvt_pk_bf16_f32 v39, v150, v151
	v_mov_b32_e32 v48, v150
	v_mov_b32_e32 v49, v151
	s_nop 1
	v_mfma_f32_16x16x32_bf16 v[0:3], v[36:39], v[0:3], v[32:35]
	v_mov_b64_e32 v[36:37], s[22:23]
	s_nop 1
	v_mul_f32_e32 v32, v29, v29
	v_fmac_f32_e32 v32, v28, v28
	v_fmac_f32_e32 v32, v30, v30
	v_fmac_f32_e32 v32, v31, v31
	v_fmac_f32_e32 v32, v24, v24
	v_fmac_f32_e32 v32, v25, v25
	v_fmac_f32_e32 v32, v26, v26
	v_fmac_f32_e32 v32, v27, v27
	v_fmac_f32_e32 v32, v20, v20
	v_fmac_f32_e32 v32, v21, v21
	v_fmac_f32_e32 v32, v22, v22
	v_fmac_f32_e32 v32, v23, v23
	v_fmac_f32_e32 v32, v16, v16
	v_fmac_f32_e32 v32, v17, v17
	v_fmac_f32_e32 v32, v18, v18
	v_fmac_f32_e32 v32, v19, v19
	v_fmac_f32_e32 v32, v12, v12
	v_fmac_f32_e32 v32, v13, v13
	v_fmac_f32_e32 v32, v14, v14
	v_fmac_f32_e32 v32, v15, v15
	v_fmac_f32_e32 v32, v8, v8
	v_fmac_f32_e32 v32, v9, v9
	v_fmac_f32_e32 v32, v10, v10
	v_fmac_f32_e32 v32, v11, v11
	v_fmac_f32_e32 v32, v4, v4
	v_fmac_f32_e32 v32, v5, v5
	v_fmac_f32_e32 v32, v6, v6
	v_fmac_f32_e32 v32, v7, v7
	v_fmac_f32_e32 v32, v0, v0
	v_fmac_f32_e32 v32, v1, v1
	v_fmac_f32_e32 v32, v2, v2
	v_fmac_f32_e32 v32, v3, v3
	v_mov_b32_e32 v33, v32
	s_nop 1
	v_permlane16_swap_b32_e32 v32, v33
	v_add_f32_e32 v32, v32, v33
	v_mov_b32_e32 v33, v32
	s_nop 1
	v_permlane32_swap_b32_e32 v32, v33
	v_add_f32_e32 v32, v32, v33
	v_fmamk_f32 v32, v32, 0x3c000000, v136
	v_cmp_gt_f32_e32 vcc, s85, v32
	v_mul_f32_e32 v33, 0x4b800000, v32
	s_nop 0
	v_cndmask_b32_e32 v32, v32, v33, vcc
	v_rsq_f32_e32 v32, v32
	s_nop 0
	v_mul_f32_e32 v33, 0x45800000, v32
	v_cndmask_b32_e32 v32, v32, v33, vcc
	v_add_u32_e32 v33, s15, v43
	v_or_b32_e32 v34, v33, v44
	v_mad_i64_i32 v[36:37], s[6:7], v34, s52, v[36:37]
	v_ashrrev_i32_e32 v35, 31, v34
	v_lshl_add_u64 v[38:39], v[36:37], 0, s[4:5]
	s_lshl_b32 s6, s10, 2
	v_lshlrev_b64 v[36:37], 11, v[34:35]
	v_lshl_add_u64 v[34:35], v[38:39], 0, v[134:135]
	global_load_dwordx2 v[152:153], v[34:35], off offset:2112
	global_load_dwordx2 v[158:159], v[34:35], off offset:2144
	global_load_dwordx2 v[164:165], v[34:35], off offset:2176
	global_load_dwordx2 v[170:171], v[34:35], off offset:2208
	global_load_dwordx2 v[176:177], v[34:35], off offset:2240
	global_load_dwordx2 v[182:183], v[34:35], off offset:2272
	s_waitcnt lgkmcnt(0)
	s_add_u32 s6, s64, s6
	global_load_dwordx2 v[38:39], v[34:35], off offset:2048
	s_addc_u32 s7, s65, 0
	v_lshlrev_b32_e32 v33, 2, v42
	global_load_dwordx4 v[144:147], v33, s[6:7]
	global_load_dwordx4 v[148:151], v33, s[6:7] offset:64
	global_load_dwordx4 v[154:157], v33, s[6:7] offset:128
	global_load_dwordx4 v[160:163], v33, s[6:7] offset:192
	global_load_dwordx4 v[166:169], v33, s[6:7] offset:256
	global_load_dwordx4 v[172:175], v33, s[6:7] offset:320
	global_load_dwordx4 v[178:181], v33, s[6:7] offset:384
	global_load_dwordx4 v[184:187], v33, s[6:7] offset:448
	s_nop 0
	v_pk_mul_f32 v[28:29], v[28:29], v[32:33] op_sel_hi:[1,0]
	v_pk_mul_f32 v[30:31], v[30:31], v[32:33] op_sel_hi:[1,0]
	v_pk_mul_f32 v[24:25], v[24:25], v[32:33] op_sel_hi:[1,0]
	v_pk_mul_f32 v[26:27], v[26:27], v[32:33] op_sel_hi:[1,0]
	v_pk_mul_f32 v[20:21], v[20:21], v[32:33] op_sel_hi:[1,0]
	v_pk_mul_f32 v[22:23], v[22:23], v[32:33] op_sel_hi:[1,0]
	v_pk_mul_f32 v[16:17], v[16:17], v[32:33] op_sel_hi:[1,0]
	v_pk_mul_f32 v[18:19], v[18:19], v[32:33] op_sel_hi:[1,0]
	v_pk_mul_f32 v[12:13], v[12:13], v[32:33] op_sel_hi:[1,0]
	v_pk_mul_f32 v[14:15], v[14:15], v[32:33] op_sel_hi:[1,0]
	v_pk_mul_f32 v[8:9], v[8:9], v[32:33] op_sel_hi:[1,0]
	v_pk_mul_f32 v[10:11], v[10:11], v[32:33] op_sel_hi:[1,0]
	v_pk_mul_f32 v[4:5], v[4:5], v[32:33] op_sel_hi:[1,0]
	v_pk_mul_f32 v[6:7], v[6:7], v[32:33] op_sel_hi:[1,0]
	v_pk_mul_f32 v[0:1], v[0:1], v[32:33] op_sel_hi:[1,0]
	v_pk_mul_f32 v[2:3], v[2:3], v[32:33] op_sel_hi:[1,0]
	s_add_i32 s14, s14, s82
	s_cmpk_gt_i32 s14, 0x3ff
	s_nop 0
	s_waitcnt vmcnt(8)
	v_lshlrev_b32_e32 v44, 16, v38
	v_and_b32_e32 v45, 0xffff0000, v38
	v_mul_f32_e32 v46, 0xbfb8aa3b, v44
	s_nop 0
	s_waitcnt vmcnt(7)
	v_pk_mul_f32 v[28:29], v[144:145], v[28:29]
	v_mul_f32_e32 v40, 0xbfb8aa3b, v45
	v_exp_f32_e32 v46, v46
	v_exp_f32_e32 v40, v40
	v_lshlrev_b32_e32 v38, 16, v39
	v_and_b32_e32 v39, 0xffff0000, v39
	v_add_f32_e32 v46, 1.0, v46
	v_add_f32_e32 v40, 1.0, v40
	v_rcp_f32_e32 v46, v46
	v_rcp_f32_e32 v47, v40
	v_pk_mul_f32 v[30:31], v[146:147], v[30:31]
	v_pk_mul_f32 v[40:41], v[46:47], v[44:45]
	s_nop 0
	v_pk_mul_f32 v[28:29], v[40:41], v[28:29]
	v_mul_f32_e32 v40, 0xbfb8aa3b, v38
	v_mul_f32_e32 v41, 0xbfb8aa3b, v39
	v_exp_f32_e32 v40, v40
	v_exp_f32_e32 v41, v41
	v_add_f32_e32 v40, 1.0, v40
	v_add_f32_e32 v41, 1.0, v41
	v_rcp_f32_e32 v40, v40
	v_rcp_f32_e32 v41, v41
	s_nop 0
	v_pk_mul_f32 v[38:39], v[40:41], v[38:39]
	s_nop 0
	v_pk_mul_f32 v[30:31], v[38:39], v[30:31]
	v_cvt_pk_bf16_f32 v38, v28, v29
	v_lshl_add_u64 v[28:29], s[30:31], 0, v[36:37]
	v_lshl_add_u64 v[28:29], v[28:29], 0, s[4:5]
	v_cvt_pk_bf16_f32 v39, v30, v31
	v_lshl_add_u64 v[28:29], v[28:29], 0, v[134:135]
	global_store_dwordx2 v[28:29], v[38:39], off
	global_load_dwordx2 v[30:31], v[34:35], off offset:2080
	s_nop 0
	s_waitcnt vmcnt(0)
; __device__ __forceinline__ void unpack4(uint2 u, float* f) { f[0] = bflo(u.x); f[1] = bfhi(u.x); f[2] = bflo(u.y); f[3] = bfhi(u.y); }
; __device__ __forceinline__ uint2 pack4(float a, float b, float c, float d) { return make_uint2(pack2(a, b), pack2(c, d)); }
; __device__ __forceinline__ float sigmoidf_(float x) { return frcp(1.f + __expf(-x)); }
; __device__ __forceinline__ void gla_out_job(const P& p, int job, char* smc) {
;     ...
; #pragma unroll
;   for (int vt = 0; vt < 8; vt++) {
;     const int v = vt * 16 + (lane >> 4) * 4;
;     float gt[4];
;     unpack4(*(const uint2*)(proj + (size_t)tok * PROJ0_LD + 1024 + h * 128 + v), gt);
;     float4 ng = *(const float4*)(p.gla_ng + h * 128 + v);
;     float o0 = O[vt][0] * sc * ng.x * (gt[0] * sigmoidf_(gt[0]));
;     float o1 = O[vt][1] * sc * ng.y * (gt[1] * sigmoidf_(gt[1]));
;     float o2 = O[vt][2] * sc * ng.z * (gt[2] * sigmoidf_(gt[2]));
;     float o3 = O[vt][3] * sc * ng.w * (gt[3] * sigmoidf_(gt[3]));
;     *(uint2*)(p.A + (size_t)tok * 1024 + h * 128 + v) = pack4(o0, o1, o2, o3);
;   }
	v_lshlrev_b32_e32 v40, 16, v30
	s_nop 0
	v_and_b32_e32 v41, 0xffff0000, v30
	v_mul_f32_e32 v42, 0xbfb8aa3b, v40
	v_exp_f32_e32 v42, v42
	v_lshlrev_b32_e32 v30, 16, v31
	v_and_b32_e32 v31, 0xffff0000, v31
	v_add_f32_e32 v42, 1.0, v42
	v_rcp_f32_e32 v42, v42
	s_nop 0
	v_pk_mul_f32 v[24:25], v[24:25], v[148:149]
	v_mul_f32_e32 v36, 0xbfb8aa3b, v41
	v_exp_f32_e32 v36, v36
	v_pk_mul_f32 v[26:27], v[26:27], v[150:151]
	v_add_f32_e32 v36, 1.0, v36
	v_rcp_f32_e32 v43, v36
	s_nop 0
	v_pk_mul_f32 v[36:37], v[42:43], v[40:41]
	s_nop 0
	v_pk_mul_f32 v[24:25], v[24:25], v[36:37]
	v_mul_f32_e32 v36, 0xbfb8aa3b, v30
	v_mul_f32_e32 v37, 0xbfb8aa3b, v31
	v_exp_f32_e32 v36, v36
	v_exp_f32_e32 v37, v37
	v_cvt_pk_bf16_f32 v24, v24, v25
	v_add_f32_e32 v36, 1.0, v36
	v_add_f32_e32 v37, 1.0, v37
	v_rcp_f32_e32 v36, v36
	v_rcp_f32_e32 v37, v37
	s_nop 0
	v_pk_mul_f32 v[30:31], v[36:37], v[30:31]
	s_nop 0
	v_pk_mul_f32 v[26:27], v[26:27], v[30:31]
	s_nop 0
	v_cvt_pk_bf16_f32 v25, v26, v27
	global_store_dwordx2 v[28:29], v[24:25], off offset:32
	s_nop 0
	s_nop 0
	v_lshlrev_b32_e32 v30, 16, v152
	v_and_b32_e32 v31, 0xffff0000, v152
	v_lshlrev_b32_e32 v36, 16, v153
	v_and_b32_e32 v37, 0xffff0000, v153
	s_nop 0
	v_mul_f32_e32 v38, 0xbfb8aa3b, v30
	v_exp_f32_e32 v38, v38
	s_nop 0
	v_pk_mul_f32 v[20:21], v[20:21], v[154:155]
	v_mul_f32_e32 v24, 0xbfb8aa3b, v31
	v_exp_f32_e32 v24, v24
	v_add_f32_e32 v38, 1.0, v38
	v_rcp_f32_e32 v38, v38
	v_pk_mul_f32 v[22:23], v[22:23], v[156:157]
	v_add_f32_e32 v24, 1.0, v24
	v_rcp_f32_e32 v39, v24
	s_nop 0
	v_pk_mul_f32 v[24:25], v[38:39], v[30:31]
	s_nop 0
	v_pk_mul_f32 v[20:21], v[20:21], v[24:25]
	v_mul_f32_e32 v24, 0xbfb8aa3b, v36
	v_mul_f32_e32 v25, 0xbfb8aa3b, v37
	v_exp_f32_e32 v24, v24
	v_exp_f32_e32 v25, v25
	v_cvt_pk_bf16_f32 v20, v20, v21
	v_add_f32_e32 v24, 1.0, v24
	v_add_f32_e32 v25, 1.0, v25
	v_rcp_f32_e32 v24, v24
	v_rcp_f32_e32 v25, v25
	s_nop 0
	v_pk_mul_f32 v[24:25], v[24:25], v[36:37]
	s_nop 0
	v_pk_mul_f32 v[22:23], v[22:23], v[24:25]
	s_nop 0
	v_cvt_pk_bf16_f32 v21, v22, v23
	global_store_dwordx2 v[28:29], v[20:21], off offset:64
	s_nop 0
	s_nop 0
	v_lshlrev_b32_e32 v24, 16, v158
	v_and_b32_e32 v25, 0xffff0000, v158
	v_lshlrev_b32_e32 v26, 16, v159
	v_and_b32_e32 v27, 0xffff0000, v159
	s_nop 0
	v_mul_f32_e32 v30, 0xbfb8aa3b, v24
	v_exp_f32_e32 v30, v30
	s_nop 0
	v_pk_mul_f32 v[16:17], v[16:17], v[160:161]
	v_mul_f32_e32 v20, 0xbfb8aa3b, v25
	v_exp_f32_e32 v20, v20
	v_add_f32_e32 v30, 1.0, v30
	v_rcp_f32_e32 v30, v30
	v_pk_mul_f32 v[18:19], v[18:19], v[162:163]
	v_add_f32_e32 v20, 1.0, v20
	v_rcp_f32_e32 v31, v20
	s_nop 0
	v_pk_mul_f32 v[20:21], v[30:31], v[24:25]
	s_nop 0
	v_pk_mul_f32 v[16:17], v[16:17], v[20:21]
	v_mul_f32_e32 v20, 0xbfb8aa3b, v26
	v_mul_f32_e32 v21, 0xbfb8aa3b, v27
	v_exp_f32_e32 v20, v20
	v_exp_f32_e32 v21, v21
	v_cvt_pk_bf16_f32 v16, v16, v17
	v_add_f32_e32 v20, 1.0, v20
	v_add_f32_e32 v21, 1.0, v21
	v_rcp_f32_e32 v20, v20
	v_rcp_f32_e32 v21, v21
	s_nop 0
	v_pk_mul_f32 v[20:21], v[20:21], v[26:27]
	s_nop 0
	v_pk_mul_f32 v[18:19], v[18:19], v[20:21]
	s_nop 0
	v_cvt_pk_bf16_f32 v17, v18, v19
	global_store_dwordx2 v[28:29], v[16:17], off offset:96
	s_nop 0
	s_nop 0
	v_lshlrev_b32_e32 v20, 16, v164
	v_and_b32_e32 v21, 0xffff0000, v164
	v_lshlrev_b32_e32 v22, 16, v165
	v_and_b32_e32 v23, 0xffff0000, v165
	s_nop 0
	v_mul_f32_e32 v24, 0xbfb8aa3b, v20
	v_exp_f32_e32 v24, v24
	s_nop 0
	v_pk_mul_f32 v[12:13], v[12:13], v[166:167]
	v_mul_f32_e32 v16, 0xbfb8aa3b, v21
	v_exp_f32_e32 v16, v16
	v_add_f32_e32 v24, 1.0, v24
	v_rcp_f32_e32 v24, v24
	v_pk_mul_f32 v[14:15], v[14:15], v[168:169]
	v_add_f32_e32 v16, 1.0, v16
	v_rcp_f32_e32 v25, v16
	s_nop 0
; __device__ __forceinline__ void unpack4(uint2 u, float* f) { f[0] = bflo(u.x); f[1] = bfhi(u.x); f[2] = bflo(u.y); f[3] = bfhi(u.y); }
; __device__ __forceinline__ uint2 pack4(float a, float b, float c, float d) { return make_uint2(pack2(a, b), pack2(c, d)); }
; __device__ __forceinline__ float sigmoidf_(float x) { return frcp(1.f + __expf(-x)); }
; __device__ __forceinline__ void gla_out_job(const P& p, int job, char* smc) {
;     ...
; #pragma unroll
;   for (int vt = 0; vt < 8; vt++) {
;     const int v = vt * 16 + (lane >> 4) * 4;
;     float gt[4];
;     unpack4(*(const uint2*)(proj + (size_t)tok * PROJ0_LD + 1024 + h * 128 + v), gt);
;     float4 ng = *(const float4*)(p.gla_ng + h * 128 + v);
;     float o0 = O[vt][0] * sc * ng.x * (gt[0] * sigmoidf_(gt[0]));
;     float o1 = O[vt][1] * sc * ng.y * (gt[1] * sigmoidf_(gt[1]));
;     float o2 = O[vt][2] * sc * ng.z * (gt[2] * sigmoidf_(gt[2]));
;     float o3 = O[vt][3] * sc * ng.w * (gt[3] * sigmoidf_(gt[3]));
;     *(uint2*)(p.A + (size_t)tok * 1024 + h * 128 + v) = pack4(o0, o1, o2, o3);
;   }
	v_pk_mul_f32 v[16:17], v[24:25], v[20:21]
	s_nop 0
	v_pk_mul_f32 v[12:13], v[12:13], v[16:17]
	v_mul_f32_e32 v16, 0xbfb8aa3b, v22
	v_mul_f32_e32 v17, 0xbfb8aa3b, v23
	v_exp_f32_e32 v16, v16
	v_exp_f32_e32 v17, v17
	v_cvt_pk_bf16_f32 v12, v12, v13
	v_add_f32_e32 v16, 1.0, v16
	v_add_f32_e32 v17, 1.0, v17
	v_rcp_f32_e32 v16, v16
	v_rcp_f32_e32 v17, v17
	s_nop 0
	v_pk_mul_f32 v[16:17], v[16:17], v[22:23]
	s_nop 0
	v_pk_mul_f32 v[14:15], v[14:15], v[16:17]
	s_nop 0
	v_cvt_pk_bf16_f32 v13, v14, v15
	global_store_dwordx2 v[28:29], v[12:13], off offset:128
	s_nop 0
	s_nop 0
	v_lshlrev_b32_e32 v16, 16, v170
	v_and_b32_e32 v17, 0xffff0000, v170
	v_lshlrev_b32_e32 v18, 16, v171
	v_and_b32_e32 v19, 0xffff0000, v171
	s_nop 0
	v_mul_f32_e32 v20, 0xbfb8aa3b, v16
	v_exp_f32_e32 v20, v20
	s_nop 0
	v_pk_mul_f32 v[8:9], v[8:9], v[172:173]
	v_mul_f32_e32 v12, 0xbfb8aa3b, v17
	v_exp_f32_e32 v12, v12
	v_add_f32_e32 v20, 1.0, v20
	v_rcp_f32_e32 v20, v20
	v_pk_mul_f32 v[10:11], v[10:11], v[174:175]
	v_add_f32_e32 v12, 1.0, v12
	v_rcp_f32_e32 v21, v12
	s_nop 0
	v_pk_mul_f32 v[12:13], v[20:21], v[16:17]
	s_nop 0
	v_pk_mul_f32 v[8:9], v[8:9], v[12:13]
	v_mul_f32_e32 v12, 0xbfb8aa3b, v18
	v_mul_f32_e32 v13, 0xbfb8aa3b, v19
	v_exp_f32_e32 v12, v12
	v_exp_f32_e32 v13, v13
	v_cvt_pk_bf16_f32 v8, v8, v9
	v_add_f32_e32 v12, 1.0, v12
	v_add_f32_e32 v13, 1.0, v13
	v_rcp_f32_e32 v12, v12
	v_rcp_f32_e32 v13, v13
	s_nop 0
	v_pk_mul_f32 v[12:13], v[12:13], v[18:19]
	s_nop 0
	v_pk_mul_f32 v[10:11], v[10:11], v[12:13]
	s_nop 0
	v_cvt_pk_bf16_f32 v9, v10, v11
	global_store_dwordx2 v[28:29], v[8:9], off offset:160
	s_nop 0
	s_nop 0
	v_lshlrev_b32_e32 v12, 16, v176
	v_and_b32_e32 v13, 0xffff0000, v176
	v_lshlrev_b32_e32 v14, 16, v177
	v_and_b32_e32 v15, 0xffff0000, v177
	s_nop 0
	v_mul_f32_e32 v16, 0xbfb8aa3b, v12
	v_exp_f32_e32 v16, v16
	s_nop 0
	v_pk_mul_f32 v[4:5], v[4:5], v[178:179]
	v_mul_f32_e32 v8, 0xbfb8aa3b, v13
	v_exp_f32_e32 v8, v8
	v_add_f32_e32 v16, 1.0, v16
	v_rcp_f32_e32 v16, v16
	v_pk_mul_f32 v[6:7], v[6:7], v[180:181]
	v_add_f32_e32 v8, 1.0, v8
	v_rcp_f32_e32 v17, v8
	s_nop 0
	v_pk_mul_f32 v[8:9], v[16:17], v[12:13]
	s_nop 0
	v_pk_mul_f32 v[4:5], v[4:5], v[8:9]
	v_mul_f32_e32 v8, 0xbfb8aa3b, v14
	v_mul_f32_e32 v9, 0xbfb8aa3b, v15
	v_exp_f32_e32 v8, v8
	v_exp_f32_e32 v9, v9
	v_cvt_pk_bf16_f32 v4, v4, v5
	v_add_f32_e32 v8, 1.0, v8
	v_add_f32_e32 v9, 1.0, v9
	v_rcp_f32_e32 v8, v8
	v_rcp_f32_e32 v9, v9
	s_nop 0
	v_pk_mul_f32 v[8:9], v[8:9], v[14:15]
	s_nop 0
	v_pk_mul_f32 v[6:7], v[6:7], v[8:9]
	s_nop 0
	v_cvt_pk_bf16_f32 v5, v6, v7
	global_store_dwordx2 v[28:29], v[4:5], off offset:192
	s_nop 0
	s_nop 0
	v_lshlrev_b32_e32 v8, 16, v182
	v_and_b32_e32 v9, 0xffff0000, v182
	v_lshlrev_b32_e32 v10, 16, v183
	v_and_b32_e32 v11, 0xffff0000, v183
	s_nop 0
	v_mul_f32_e32 v12, 0xbfb8aa3b, v8
	v_exp_f32_e32 v12, v12
	s_nop 0
	v_pk_mul_f32 v[0:1], v[0:1], v[184:185]
	v_mul_f32_e32 v4, 0xbfb8aa3b, v9
	v_exp_f32_e32 v4, v4
	v_add_f32_e32 v12, 1.0, v12
	v_rcp_f32_e32 v12, v12
	v_pk_mul_f32 v[2:3], v[2:3], v[186:187]
	v_mov_b32_e32 v6, v186
	v_mov_b32_e32 v7, v187
	v_add_f32_e32 v4, 1.0, v4
	v_rcp_f32_e32 v13, v4
	s_nop 0
	v_pk_mul_f32 v[4:5], v[12:13], v[8:9]
	s_nop 0
	v_pk_mul_f32 v[0:1], v[0:1], v[4:5]
	v_mul_f32_e32 v4, 0xbfb8aa3b, v10
	v_mul_f32_e32 v5, 0xbfb8aa3b, v11
	v_exp_f32_e32 v4, v4
	v_exp_f32_e32 v5, v5
	v_cvt_pk_bf16_f32 v0, v0, v1
	v_add_f32_e32 v4, 1.0, v4
	v_add_f32_e32 v5, 1.0, v5
	v_rcp_f32_e32 v4, v4
	v_rcp_f32_e32 v5, v5
	s_nop 0
	v_pk_mul_f32 v[4:5], v[4:5], v[10:11]
	s_nop 0
	v_pk_mul_f32 v[2:3], v[2:3], v[4:5]
	s_nop 0
	v_cvt_pk_bf16_f32 v1, v2, v3
	global_store_dwordx2 v[28:29], v[0:1], off offset:224
	s_cbranch_scc1 .LBB0_345

; __device__ __forceinline__ uint2 pack4(float a, float b, float c, float d) { return make_uint2(pack2(a, b), pack2(c, d)); }
; __device__ __forceinline__ int ltid() { int t = threadIdx.x; asm volatile("" : "+v"(t)); return t; }
; __device__ __forceinline__ void norm_rows(const float* in, const float* gain, u16* outb, int nrows, int job0w, int jstridew) {
;   const int lane = ltid() & 63;
;   for (int r = job0w; r < nrows; r += jstridew) {
;     const float4* ip = (const float4*)(in + (size_t)r * 1024);
;     float4 v[4];
;     float ss = 0.f;
; #pragma unroll
;     for (int i = 0; i < 4; i++) {
;       { const f32x4 t_ = __builtin_nontemporal_load((const f32x4*)ip + lane + i * 64); v[i] = make_float4(t_[0], t_[1], t_[2], t_[3]); }
;       ss += v[i].x * v[i].x + v[i].y * v[i].y + v[i].z * v[i].z + v[i].w * v[i].w;
;     }
;     ss = wave_sum(ss);
;     float sc = rsqrtf(ss * (1.f / 1024.f) + 1e-6f);
; #pragma unroll
;     for (int i = 0; i < 4; i++) {
;       float4 g = ((const float4*)gain)[lane + i * 64];
;       *(uint2*)(outb + (size_t)r * 1024 + (lane + i * 64) * 4) =
;           pack4(v[i].x * sc * g.x, v[i].y * sc * g.y, v[i].z * sc * g.z, v[i].w * sc * g.w);
;     }
;   }
; }
.LBB0_592:
	s_movk_i32 s4, 0x400
	v_mov_b32_e32 v0, v132
	v_cmp_gt_i32_e32 vcc, s4, v142
	v_ashrrev_i32_e32 v143, 31, v142
	s_and_saveexec_b64 s[6:7], vcc
	v_readlane_b32 s10, v229, 1
	v_readlane_b32 s12, v229, 7
	v_readlane_b32 s11, v229, 2
	v_readlane_b32 s13, v229, 8
	s_cbranch_execz .LBB0_595
	v_and_b32_e32 v2, 63, v0
	v_lshlrev_b32_e32 v134, 4, v2
	v_readlane_b32 s8, v230, 29
	v_readlane_b32 s9, v230, 30
	v_or_b32_e32 v0, 0x400, v134
	v_mov_b32_e32 v1, v135
	s_waitcnt vmcnt(0)
	v_lshl_add_u64 v[18:19], s[8:9], 0, v[0:1]
	v_or_b32_e32 v0, 0x800, v134
	v_lshl_add_u64 v[20:21], s[8:9], 0, v[0:1]
	v_or_b32_e32 v0, 0xc00, v134
	v_lshl_add_u64 v[16:17], s[8:9], 0, v[134:135]
	v_lshl_add_u64 v[22:23], s[8:9], 0, v[0:1]
	v_lshlrev_b64 v[0:1], 11, v[142:143]
	v_readlane_b32 s8, v230, 63
	v_lshl_or_b32 v0, v2, 3, v0
	v_readlane_b32 s9, v229, 0
	v_mov_b32_e32 v28, v142
	s_nop 0
	v_lshl_add_u64 v[24:25], s[8:9], 0, v[0:1]
	v_lshlrev_b64 v[0:1], 12, v[142:143]
	v_readlane_b32 s8, v229, 3
	v_or_b32_e32 v0, v0, v134
	v_readlane_b32 s9, v229, 4
	s_nop 1
	v_lshl_add_u64 v[26:27], s[8:9], 0, v[0:1]
	s_mov_b64 s[8:9], 0
	global_load_dwordx4 v[152:155], v[16:17], off
	global_load_dwordx4 v[156:159], v[18:19], off
	global_load_dwordx4 v[160:163], v[20:21], off
	global_load_dwordx4 v[164:167], v[22:23], off
	global_load_dwordx4 v[0:3], v[26:27], off offset:-3072 nt
	global_load_dwordx4 v[4:7], v[26:27], off offset:-2048 nt
	global_load_dwordx4 v[8:11], v[26:27], off offset:-1024 nt
	global_load_dwordx4 v[12:15], v[26:27], off nt
	s_waitcnt vmcnt(0)
.LBB0_594:
	v_add_u32_e32 v28, s34, v28
	v_cmp_lt_i32_e32 vcc, s59, v28
	s_or_b64 s[8:9], vcc, s[8:9]
	s_cbranch_vccnz .Lnr1_npa
	v_lshl_add_u64 v[26:27], v[26:27], 0, s[12:13]
	global_load_dwordx4 v[168:171], v[26:27], off offset:-3072 nt
	global_load_dwordx4 v[172:175], v[26:27], off offset:-2048 nt
	global_load_dwordx4 v[176:179], v[26:27], off offset:-1024 nt
	global_load_dwordx4 v[180:183], v[26:27], off nt
	s_waitcnt vmcnt(8)
	s_branch .Lnr1_ja

; __device__ __forceinline__ uint2 pack4(float a, float b, float c, float d) { return make_uint2(pack2(a, b), pack2(c, d)); }
; __device__ __forceinline__ int ltid() { int t = threadIdx.x; asm volatile("" : "+v"(t)); return t; }
; __device__ __forceinline__ void norm_rows(const float* in, const float* gain, u16* outb, int nrows, int job0w, int jstridew) {
;   const int lane = ltid() & 63;
;   for (int r = job0w; r < nrows; r += jstridew) {
;     const float4* ip = (const float4*)(in + (size_t)r * 1024);
;     float4 v[4];
;     float ss = 0.f;
; #pragma unroll
;     for (int i = 0; i < 4; i++) {
;       { const f32x4 t_ = __builtin_nontemporal_load((const f32x4*)ip + lane + i * 64); v[i] = make_float4(t_[0], t_[1], t_[2], t_[3]); }
;       ss += v[i].x * v[i].x + v[i].y * v[i].y + v[i].z * v[i].z + v[i].w * v[i].w;
;     }
;     ss = wave_sum(ss);
;     float sc = rsqrtf(ss * (1.f / 1024.f) + 1e-6f);
; #pragma unroll
;     for (int i = 0; i < 4; i++) {
;       float4 g = ((const float4*)gain)[lane + i * 64];
;       *(uint2*)(outb + (size_t)r * 1024 + (lane + i * 64) * 4) =
;           pack4(v[i].x * sc * g.x, v[i].y * sc * g.y, v[i].z * sc * g.z, v[i].w * sc * g.w);
;     }
;   }
; }
.Lnr1_ja:
	v_mul_f32_e32 v144, v1, v1
	v_mul_f32_e32 v145, v5, v5
	v_mul_f32_e32 v146, v9, v9
	v_mul_f32_e32 v147, v13, v13
	v_fmac_f32_e32 v144, v0, v0
	v_fmac_f32_e32 v145, v4, v4
	v_fmac_f32_e32 v146, v8, v8
	v_fmac_f32_e32 v147, v12, v12
	v_fmac_f32_e32 v144, v2, v2
	v_fmac_f32_e32 v145, v6, v6
	v_fmac_f32_e32 v146, v10, v10
	v_fmac_f32_e32 v147, v14, v14
	v_fmac_f32_e32 v144, v3, v3
	v_fmac_f32_e32 v145, v7, v7
	v_fmac_f32_e32 v146, v11, v11
	v_fmac_f32_e32 v147, v15, v15
	v_add_f32_e32 v148, v144, v145
	v_add_f32_e32 v148, v148, v146
	v_add_f32_e32 v148, v148, v147
	s_nop 1
	v_add_f32_dpp v148, v148, v148 quad_perm:[1,0,3,2] row_mask:0xf bank_mask:0xf bound_ctrl:1
	s_nop 1
	v_add_f32_dpp v148, v148, v148 quad_perm:[2,3,0,1] row_mask:0xf bank_mask:0xf bound_ctrl:1
	s_nop 1
	v_add_f32_dpp v148, v148, v148 row_half_mirror row_mask:0xf bank_mask:0xf bound_ctrl:1
	s_nop 1
	v_add_f32_dpp v148, v148, v148 row_mirror row_mask:0xf bank_mask:0xf bound_ctrl:1
	v_mov_b32_e32 v149, v148
	s_nop 1
	v_permlane16_swap_b32_e32 v148, v149
	v_add_f32_e32 v148, v148, v149
	v_mov_b32_e32 v149, v148
	s_nop 1
	v_permlane32_swap_b32_e32 v148, v149
	v_add_f32_e32 v148, v148, v149
	v_fmamk_f32 v148, v148, 0x3a800000, v136
	v_cmp_gt_f32_e32 vcc, s85, v148
	v_mul_f32_e32 v149, 0x4b800000, v148
	s_nop 0
	v_cndmask_b32_e32 v148, v148, v149, vcc
	v_rsq_f32_e32 v148, v148
	s_nop 0
	v_mul_f32_e32 v149, 0x45800000, v148
	v_cndmask_b32_e32 v150, v148, v149, vcc
	s_nop 0
	v_pk_mul_f32 v[0:1], v[0:1], v[150:151] op_sel_hi:[1,0]
	v_pk_mul_f32 v[2:3], v[2:3], v[150:151] op_sel_hi:[1,0]
	v_pk_mul_f32 v[4:5], v[4:5], v[150:151] op_sel_hi:[1,0]
	v_pk_mul_f32 v[6:7], v[6:7], v[150:151] op_sel_hi:[1,0]
	v_pk_mul_f32 v[8:9], v[8:9], v[150:151] op_sel_hi:[1,0]
	v_pk_mul_f32 v[10:11], v[10:11], v[150:151] op_sel_hi:[1,0]
	v_pk_mul_f32 v[12:13], v[12:13], v[150:151] op_sel_hi:[1,0]
	v_pk_mul_f32 v[14:15], v[14:15], v[150:151] op_sel_hi:[1,0]
	v_pk_mul_f32 v[0:1], v[152:153], v[0:1]
	v_pk_mul_f32 v[2:3], v[154:155], v[2:3]
	v_pk_mul_f32 v[4:5], v[156:157], v[4:5]
	v_pk_mul_f32 v[6:7], v[158:159], v[6:7]
	v_pk_mul_f32 v[8:9], v[160:161], v[8:9]
	v_pk_mul_f32 v[10:11], v[162:163], v[10:11]
	v_pk_mul_f32 v[12:13], v[164:165], v[12:13]
	v_pk_mul_f32 v[14:15], v[166:167], v[14:15]
	v_cvt_pk_bf16_f32 v0, v0, v1
	v_cvt_pk_bf16_f32 v1, v2, v3
	v_cvt_pk_bf16_f32 v4, v4, v5
	v_cvt_pk_bf16_f32 v5, v6, v7
	v_cvt_pk_bf16_f32 v8, v8, v9
	v_cvt_pk_bf16_f32 v9, v10, v11
	v_cvt_pk_bf16_f32 v12, v12, v13
	v_cvt_pk_bf16_f32 v13, v14, v15
	global_store_dwordx2 v[24:25], v[0:1], off offset:-1024
	global_store_dwordx2 v[24:25], v[4:5], off offset:-512
	global_store_dwordx2 v[24:25], v[8:9], off
	global_store_dwordx2 v[24:25], v[12:13], off offset:512
	v_lshl_add_u64 v[24:25], v[24:25], 0, s[10:11]
	s_andn2_b64 exec, exec, s[8:9]
	s_cbranch_execz .Lnr1_done
	v_add_u32_e32 v28, s34, v28
	v_cmp_lt_i32_e32 vcc, s59, v28
	s_or_b64 s[8:9], vcc, s[8:9]
	s_cbranch_vccnz .Lnr1_npb
	v_lshl_add_u64 v[26:27], v[26:27], 0, s[12:13]
	global_load_dwordx4 v[0:3], v[26:27], off offset:-3072 nt
	global_load_dwordx4 v[4:7], v[26:27], off offset:-2048 nt
	global_load_dwordx4 v[8:11], v[26:27], off offset:-1024 nt
	global_load_dwordx4 v[12:15], v[26:27], off nt
	s_waitcnt vmcnt(8)
	s_branch .Lnr1_jb

; __device__ __forceinline__ uint2 pack4(float a, float b, float c, float d) { return make_uint2(pack2(a, b), pack2(c, d)); }
; __device__ __forceinline__ int ltid() { int t = threadIdx.x; asm volatile("" : "+v"(t)); return t; }
; __device__ __forceinline__ void norm_rows(const float* in, const float* gain, u16* outb, int nrows, int job0w, int jstridew) {
;   const int lane = ltid() & 63;
;   for (int r = job0w; r < nrows; r += jstridew) {
;     const float4* ip = (const float4*)(in + (size_t)r * 1024);
;     float4 v[4];
;     float ss = 0.f;
; #pragma unroll
;     for (int i = 0; i < 4; i++) {
;       { const f32x4 t_ = __builtin_nontemporal_load((const f32x4*)ip + lane + i * 64); v[i] = make_float4(t_[0], t_[1], t_[2], t_[3]); }
;       ss += v[i].x * v[i].x + v[i].y * v[i].y + v[i].z * v[i].z + v[i].w * v[i].w;
;     }
;     ss = wave_sum(ss);
;     float sc = rsqrtf(ss * (1.f / 1024.f) + 1e-6f);
; #pragma unroll
;     for (int i = 0; i < 4; i++) {
;       float4 g = ((const float4*)gain)[lane + i * 64];
;       *(uint2*)(outb + (size_t)r * 1024 + (lane + i * 64) * 4) =
;           pack4(v[i].x * sc * g.x, v[i].y * sc * g.y, v[i].z * sc * g.z, v[i].w * sc * g.w);
;     }
;   }
; }
; __global__ void __launch_bounds__(NTHR, 2) mega(P p, int ph_lo, int ph_hi) {
;     ...
;         norm_rows(p.mem, p.norm_gain + 6 * 1024, p.memn, 1024, gw, nw);
;         norm_rows(p.x, p.norm_gain, p.A, T_TOK, gw, nw);
.Lnr1_jb:
	v_mul_f32_e32 v144, v169, v169
	v_mul_f32_e32 v145, v173, v173
	v_mul_f32_e32 v146, v177, v177
	v_mul_f32_e32 v147, v181, v181
	v_fmac_f32_e32 v144, v168, v168
	v_fmac_f32_e32 v145, v172, v172
	v_fmac_f32_e32 v146, v176, v176
	v_fmac_f32_e32 v147, v180, v180
	v_fmac_f32_e32 v144, v170, v170
	v_fmac_f32_e32 v145, v174, v174
	v_fmac_f32_e32 v146, v178, v178
	v_fmac_f32_e32 v147, v182, v182
	v_fmac_f32_e32 v144, v171, v171
	v_fmac_f32_e32 v145, v175, v175
	v_fmac_f32_e32 v146, v179, v179
	v_fmac_f32_e32 v147, v183, v183
	v_add_f32_e32 v148, v144, v145
	v_add_f32_e32 v148, v148, v146
	v_add_f32_e32 v148, v148, v147
	s_nop 1
	v_add_f32_dpp v148, v148, v148 quad_perm:[1,0,3,2] row_mask:0xf bank_mask:0xf bound_ctrl:1
	s_nop 1
	v_add_f32_dpp v148, v148, v148 quad_perm:[2,3,0,1] row_mask:0xf bank_mask:0xf bound_ctrl:1
	s_nop 1
	v_add_f32_dpp v148, v148, v148 row_half_mirror row_mask:0xf bank_mask:0xf bound_ctrl:1
	s_nop 1
	v_add_f32_dpp v148, v148, v148 row_mirror row_mask:0xf bank_mask:0xf bound_ctrl:1
	v_mov_b32_e32 v149, v148
	s_nop 1
	v_permlane16_swap_b32_e32 v148, v149
	v_add_f32_e32 v148, v148, v149
	v_mov_b32_e32 v149, v148
	s_nop 1
	v_permlane32_swap_b32_e32 v148, v149
	v_add_f32_e32 v148, v148, v149
	v_fmamk_f32 v148, v148, 0x3a800000, v136
	v_cmp_gt_f32_e32 vcc, s85, v148
	v_mul_f32_e32 v149, 0x4b800000, v148
	s_nop 0
	v_cndmask_b32_e32 v148, v148, v149, vcc
	v_rsq_f32_e32 v148, v148
	s_nop 0
	v_mul_f32_e32 v149, 0x45800000, v148
	v_cndmask_b32_e32 v150, v148, v149, vcc
	s_nop 0
	v_pk_mul_f32 v[168:169], v[168:169], v[150:151] op_sel_hi:[1,0]
	v_pk_mul_f32 v[170:171], v[170:171], v[150:151] op_sel_hi:[1,0]
	v_pk_mul_f32 v[172:173], v[172:173], v[150:151] op_sel_hi:[1,0]
	v_pk_mul_f32 v[174:175], v[174:175], v[150:151] op_sel_hi:[1,0]
	v_pk_mul_f32 v[176:177], v[176:177], v[150:151] op_sel_hi:[1,0]
	v_pk_mul_f32 v[178:179], v[178:179], v[150:151] op_sel_hi:[1,0]
	v_pk_mul_f32 v[180:181], v[180:181], v[150:151] op_sel_hi:[1,0]
	v_pk_mul_f32 v[182:183], v[182:183], v[150:151] op_sel_hi:[1,0]
	v_pk_mul_f32 v[168:169], v[152:153], v[168:169]
	v_pk_mul_f32 v[170:171], v[154:155], v[170:171]
	v_pk_mul_f32 v[172:173], v[156:157], v[172:173]
	v_pk_mul_f32 v[174:175], v[158:159], v[174:175]
	v_pk_mul_f32 v[176:177], v[160:161], v[176:177]
	v_pk_mul_f32 v[178:179], v[162:163], v[178:179]
	v_pk_mul_f32 v[180:181], v[164:165], v[180:181]
	v_pk_mul_f32 v[182:183], v[166:167], v[182:183]
	v_cvt_pk_bf16_f32 v168, v168, v169
	v_cvt_pk_bf16_f32 v169, v170, v171
	v_cvt_pk_bf16_f32 v172, v172, v173
	v_cvt_pk_bf16_f32 v173, v174, v175
	v_cvt_pk_bf16_f32 v176, v176, v177
	v_cvt_pk_bf16_f32 v177, v178, v179
	v_cvt_pk_bf16_f32 v180, v180, v181
	v_cvt_pk_bf16_f32 v181, v182, v183
	global_store_dwordx2 v[24:25], v[168:169], off offset:-1024
	global_store_dwordx2 v[24:25], v[172:173], off offset:-512
	global_store_dwordx2 v[24:25], v[176:177], off
	global_store_dwordx2 v[24:25], v[180:181], off offset:512
	v_lshl_add_u64 v[24:25], v[24:25], 0, s[10:11]
	s_andn2_b64 exec, exec, s[8:9]
	s_cbranch_execnz .LBB0_594
.Lnr1_done:
.LBB0_595:
	s_or_b64 exec, exec, s[6:7]
	s_movk_i32 s4, 0x4000
	v_mov_b32_e32 v0, v132
	v_cmp_gt_i32_e32 vcc, s4, v142
	s_and_saveexec_b64 s[6:7], vcc
	v_readlane_b32 s10, v229, 1
	v_readlane_b32 s12, v229, 7
	v_readlane_b32 s11, v229, 2
	v_readlane_b32 s13, v229, 8
	s_cbranch_execnz .LBB0_596
	s_getpc_b64 s[98:99]

; __device__ __forceinline__ uint2 pack4(float a, float b, float c, float d) { return make_uint2(pack2(a, b), pack2(c, d)); }
; __device__ __forceinline__ int ltid() { int t = threadIdx.x; asm volatile("" : "+v"(t)); return t; }
; __device__ __forceinline__ void norm_rows(const float* in, const float* gain, u16* outb, int nrows, int job0w, int jstridew) {
;   const int lane = ltid() & 63;
;   for (int r = job0w; r < nrows; r += jstridew) {
;     const float4* ip = (const float4*)(in + (size_t)r * 1024);
;     float4 v[4];
;     float ss = 0.f;
; #pragma unroll
;     for (int i = 0; i < 4; i++) {
;       { const f32x4 t_ = __builtin_nontemporal_load((const f32x4*)ip + lane + i * 64); v[i] = make_float4(t_[0], t_[1], t_[2], t_[3]); }
;       ss += v[i].x * v[i].x + v[i].y * v[i].y + v[i].z * v[i].z + v[i].w * v[i].w;
;     }
;     ss = wave_sum(ss);
;     float sc = rsqrtf(ss * (1.f / 1024.f) + 1e-6f);
; #pragma unroll
;     for (int i = 0; i < 4; i++) {
;       float4 g = ((const float4*)gain)[lane + i * 64];
;       *(uint2*)(outb + (size_t)r * 1024 + (lane + i * 64) * 4) =
;           pack4(v[i].x * sc * g.x, v[i].y * sc * g.y, v[i].z * sc * g.z, v[i].w * sc * g.w);
;     }
;   }
; }
.LBB0_596:
	s_load_dwordx2 s[8:9], s[0:1], 0x10
	v_and_b32_e32 v2, 63, v0
	v_lshlrev_b32_e32 v134, 4, v2
	v_lshlrev_b64 v[0:1], 11, v[142:143]
	v_lshl_or_b32 v0, v2, 3, v0
	s_waitcnt vmcnt(0) lgkmcnt(0)
	v_lshl_add_u64 v[16:17], s[8:9], 0, v[134:135]
	v_readlane_b32 s8, v229, 22
	v_readlane_b32 s9, v229, 23
	s_nop 1
	v_lshl_add_u64 v[18:19], s[8:9], 0, v[0:1]
	v_lshlrev_b64 v[0:1], 12, v[142:143]
	v_readlane_b32 s8, v229, 24
	v_or_b32_e32 v0, v0, v134
	v_readlane_b32 s9, v229, 25
	s_nop 1
	v_lshl_add_u64 v[20:21], s[8:9], 0, v[0:1]
	s_mov_b64 s[8:9], 0
	global_load_dwordx4 v[152:155], v[16:17], off
	global_load_dwordx4 v[156:159], v[16:17], off offset:1024
	global_load_dwordx4 v[160:163], v[16:17], off offset:2048
	global_load_dwordx4 v[164:167], v[16:17], off offset:3072
	global_load_dwordx4 v[0:3], v[20:21], off offset:-3072 nt
	global_load_dwordx4 v[4:7], v[20:21], off offset:-2048 nt
	global_load_dwordx4 v[8:11], v[20:21], off offset:-1024 nt
	global_load_dwordx4 v[12:15], v[20:21], off nt
	s_waitcnt vmcnt(0)
.LBB0_597:
	v_add_u32_e32 v142, s34, v142
	v_cmp_lt_i32_e32 vcc, s76, v142
	s_or_b64 s[8:9], vcc, s[8:9]
	s_cbranch_vccnz .Lnr0_npa
	v_lshl_add_u64 v[20:21], v[20:21], 0, s[12:13]
	global_load_dwordx4 v[168:171], v[20:21], off offset:-3072 nt
	global_load_dwordx4 v[172:175], v[20:21], off offset:-2048 nt
	global_load_dwordx4 v[176:179], v[20:21], off offset:-1024 nt
	global_load_dwordx4 v[180:183], v[20:21], off nt
	s_waitcnt vmcnt(8)
	s_branch .Lnr0_ja

; __device__ __forceinline__ uint2 pack4(float a, float b, float c, float d) { return make_uint2(pack2(a, b), pack2(c, d)); }
; __device__ __forceinline__ int ltid() { int t = threadIdx.x; asm volatile("" : "+v"(t)); return t; }
; __device__ __forceinline__ void norm_rows(const float* in, const float* gain, u16* outb, int nrows, int job0w, int jstridew) {
;   const int lane = ltid() & 63;
;   for (int r = job0w; r < nrows; r += jstridew) {
;     const float4* ip = (const float4*)(in + (size_t)r * 1024);
;     float4 v[4];
;     float ss = 0.f;
; #pragma unroll
;     for (int i = 0; i < 4; i++) {
;       { const f32x4 t_ = __builtin_nontemporal_load((const f32x4*)ip + lane + i * 64); v[i] = make_float4(t_[0], t_[1], t_[2], t_[3]); }
;       ss += v[i].x * v[i].x + v[i].y * v[i].y + v[i].z * v[i].z + v[i].w * v[i].w;
;     }
;     ss = wave_sum(ss);
;     float sc = rsqrtf(ss * (1.f / 1024.f) + 1e-6f);
; #pragma unroll
;     for (int i = 0; i < 4; i++) {
;       float4 g = ((const float4*)gain)[lane + i * 64];
;       *(uint2*)(outb + (size_t)r * 1024 + (lane + i * 64) * 4) =
;           pack4(v[i].x * sc * g.x, v[i].y * sc * g.y, v[i].z * sc * g.z, v[i].w * sc * g.w);
;     }
;   }
; }
.Lnr0_ja:
	v_mul_f32_e32 v144, v1, v1
	v_mul_f32_e32 v145, v5, v5
	v_mul_f32_e32 v146, v9, v9
	v_mul_f32_e32 v147, v13, v13
	v_fmac_f32_e32 v144, v0, v0
	v_fmac_f32_e32 v145, v4, v4
	v_fmac_f32_e32 v146, v8, v8
	v_fmac_f32_e32 v147, v12, v12
	v_fmac_f32_e32 v144, v2, v2
	v_fmac_f32_e32 v145, v6, v6
	v_fmac_f32_e32 v146, v10, v10
	v_fmac_f32_e32 v147, v14, v14
	v_fmac_f32_e32 v144, v3, v3
	v_fmac_f32_e32 v145, v7, v7
	v_fmac_f32_e32 v146, v11, v11
	v_fmac_f32_e32 v147, v15, v15
	v_add_f32_e32 v148, v144, v145
	v_add_f32_e32 v148, v148, v146
	v_add_f32_e32 v148, v148, v147
	s_nop 1
	v_add_f32_dpp v148, v148, v148 quad_perm:[1,0,3,2] row_mask:0xf bank_mask:0xf bound_ctrl:1
	s_nop 1
	v_add_f32_dpp v148, v148, v148 quad_perm:[2,3,0,1] row_mask:0xf bank_mask:0xf bound_ctrl:1
	s_nop 1
	v_add_f32_dpp v148, v148, v148 row_half_mirror row_mask:0xf bank_mask:0xf bound_ctrl:1
	s_nop 1
	v_add_f32_dpp v148, v148, v148 row_mirror row_mask:0xf bank_mask:0xf bound_ctrl:1
	v_mov_b32_e32 v149, v148
	s_nop 1
	v_permlane16_swap_b32_e32 v148, v149
	v_add_f32_e32 v148, v148, v149
	v_mov_b32_e32 v149, v148
	s_nop 1
	v_permlane32_swap_b32_e32 v148, v149
	v_add_f32_e32 v148, v148, v149
	v_fmamk_f32 v148, v148, 0x3a800000, v136
	v_cmp_gt_f32_e32 vcc, s85, v148
	v_mul_f32_e32 v149, 0x4b800000, v148
	s_nop 0
	v_cndmask_b32_e32 v148, v148, v149, vcc
	v_rsq_f32_e32 v148, v148
	s_nop 0
	v_mul_f32_e32 v149, 0x45800000, v148
	v_cndmask_b32_e32 v150, v148, v149, vcc
	s_nop 0
	v_pk_mul_f32 v[0:1], v[0:1], v[150:151] op_sel_hi:[1,0]
	v_pk_mul_f32 v[2:3], v[2:3], v[150:151] op_sel_hi:[1,0]
	v_pk_mul_f32 v[4:5], v[4:5], v[150:151] op_sel_hi:[1,0]
	v_pk_mul_f32 v[6:7], v[6:7], v[150:151] op_sel_hi:[1,0]
	v_pk_mul_f32 v[8:9], v[8:9], v[150:151] op_sel_hi:[1,0]
	v_pk_mul_f32 v[10:11], v[10:11], v[150:151] op_sel_hi:[1,0]
	v_pk_mul_f32 v[12:13], v[12:13], v[150:151] op_sel_hi:[1,0]
	v_pk_mul_f32 v[14:15], v[14:15], v[150:151] op_sel_hi:[1,0]
	v_pk_mul_f32 v[0:1], v[152:153], v[0:1]
	v_pk_mul_f32 v[2:3], v[154:155], v[2:3]
	v_pk_mul_f32 v[4:5], v[156:157], v[4:5]
	v_pk_mul_f32 v[6:7], v[158:159], v[6:7]
	v_pk_mul_f32 v[8:9], v[160:161], v[8:9]
	v_pk_mul_f32 v[10:11], v[162:163], v[10:11]
	v_pk_mul_f32 v[12:13], v[164:165], v[12:13]
	v_pk_mul_f32 v[14:15], v[166:167], v[14:15]
	v_cvt_pk_bf16_f32 v0, v0, v1
	v_cvt_pk_bf16_f32 v1, v2, v3
	v_cvt_pk_bf16_f32 v4, v4, v5
	v_cvt_pk_bf16_f32 v5, v6, v7
	v_cvt_pk_bf16_f32 v8, v8, v9
	v_cvt_pk_bf16_f32 v9, v10, v11
	v_cvt_pk_bf16_f32 v12, v12, v13
	v_cvt_pk_bf16_f32 v13, v14, v15
	global_store_dwordx2 v[18:19], v[0:1], off offset:-1024
	global_store_dwordx2 v[18:19], v[4:5], off offset:-512
	global_store_dwordx2 v[18:19], v[8:9], off
	global_store_dwordx2 v[18:19], v[12:13], off offset:512
	v_lshl_add_u64 v[18:19], v[18:19], 0, s[10:11]
	s_andn2_b64 exec, exec, s[8:9]
	s_cbranch_execz .Lnr0_done
	v_add_u32_e32 v142, s34, v142
	v_cmp_lt_i32_e32 vcc, s76, v142
	s_or_b64 s[8:9], vcc, s[8:9]
	s_cbranch_vccnz .Lnr0_npb
	v_lshl_add_u64 v[20:21], v[20:21], 0, s[12:13]
	global_load_dwordx4 v[0:3], v[20:21], off offset:-3072 nt
	global_load_dwordx4 v[4:7], v[20:21], off offset:-2048 nt
	global_load_dwordx4 v[8:11], v[20:21], off offset:-1024 nt
	global_load_dwordx4 v[12:15], v[20:21], off nt
	s_waitcnt vmcnt(8)
	s_branch .Lnr0_jb

; __device__ __forceinline__ uint2 pack4(float a, float b, float c, float d) { return make_uint2(pack2(a, b), pack2(c, d)); }
; __device__ __forceinline__ int ltid() { int t = threadIdx.x; asm volatile("" : "+v"(t)); return t; }
; __device__ __forceinline__ void norm_rows(const float* in, const float* gain, u16* outb, int nrows, int job0w, int jstridew) {
;   const int lane = ltid() & 63;
;   for (int r = job0w; r < nrows; r += jstridew) {
;     const float4* ip = (const float4*)(in + (size_t)r * 1024);
;     float4 v[4];
;     float ss = 0.f;
; #pragma unroll
;     for (int i = 0; i < 4; i++) {
;       { const f32x4 t_ = __builtin_nontemporal_load((const f32x4*)ip + lane + i * 64); v[i] = make_float4(t_[0], t_[1], t_[2], t_[3]); }
;       ss += v[i].x * v[i].x + v[i].y * v[i].y + v[i].z * v[i].z + v[i].w * v[i].w;
;     }
;     ss = wave_sum(ss);
;     float sc = rsqrtf(ss * (1.f / 1024.f) + 1e-6f);
; #pragma unroll
;     for (int i = 0; i < 4; i++) {
;       float4 g = ((const float4*)gain)[lane + i * 64];
;       *(uint2*)(outb + (size_t)r * 1024 + (lane + i * 64) * 4) =
;           pack4(v[i].x * sc * g.x, v[i].y * sc * g.y, v[i].z * sc * g.z, v[i].w * sc * g.w);
;     }
;   }
; }
.Lnr0_jb:
	v_mul_f32_e32 v144, v169, v169
	v_mul_f32_e32 v145, v173, v173
	v_mul_f32_e32 v146, v177, v177
	v_mul_f32_e32 v147, v181, v181
	v_fmac_f32_e32 v144, v168, v168
	v_fmac_f32_e32 v145, v172, v172
	v_fmac_f32_e32 v146, v176, v176
	v_fmac_f32_e32 v147, v180, v180
	v_fmac_f32_e32 v144, v170, v170
	v_fmac_f32_e32 v145, v174, v174
	v_fmac_f32_e32 v146, v178, v178
	v_fmac_f32_e32 v147, v182, v182
	v_fmac_f32_e32 v144, v171, v171
	v_fmac_f32_e32 v145, v175, v175
	v_fmac_f32_e32 v146, v179, v179
	v_fmac_f32_e32 v147, v183, v183
	v_add_f32_e32 v148, v144, v145
	v_add_f32_e32 v148, v148, v146
	v_add_f32_e32 v148, v148, v147
	s_nop 1
	v_add_f32_dpp v148, v148, v148 quad_perm:[1,0,3,2] row_mask:0xf bank_mask:0xf bound_ctrl:1
	s_nop 1
	v_add_f32_dpp v148, v148, v148 quad_perm:[2,3,0,1] row_mask:0xf bank_mask:0xf bound_ctrl:1
	s_nop 1
	v_add_f32_dpp v148, v148, v148 row_half_mirror row_mask:0xf bank_mask:0xf bound_ctrl:1
	s_nop 1
	v_add_f32_dpp v148, v148, v148 row_mirror row_mask:0xf bank_mask:0xf bound_ctrl:1
	v_mov_b32_e32 v149, v148
	s_nop 1
	v_permlane16_swap_b32_e32 v148, v149
	v_add_f32_e32 v148, v148, v149
	v_mov_b32_e32 v149, v148
	s_nop 1
	v_permlane32_swap_b32_e32 v148, v149
	v_add_f32_e32 v148, v148, v149
	v_fmamk_f32 v148, v148, 0x3a800000, v136
	v_cmp_gt_f32_e32 vcc, s85, v148
	v_mul_f32_e32 v149, 0x4b800000, v148
	s_nop 0
	v_cndmask_b32_e32 v148, v148, v149, vcc
	v_rsq_f32_e32 v148, v148
	s_nop 0
	v_mul_f32_e32 v149, 0x45800000, v148
	v_cndmask_b32_e32 v150, v148, v149, vcc
	s_nop 0
	v_pk_mul_f32 v[168:169], v[168:169], v[150:151] op_sel_hi:[1,0]
	v_pk_mul_f32 v[170:171], v[170:171], v[150:151] op_sel_hi:[1,0]
	v_pk_mul_f32 v[172:173], v[172:173], v[150:151] op_sel_hi:[1,0]
	v_pk_mul_f32 v[174:175], v[174:175], v[150:151] op_sel_hi:[1,0]
	v_pk_mul_f32 v[176:177], v[176:177], v[150:151] op_sel_hi:[1,0]
	v_pk_mul_f32 v[178:179], v[178:179], v[150:151] op_sel_hi:[1,0]
	v_pk_mul_f32 v[180:181], v[180:181], v[150:151] op_sel_hi:[1,0]
	v_pk_mul_f32 v[182:183], v[182:183], v[150:151] op_sel_hi:[1,0]
	v_pk_mul_f32 v[168:169], v[152:153], v[168:169]
	v_pk_mul_f32 v[170:171], v[154:155], v[170:171]
	v_pk_mul_f32 v[172:173], v[156:157], v[172:173]
	v_pk_mul_f32 v[174:175], v[158:159], v[174:175]
	v_pk_mul_f32 v[176:177], v[160:161], v[176:177]
	v_pk_mul_f32 v[178:179], v[162:163], v[178:179]
	v_pk_mul_f32 v[180:181], v[164:165], v[180:181]
	v_pk_mul_f32 v[182:183], v[166:167], v[182:183]
	v_cvt_pk_bf16_f32 v168, v168, v169
	v_cvt_pk_bf16_f32 v169, v170, v171
	v_cvt_pk_bf16_f32 v172, v172, v173
	v_cvt_pk_bf16_f32 v173, v174, v175
	v_cvt_pk_bf16_f32 v176, v176, v177
	v_cvt_pk_bf16_f32 v177, v178, v179
	v_cvt_pk_bf16_f32 v180, v180, v181
	v_cvt_pk_bf16_f32 v181, v182, v183
	global_store_dwordx2 v[18:19], v[168:169], off offset:-1024
	global_store_dwordx2 v[18:19], v[172:173], off offset:-512
	global_store_dwordx2 v[18:19], v[176:177], off
	global_store_dwordx2 v[18:19], v[180:181], off offset:512
	v_lshl_add_u64 v[18:19], v[18:19], 0, s[10:11]
	s_andn2_b64 exec, exec, s[8:9]
	s_cbranch_execnz .LBB0_597
.Lnr0_done:
	s_getpc_b64 s[98:99]

; __device__ __forceinline__ int ltid() { int t = threadIdx.x; asm volatile("" : "+v"(t)); return t; }
; __device__ __forceinline__ void transpose_tile(const TDesc& d, int tile, float* sm) {
;   const int ktn = d.K >> 6;
;   const int kt = tile % ktn, ntl = tile / ktn;
;   const int k0 = kt * 64, n0 = ntl * 64;
;   const int tid = ltid();
;   __syncthreads();
; #pragma unroll
;   for (int i = 0; i < 16; i++) {
;     int e = tid + i * 256;
;     int kk = e >> 6, nn = e & 63;
;     const int nc = n0 + nn;
;     float v = __builtin_nontemporal_load(&d.src[(size_t)(k0 + kk) * d.N + (nc < d.N ? nc : d.N - 1)]);
;     sm[kk * 65 + nn] = (nc < d.N) ? v : 0.f;
;   }
;   __syncthreads();
; #pragma unroll
;   for (int i = 0; i < 2; i++) {
;     int e = tid + i * 256;
;     int nn = e >> 3, kc = (e & 7) * 8;
;     float f[8];
; #pragma unroll
;     for (int q = 0; q < 8; q++) f[q] = sm[(kc + q) * 65 + nn];
;     *(bf16x8*)(d.dst + (size_t)(n0 + nn) * d.K + k0 + kc) = pack8(f);
;   }
; }
; __device__ __forceinline__ void transpose_jobs(const TDesc* tab, int ntab, int ntiles, float* sm, int job0, int jstride) {
;   for (int t = job0; t < ntiles; t += jstride) {
;     int di = 0;
;     for (int i = 1; i < ntab; i++)
;       if (t >= tab[i].t0) di = i;
;     transpose_tile(tab[di], t - tab[di].t0, sm);
;   }
; }
.LBB0_599:
	s_lshl_b64 s[6:7], s[6:7], 5
	s_add_u32 s12, s0, s6
	s_addc_u32 s13, s1, s7
	s_load_dwordx4 s[8:11], s[12:13], 0x238
	s_load_dwordx2 s[6:7], s[12:13], 0x248
	s_load_dword s4, s[12:13], 0x254
	v_mov_b32_e32 v1, v132
	s_load_dword s12, s[12:13], 0x248
	s_waitcnt lgkmcnt(0)
	v_mov_b32_e32 v2, s8
	s_sub_i32 s4, s14, s4
	s_abs_i32 s15, s4
	s_ashr_i32 s12, s12, 6
	s_abs_i32 s16, s12
	v_cvt_f32_u32_e32 v0, s16
	s_sub_i32 s17, 0, s16
	s_xor_b32 s13, s4, s12
	s_ashr_i32 s13, s13, 31
	v_rcp_iflag_f32_e32 v0, v0
	v_mov_b32_e32 v3, s9
	v_ashrrev_i32_e32 v6, 6, v1
	s_waitcnt vmcnt(0)
	v_mul_f32_e32 v0, 0x4f7ffffe, v0
	v_cvt_u32_f32_e32 v0, v0
	s_barrier
	v_ashrrev_i32_e32 v11, 3, v1
	v_readfirstlane_b32 s34, v0
	s_mul_i32 s17, s17, s34
	s_mul_hi_u32 s17, s34, s17
	s_add_i32 s34, s34, s17
	s_mul_hi_u32 s17, s15, s34
	s_mul_i32 s34, s17, s16
	s_sub_i32 s15, s15, s34
	s_add_i32 s34, s17, 1
	s_sub_i32 s35, s15, s16
	s_cmp_ge_u32 s15, s16
	s_cselect_b32 s17, s34, s17
	s_cselect_b32 s15, s35, s15
	s_add_i32 s34, s17, 1
	s_cmp_ge_u32 s15, s16
	s_cselect_b32 s15, s34, s17
	s_xor_b32 s15, s15, s13
	s_sub_i32 s13, s15, s13
	s_mul_i32 s12, s13, s12
	s_sub_i32 s4, s4, s12
	s_lshl_b32 s12, s4, 6
	s_lshl_b32 s4, s13, 6
	v_and_b32_e32 v0, 63, v1
	v_or_b32_e32 v4, s4, v0
	s_add_i32 s8, s7, -1
	v_cmp_gt_i32_e32 vcc, s7, v4
	v_min_i32_e32 v4, s8, v4
	v_ashrrev_i32_e32 v5, 31, v4
	v_lshl_add_u64 v[2:3], v[4:5], 2, v[2:3]
	v_add_u32_e32 v4, s12, v6
	v_mad_i64_i32 v[4:5], s[8:9], s7, v4, 0
	v_lshl_add_u64 v[4:5], v[4:5], 2, v[2:3]
	v_lshlrev_b32_e32 v0, 2, v0
	s_ashr_i32 s13, s12, 31
	v_readlane_b32 s34, v229, 5
	v_readlane_b32 s35, v229, 6
	v_mov_b32_e32 v28, s7
	v_mov_b32_e32 v29, 0
	v_lshlrev_b32_e32 v28, 4, v28
	v_mad_u32_u24 v30, v6, s77, v0
	global_load_dword v12, v[4:5], off nt
	v_lshl_add_u64 v[4:5], v[4:5], 0, v[28:29]
	global_load_dword v13, v[4:5], off nt
	v_lshl_add_u64 v[4:5], v[4:5], 0, v[28:29]
	global_load_dword v14, v[4:5], off nt
	v_lshl_add_u64 v[4:5], v[4:5], 0, v[28:29]
	global_load_dword v15, v[4:5], off nt
	v_lshl_add_u64 v[4:5], v[4:5], 0, v[28:29]
	global_load_dword v16, v[4:5], off nt
	v_lshl_add_u64 v[4:5], v[4:5], 0, v[28:29]
	global_load_dword v17, v[4:5], off nt
	v_lshl_add_u64 v[4:5], v[4:5], 0, v[28:29]
	global_load_dword v18, v[4:5], off nt
	v_lshl_add_u64 v[4:5], v[4:5], 0, v[28:29]
	global_load_dword v19, v[4:5], off nt
	v_lshl_add_u64 v[4:5], v[4:5], 0, v[28:29]
	global_load_dword v20, v[4:5], off nt
	v_lshl_add_u64 v[4:5], v[4:5], 0, v[28:29]
	global_load_dword v21, v[4:5], off nt
	v_lshl_add_u64 v[4:5], v[4:5], 0, v[28:29]
	global_load_dword v22, v[4:5], off nt
	v_lshl_add_u64 v[4:5], v[4:5], 0, v[28:29]
	global_load_dword v23, v[4:5], off nt
	v_lshl_add_u64 v[4:5], v[4:5], 0, v[28:29]
	global_load_dword v24, v[4:5], off nt
	v_lshl_add_u64 v[4:5], v[4:5], 0, v[28:29]
	global_load_dword v25, v[4:5], off nt
	v_lshl_add_u64 v[4:5], v[4:5], 0, v[28:29]
	global_load_dword v26, v[4:5], off nt
	v_lshl_add_u64 v[4:5], v[4:5], 0, v[28:29]
	global_load_dword v27, v[4:5], off nt
	s_waitcnt vmcnt(15)
	v_cndmask_b32_e32 v31, 0, v12, vcc
	ds_write_b32 v30, v31
	s_waitcnt vmcnt(14)
	v_cndmask_b32_e32 v32, 0, v13, vcc
	ds_write_b32 v30, v32 offset:1040
	s_waitcnt vmcnt(13)
	v_cndmask_b32_e32 v31, 0, v14, vcc
	ds_write_b32 v30, v31 offset:2080
	s_waitcnt vmcnt(12)
	v_cndmask_b32_e32 v32, 0, v15, vcc
	ds_write_b32 v30, v32 offset:3120
	s_waitcnt vmcnt(11)
	v_cndmask_b32_e32 v31, 0, v16, vcc
	ds_write_b32 v30, v31 offset:4160
	s_waitcnt vmcnt(10)
	v_cndmask_b32_e32 v32, 0, v17, vcc
	ds_write_b32 v30, v32 offset:5200
	s_waitcnt vmcnt(9)
	v_cndmask_b32_e32 v31, 0, v18, vcc
	ds_write_b32 v30, v31 offset:6240
	s_waitcnt vmcnt(8)
	v_cndmask_b32_e32 v32, 0, v19, vcc
	ds_write_b32 v30, v32 offset:7280
	s_waitcnt vmcnt(7)
	v_cndmask_b32_e32 v31, 0, v20, vcc
	ds_write_b32 v30, v31 offset:8320
	s_waitcnt vmcnt(6)
	v_cndmask_b32_e32 v32, 0, v21, vcc
	ds_write_b32 v30, v32 offset:9360
	s_waitcnt vmcnt(5)
	v_cndmask_b32_e32 v31, 0, v22, vcc
	ds_write_b32 v30, v31 offset:10400
	s_waitcnt vmcnt(4)
	v_cndmask_b32_e32 v32, 0, v23, vcc
	ds_write_b32 v30, v32 offset:11440
	s_waitcnt vmcnt(3)
	v_cndmask_b32_e32 v31, 0, v24, vcc
	ds_write_b32 v30, v31 offset:12480
	s_waitcnt vmcnt(2)
	v_cndmask_b32_e32 v32, 0, v25, vcc
	ds_write_b32 v30, v32 offset:13520
	s_waitcnt vmcnt(1)
	v_cndmask_b32_e32 v31, 0, v26, vcc
	ds_write_b32 v30, v31 offset:14560
	s_waitcnt vmcnt(0)
	v_cndmask_b32_e32 v32, 0, v27, vcc
	ds_write_b32 v30, v32 offset:15600
	v_add_u32_e32 v4, 0x100, v1
	v_lshlrev_b32_e32 v0, 3, v1
	v_and_b32_e32 v5, 56, v0
	v_mul_u32_u24_e32 v10, 0x104, v5
	v_lshl_add_u32 v6, v11, 2, v10
	s_waitcnt lgkmcnt(0)
	s_barrier
	ds_read2_b32 v[0:1], v6 offset1:65
	ds_read2_b32 v[2:3], v6 offset0:130 offset1:195
	v_add_u32_e32 v8, 0x400, v6
	ds_read2_b32 v[6:7], v8 offset0:4 offset1:69
	ds_read2_b32 v[8:9], v8 offset0:134 offset1:199
	v_lshlrev_b32_e32 v134, 1, v5
	s_waitcnt lgkmcnt(3)
	v_cvt_pk_bf16_f32 v0, v0, v1
	s_waitcnt lgkmcnt(2)
	v_cvt_pk_bf16_f32 v1, v2, v3
	s_waitcnt lgkmcnt(1)
	v_cvt_pk_bf16_f32 v2, v6, v7
	v_add_u32_e32 v6, s4, v11
	v_mad_i64_i32 v[6:7], s[8:9], s6, v6, 0
	v_lshl_add_u64 v[6:7], v[6:7], 1, s[10:11]
	s_lshl_b64 s[8:9], s[12:13], 1
	v_lshl_add_u64 v[6:7], v[6:7], 0, s[8:9]
	s_waitcnt lgkmcnt(0)
	v_cvt_pk_bf16_f32 v3, v8, v9
	v_lshl_add_u64 v[6:7], v[6:7], 0, v[134:135]
	v_ashrrev_i32_e32 v8, 3, v4
	global_store_dwordx4 v[6:7], v[0:3], off
	v_lshl_add_u32 v4, v8, 2, v10
	ds_read2_b32 v[0:1], v4 offset1:65
	ds_read2_b32 v[2:3], v4 offset0:130 offset1:195
	v_add_u32_e32 v6, 0x400, v4
	ds_read2_b32 v[4:5], v6 offset0:4 offset1:69
	ds_read2_b32 v[6:7], v6 offset0:134 offset1:199
	s_waitcnt lgkmcnt(3)
	v_cvt_pk_bf16_f32 v0, v0, v1
	s_waitcnt lgkmcnt(2)
	v_cvt_pk_bf16_f32 v1, v2, v3
	s_waitcnt lgkmcnt(1)
	v_cvt_pk_bf16_f32 v2, v4, v5
	v_add_u32_e32 v4, s4, v8
	v_mad_i64_i32 v[4:5], s[6:7], s6, v4, 0
	v_lshl_add_u64 v[4:5], v[4:5], 1, s[10:11]
	v_readlane_b32 s4, v230, 26
	v_lshl_add_u64 v[4:5], v[4:5], 0, s[8:9]
	s_add_i32 s14, s4, s14
	s_waitcnt lgkmcnt(0)
	v_cvt_pk_bf16_f32 v3, v6, v7
	v_lshl_add_u64 v[4:5], v[4:5], 0, v[134:135]
	s_cmp_ge_i32 s14, s89
	global_store_dwordx4 v[4:5], v[0:3], off
	s_cbranch_scc1 .LBB0_592
